# MFMA-segment issue-slot cleanup: removed the redundant adjacent s_setprio 0/1 pair in the middle of each 32-MFMA block and the already-satisfied lgkmcnt(0) at its head, in all six K-loops and their pe
# speedup vs baseline: 1.0065x; 1.0028x over previous
; #define PG8_STAGE(bufoff, gbase, voff) do { _Pragma("unroll") for (int _i = 0; _i < 2; ++_i) \
;         __builtin_amdgcn_global_load_lds((const unsigned*)((const char*)(gbase) + (voff)[_i]), (PG8_LAS unsigned*)(lds + (bufoff) + ldsw + _i * 8192), 16, 0, 0); } while (0)
; #define PG8_LDA(dst, b, h) do { _Pragma("unroll") for (int m = 0; m < 4; ++m) _Pragma("unroll") for (int k = 0; k < 2; ++k) dst[m][k] = *(const PG8_LAS bf16x8*)(lds + PG8_SA(b, h) + aoff + m * 2048 + k * 1024); } while (0)
; template <class Epi, class Sched, bool ALIGN_EPI = false, bool SP2 = false>
; __device__ __forceinline__ void gemm_phase(PG8_LAS unsigned char* lds, const Gemm g, const Sched& S, const Epi& E) {
;     ...
;         const bool has_next = S.next(ui + 1, nxt);
;         const char* nA = has_next ? (const char*)g.A + (size_t)nxt.pm * tstep : cA; const char* nB = has_next ? (const char*)g.Bt + (size_t)nxt.pn * tstep : cB;
;         for (int t = 0; t < nt; t += 2) {
;             const bool last = (t == nt - 2);
;             const char* a1 = cA + (size_t)(t + 1) * kstep;
;             const char* a2 = last ? nA : cA + (size_t)(t + 2) * kstep; const char* b2 = last ? nB : cB + (size_t)(t + 2) * kstep;
;             const char* a3 = a2 + kstep; const char* b3 = b2 + kstep;
;             if (last && has_next) S.a_ready(nxt);
;             if constexpr (SP2) {
;             PG8_LDB(B0, 0, 0); PG8_LDB(B1, 0, 1); PG8_SCHED; PG8_LDA(At, 0, 0); PG8_STAGE(PG8_SA(1, 1), a1 + hstep, voffA);
;             PG8_WAIT_V(8); PG8_WAIT_L(0); PG8_BAR; PG8_MMA(0, 0, At, B0); PG8_MMA(0, 1, At, B1); PG8_BAR; PG8_SCHED;
;             PG8_LDA(At, 0, 1); PG8_STAGE(PG8_SB(0, 0), b2, voffB); PG8_STAGE(PG8_SB(0, 1), b2 + hstep, voffB); PG8_STAGE(PG8_SA(0, 0), a2, voffA);
;             PG8_WAIT_V(8); PG8_WAIT_L(0); PG8_BAR; PG8_MMA(1, 0, At, B0); PG8_MMA(1, 1, At, B1); PG8_BAR; PG8_SCHED;
;             PG8_LDB(B0, 1, 0); PG8_LDB(B1, 1, 1); PG8_SCHED; PG8_LDA(At, 1, 0); PG8_STAGE(PG8_SA(0, 1), a2 + hstep, voffA);
;             PG8_WAIT_V(8); PG8_WAIT_L(0); PG8_BAR; PG8_MMA(0, 0, At, B0); PG8_MMA(0, 1, At, B1); PG8_BAR; PG8_SCHED;
;             PG8_LDA(At, 1, 1); PG8_STAGE(PG8_SB(1, 0), b3, voffB); PG8_STAGE(PG8_SB(1, 1), b3 + hstep, voffB); PG8_STAGE(PG8_SA(1, 0), a3, voffA);
;             PG8_WAIT_V(8); PG8_WAIT_L(0); PG8_BAR; PG8_MMA(1, 0, At, B0); PG8_MMA(1, 1, At, B1); PG8_BAR; PG8_SCHED;
.LBB0_84:
	s_ashr_i32 s11, s10, 31
	s_lshl_b64 s[12:13], s[10:11], 20
	s_add_u32 s12, s46, s12
	s_addc_u32 s13, s47, s13
	s_and_b64 s[14:15], s[2:3], exec
	s_cselect_b32 s11, s13, s19
	s_cselect_b32 s42, s12, s18
	s_ashr_i32 s9, s8, 31
	s_lshl_b64 s[14:15], s[8:9], 20
	v_readlane_b32 s9, v255, 30
	s_add_u32 s14, s9, s14
	v_readlane_b32 s9, v255, 31
	s_addc_u32 s15, s9, s15
	s_and_b64 s[22:23], s[2:3], exec
	s_cselect_b32 s9, s15, s21
	s_cselect_b32 s44, s14, s20
	s_add_u32 s18, s18, 0x80080
	s_addc_u32 s19, s19, 0
	s_add_u32 s45, s20, 0x100
	s_addc_u32 s50, s21, 0
	s_mov_b32 s51, -2
	s_add_u32 s20, s18, 0xfff80080
	s_addc_u32 s21, s19, -1
	s_add_i32 s56, 0, 0x10000
	s_cmp_eq_u32 s51, 28
	s_cselect_b32 s23, s11, s21
	s_cselect_b32 s22, s42, s20
	v_add_u32_e32 v150, s56, v153
	s_cselect_b32 s21, s9, s50
	s_cselect_b32 s20, s44, s45
	s_add_i32 s63, 0, 0x14000
	ds_read_b128 v[184:187], v150
	ds_read_b128 v[188:191], v150 offset:1024
	ds_read_b128 v[192:195], v150 offset:2048
	ds_read_b128 v[196:199], v150 offset:3072
	v_add_u32_e32 v150, s63, v153
	ds_read_b128 v[200:203], v150
	ds_read_b128 v[204:207], v150 offset:1024
	ds_read_b128 v[208:211], v150 offset:2048
	ds_read_b128 v[212:215], v150 offset:3072
	s_add_i32 m0, s27, 0xc000
	ds_read_b128 v[216:219], v155
	ds_read_b128 v[220:223], v155 offset:1024
	ds_read_b128 v[224:227], v155 offset:2048
	ds_read_b128 v[228:231], v155 offset:3072
	ds_read_b128 v[232:235], v155 offset:4096
	ds_read_b128 v[236:239], v155 offset:5120
	ds_read_b128 v[240:243], v155 offset:6144
	ds_read_b128 v[244:247], v155 offset:7168
	global_load_lds_dwordx4 v136, s[18:19]
	s_add_i32 m0, s27, 0xe000
	s_nop 0
	global_load_lds_dwordx4 v138, s[18:19]
	s_waitcnt vmcnt(8)
	s_waitcnt lgkmcnt(0)
	s_barrier
	s_setprio 1
	v_mfma_f32_16x16x32_bf16 v[128:131], v[184:187], v[216:219], 0
	v_mfma_f32_16x16x32_bf16 v[120:123], v[192:195], v[216:219], 0
	v_mfma_f32_16x16x32_bf16 v[112:115], v[184:187], v[224:227], 0
	v_mfma_f32_16x16x32_bf16 v[104:107], v[192:195], v[224:227], 0
	v_mfma_f32_16x16x32_bf16 v[96:99], v[184:187], v[232:235], 0
	v_mfma_f32_16x16x32_bf16 v[88:91], v[192:195], v[232:235], 0
	v_mfma_f32_16x16x32_bf16 v[80:83], v[184:187], v[240:243], 0
	v_mfma_f32_16x16x32_bf16 v[72:75], v[192:195], v[240:243], 0
	v_mfma_f32_16x16x32_bf16 v[128:131], v[188:191], v[220:223], v[128:131]
	v_mfma_f32_16x16x32_bf16 v[120:123], v[196:199], v[220:223], v[120:123]
	v_mfma_f32_16x16x32_bf16 v[112:115], v[188:191], v[228:231], v[112:115]
	v_mfma_f32_16x16x32_bf16 v[104:107], v[196:199], v[228:231], v[104:107]
	v_mfma_f32_16x16x32_bf16 v[96:99], v[188:191], v[236:239], v[96:99]
	v_mfma_f32_16x16x32_bf16 v[88:91], v[196:199], v[236:239], v[88:91]
	v_mfma_f32_16x16x32_bf16 v[80:83], v[188:191], v[244:247], v[80:83]
	v_mfma_f32_16x16x32_bf16 v[72:75], v[196:199], v[244:247], v[72:75]
	v_mfma_f32_16x16x32_bf16 v[124:127], v[200:203], v[216:219], 0
	v_mfma_f32_16x16x32_bf16 v[116:119], v[208:211], v[216:219], 0
	v_mfma_f32_16x16x32_bf16 v[108:111], v[200:203], v[224:227], 0
	v_mfma_f32_16x16x32_bf16 v[100:103], v[208:211], v[224:227], 0
	v_mfma_f32_16x16x32_bf16 v[92:95], v[200:203], v[232:235], 0
	v_mfma_f32_16x16x32_bf16 v[84:87], v[208:211], v[232:235], 0
	v_mfma_f32_16x16x32_bf16 v[76:79], v[200:203], v[240:243], 0
	v_mfma_f32_16x16x32_bf16 v[68:71], v[208:211], v[240:243], 0
	v_mfma_f32_16x16x32_bf16 v[124:127], v[204:207], v[220:223], v[124:127]
	v_mfma_f32_16x16x32_bf16 v[116:119], v[212:215], v[220:223], v[116:119]
	v_mfma_f32_16x16x32_bf16 v[108:111], v[204:207], v[228:231], v[108:111]
	v_mfma_f32_16x16x32_bf16 v[100:103], v[212:215], v[228:231], v[100:103]
	v_mfma_f32_16x16x32_bf16 v[92:95], v[204:207], v[236:239], v[92:95]
	v_mfma_f32_16x16x32_bf16 v[84:87], v[212:215], v[236:239], v[84:87]
	v_mfma_f32_16x16x32_bf16 v[76:79], v[204:207], v[244:247], v[76:79]
	v_mfma_f32_16x16x32_bf16 v[68:71], v[212:215], v[244:247], v[68:71]
	s_setprio 0
	s_barrier
	s_add_i32 s56, s56, s25
	s_mov_b32 m0, s56
	ds_read_b128 v[216:219], v155 offset:16384
	ds_read_b128 v[220:223], v155 offset:17408
	ds_read_b128 v[224:227], v155 offset:18432
	ds_read_b128 v[228:231], v155 offset:19456
	ds_read_b128 v[232:235], v155 offset:20480
	ds_read_b128 v[236:239], v155 offset:21504
	ds_read_b128 v[240:243], v155 offset:22528
	ds_read_b128 v[244:247], v155 offset:23552
	global_load_lds_dwordx4 v2, s[20:21]
	s_add_i32 m0, s56, 0x2000
	s_add_u32 s56, s20, 0x80000
	s_addc_u32 s57, s21, 0
	s_add_i32 s63, s63, s25
	global_load_lds_dwordx4 v0, s[20:21]
	s_mov_b32 m0, s63
	v_lshl_add_u64 v[252:253], s[22:23], 0, v[132:133]
	global_load_lds_dwordx4 v2, s[56:57]
	s_add_i32 m0, s63, 0x2000
	s_nop 0
	global_load_lds_dwordx4 v0, s[56:57]
	v_lshl_add_u64 v[250:251], s[22:23], 0, v[134:135]
	s_mov_b32 m0, s27
	s_nop 0
	global_load_lds_dwordx4 v[250:251], off
	s_mov_b32 m0, s28
	s_nop 0
	global_load_lds_dwordx4 v[252:253], off
	s_waitcnt vmcnt(8)
	s_waitcnt lgkmcnt(0)
	s_barrier
; #define PG8_STAGE(bufoff, gbase, voff) do { _Pragma("unroll") for (int _i = 0; _i < 2; ++_i) \
;         __builtin_amdgcn_global_load_lds((const unsigned*)((const char*)(gbase) + (voff)[_i]), (PG8_LAS unsigned*)(lds + (bufoff) + ldsw + _i * 8192), 16, 0, 0); } while (0)
; #define PG8_LDA(dst, b, h) do { _Pragma("unroll") for (int m = 0; m < 4; ++m) _Pragma("unroll") for (int k = 0; k < 2; ++k) dst[m][k] = *(const PG8_LAS bf16x8*)(lds + PG8_SA(b, h) + aoff + m * 2048 + k * 1024); } while (0)
; #define PG8_LDB(dst, b, h) do { _Pragma("unroll") for (int n = 0; n < 2; ++n) _Pragma("unroll") for (int k = 0; k < 2; ++k) dst[n][k] = *(const PG8_LAS bf16x8*)(lds + PG8_SB(b, h) + boff + n * 2048 + k * 1024); } while (0)
; #define PG8_MMA(ai, bj, At, Bt) do { __builtin_amdgcn_s_setprio(1); _Pragma("unroll") for (int m = 0; m < 4; ++m) _Pragma("unroll") for (int n = 0; n < 2; ++n) _Pragma("unroll") for (int k = 0; k < 2; ++k) \
;         acc[ai][bj][m][n] = __builtin_amdgcn_mfma_f32_16x16x32_bf16(Bt[n][k], At[m][k], acc[ai][bj][m][n], 0, 0, 0); __builtin_amdgcn_s_setprio(0); } while (0)
; #define PG8_WAIT_V(n) asm volatile("s_waitcnt vmcnt(" #n ")" ::: "memory")
; template <class Epi, class Sched, bool ALIGN_EPI = false, bool SP2 = false>
; __device__ __forceinline__ void gemm_phase(PG8_LAS unsigned char* lds, const Gemm g, const Sched& S, const Epi& E) {
;     ...
;             PG8_LDB(B0, 0, 0); PG8_LDB(B1, 0, 1); PG8_SCHED; PG8_LDA(At, 0, 0); PG8_STAGE(PG8_SA(1, 1), a1 + hstep, voffA);
;             PG8_WAIT_V(8); PG8_WAIT_L(0); PG8_BAR; PG8_MMA(0, 0, At, B0); PG8_MMA(0, 1, At, B1); PG8_BAR; PG8_SCHED;
;             PG8_LDA(At, 0, 1); PG8_STAGE(PG8_SB(0, 0), b2, voffB); PG8_STAGE(PG8_SB(0, 1), b2 + hstep, voffB); PG8_STAGE(PG8_SA(0, 0), a2, voffA);
;             PG8_WAIT_V(8); PG8_WAIT_L(0); PG8_BAR; PG8_MMA(1, 0, At, B0); PG8_MMA(1, 1, At, B1); PG8_BAR; PG8_SCHED;
;             PG8_LDB(B0, 1, 0); PG8_LDB(B1, 1, 1); PG8_SCHED; PG8_LDA(At, 1, 0); PG8_STAGE(PG8_SA(0, 1), a2 + hstep, voffA);
;             PG8_WAIT_V(8); PG8_WAIT_L(0); PG8_BAR; PG8_MMA(0, 0, At, B0); PG8_MMA(0, 1, At, B1); PG8_BAR; PG8_SCHED;
;             PG8_LDA(At, 1, 1); PG8_STAGE(PG8_SB(1, 0), b3, voffB); PG8_STAGE(PG8_SB(1, 1), b3 + hstep, voffB); PG8_STAGE(PG8_SA(1, 0), a3, voffA);
;             PG8_WAIT_V(8); PG8_WAIT_L(0); PG8_BAR; PG8_MMA(1, 0, At, B0); PG8_MMA(1, 1, At, B1); PG8_BAR; PG8_SCHED;
	s_setprio 1
	v_mfma_f32_16x16x32_bf16 v[64:67], v[184:187], v[216:219], 0
	v_mfma_f32_16x16x32_bf16 v[56:59], v[192:195], v[216:219], 0
	v_mfma_f32_16x16x32_bf16 v[48:51], v[184:187], v[224:227], 0
	v_mfma_f32_16x16x32_bf16 v[40:43], v[192:195], v[224:227], 0
	v_mfma_f32_16x16x32_bf16 v[32:35], v[184:187], v[232:235], 0
	v_mfma_f32_16x16x32_bf16 v[24:27], v[192:195], v[232:235], 0
	v_mfma_f32_16x16x32_bf16 v[16:19], v[184:187], v[240:243], 0
	v_mfma_f32_16x16x32_bf16 v[8:11], v[192:195], v[240:243], 0
	v_mfma_f32_16x16x32_bf16 v[64:67], v[188:191], v[220:223], v[64:67]
	v_mfma_f32_16x16x32_bf16 v[56:59], v[196:199], v[220:223], v[56:59]
	v_mfma_f32_16x16x32_bf16 v[48:51], v[188:191], v[228:231], v[48:51]
	v_mfma_f32_16x16x32_bf16 v[40:43], v[196:199], v[228:231], v[40:43]
	v_mfma_f32_16x16x32_bf16 v[32:35], v[188:191], v[236:239], v[32:35]
	v_mfma_f32_16x16x32_bf16 v[24:27], v[196:199], v[236:239], v[24:27]
	v_mfma_f32_16x16x32_bf16 v[16:19], v[188:191], v[244:247], v[16:19]
	v_mfma_f32_16x16x32_bf16 v[8:11], v[196:199], v[244:247], v[8:11]
	v_mfma_f32_16x16x32_bf16 v[60:63], v[200:203], v[216:219], 0
	v_mfma_f32_16x16x32_bf16 v[52:55], v[208:211], v[216:219], 0
	v_mfma_f32_16x16x32_bf16 v[44:47], v[200:203], v[224:227], 0
	v_mfma_f32_16x16x32_bf16 v[36:39], v[208:211], v[224:227], 0
	v_mfma_f32_16x16x32_bf16 v[28:31], v[200:203], v[232:235], 0
	v_mfma_f32_16x16x32_bf16 v[20:23], v[208:211], v[232:235], 0
	v_mfma_f32_16x16x32_bf16 v[12:15], v[200:203], v[240:243], 0
	v_mfma_f32_16x16x32_bf16 v[4:7], v[208:211], v[240:243], 0
	v_mfma_f32_16x16x32_bf16 v[60:63], v[204:207], v[220:223], v[60:63]
	v_mfma_f32_16x16x32_bf16 v[52:55], v[212:215], v[220:223], v[52:55]
	v_mfma_f32_16x16x32_bf16 v[44:47], v[204:207], v[228:231], v[44:47]
	v_mfma_f32_16x16x32_bf16 v[36:39], v[212:215], v[228:231], v[36:39]
	v_mfma_f32_16x16x32_bf16 v[28:31], v[204:207], v[236:239], v[28:31]
	v_mfma_f32_16x16x32_bf16 v[20:23], v[212:215], v[236:239], v[20:23]
	v_mfma_f32_16x16x32_bf16 v[12:15], v[204:207], v[244:247], v[12:15]
	v_mfma_f32_16x16x32_bf16 v[4:7], v[212:215], v[244:247], v[4:7]
	s_setprio 0
	s_barrier
	s_add_i32 s56, 0, 0x18000
	v_add_u32_e32 v161, s56, v153
	s_add_i32 s57, 0, 0x1c000
	ds_read_b128 v[184:187], v161
	ds_read_b128 v[188:191], v161 offset:1024
	ds_read_b128 v[192:195], v161 offset:2048
	ds_read_b128 v[196:199], v161 offset:3072
	v_add_u32_e32 v161, s57, v153
	ds_read_b128 v[200:203], v161
	ds_read_b128 v[204:207], v161 offset:1024
	ds_read_b128 v[208:211], v161 offset:2048
	ds_read_b128 v[212:215], v161 offset:3072
	s_add_u32 s22, s22, 0x80000
	s_addc_u32 s23, s23, 0
	s_mov_b32 m0, s29
	ds_read_b128 v[216:219], v155 offset:32768
	ds_read_b128 v[220:223], v155 offset:33792
	ds_read_b128 v[224:227], v155 offset:34816
	ds_read_b128 v[228:231], v155 offset:35840
	ds_read_b128 v[232:235], v155 offset:36864
	ds_read_b128 v[236:239], v155 offset:37888
	ds_read_b128 v[240:243], v155 offset:38912
	ds_read_b128 v[244:247], v155 offset:39936
	global_load_lds_dwordx4 v134, s[22:23]
	s_mov_b32 m0, s30
	s_nop 0
	global_load_lds_dwordx4 v132, s[22:23]
	s_waitcnt vmcnt(8)
	s_waitcnt lgkmcnt(0)
	s_barrier
	s_setprio 1
	v_mfma_f32_16x16x32_bf16 v[128:131], v[184:187], v[216:219], v[128:131]
	v_mfma_f32_16x16x32_bf16 v[120:123], v[192:195], v[216:219], v[120:123]
	v_mfma_f32_16x16x32_bf16 v[112:115], v[184:187], v[224:227], v[112:115]
	v_mfma_f32_16x16x32_bf16 v[104:107], v[192:195], v[224:227], v[104:107]
	v_mfma_f32_16x16x32_bf16 v[96:99], v[184:187], v[232:235], v[96:99]
	v_mfma_f32_16x16x32_bf16 v[88:91], v[192:195], v[232:235], v[88:91]
	v_mfma_f32_16x16x32_bf16 v[80:83], v[184:187], v[240:243], v[80:83]
	v_mfma_f32_16x16x32_bf16 v[72:75], v[192:195], v[240:243], v[72:75]
	v_mfma_f32_16x16x32_bf16 v[128:131], v[188:191], v[220:223], v[128:131]
	v_mfma_f32_16x16x32_bf16 v[120:123], v[196:199], v[220:223], v[120:123]
	v_mfma_f32_16x16x32_bf16 v[112:115], v[188:191], v[228:231], v[112:115]
	v_mfma_f32_16x16x32_bf16 v[104:107], v[196:199], v[228:231], v[104:107]
	v_mfma_f32_16x16x32_bf16 v[96:99], v[188:191], v[236:239], v[96:99]
	v_mfma_f32_16x16x32_bf16 v[88:91], v[196:199], v[236:239], v[88:91]
	v_mfma_f32_16x16x32_bf16 v[80:83], v[188:191], v[244:247], v[80:83]
	v_mfma_f32_16x16x32_bf16 v[72:75], v[196:199], v[244:247], v[72:75]
	v_mfma_f32_16x16x32_bf16 v[124:127], v[200:203], v[216:219], v[124:127]
	v_mfma_f32_16x16x32_bf16 v[116:119], v[208:211], v[216:219], v[116:119]
	v_mfma_f32_16x16x32_bf16 v[108:111], v[200:203], v[224:227], v[108:111]
	v_mfma_f32_16x16x32_bf16 v[100:103], v[208:211], v[224:227], v[100:103]
	v_mfma_f32_16x16x32_bf16 v[92:95], v[200:203], v[232:235], v[92:95]
	v_mfma_f32_16x16x32_bf16 v[84:87], v[208:211], v[232:235], v[84:87]
	v_mfma_f32_16x16x32_bf16 v[76:79], v[200:203], v[240:243], v[76:79]
	v_mfma_f32_16x16x32_bf16 v[68:71], v[208:211], v[240:243], v[68:71]
	v_mfma_f32_16x16x32_bf16 v[124:127], v[204:207], v[220:223], v[124:127]
	v_mfma_f32_16x16x32_bf16 v[116:119], v[212:215], v[220:223], v[116:119]
	v_mfma_f32_16x16x32_bf16 v[108:111], v[204:207], v[228:231], v[108:111]
	v_mfma_f32_16x16x32_bf16 v[100:103], v[212:215], v[228:231], v[100:103]
	v_mfma_f32_16x16x32_bf16 v[92:95], v[204:207], v[236:239], v[92:95]
	v_mfma_f32_16x16x32_bf16 v[84:87], v[212:215], v[236:239], v[84:87]
	v_mfma_f32_16x16x32_bf16 v[76:79], v[204:207], v[244:247], v[76:79]
	v_mfma_f32_16x16x32_bf16 v[68:71], v[212:215], v[244:247], v[68:71]
	s_setprio 0
	s_barrier
; #define PG8_STAGE(bufoff, gbase, voff) do { _Pragma("unroll") for (int _i = 0; _i < 2; ++_i) \
;         __builtin_amdgcn_global_load_lds((const unsigned*)((const char*)(gbase) + (voff)[_i]), (PG8_LAS unsigned*)(lds + (bufoff) + ldsw + _i * 8192), 16, 0, 0); } while (0)
; #define PG8_LDA(dst, b, h) do { _Pragma("unroll") for (int m = 0; m < 4; ++m) _Pragma("unroll") for (int k = 0; k < 2; ++k) dst[m][k] = *(const PG8_LAS bf16x8*)(lds + PG8_SA(b, h) + aoff + m * 2048 + k * 1024); } while (0)
; #define PG8_LDB(dst, b, h) do { _Pragma("unroll") for (int n = 0; n < 2; ++n) _Pragma("unroll") for (int k = 0; k < 2; ++k) dst[n][k] = *(const PG8_LAS bf16x8*)(lds + PG8_SB(b, h) + boff + n * 2048 + k * 1024); } while (0)
; #define PG8_MMA(ai, bj, At, Bt) do { __builtin_amdgcn_s_setprio(1); _Pragma("unroll") for (int m = 0; m < 4; ++m) _Pragma("unroll") for (int n = 0; n < 2; ++n) _Pragma("unroll") for (int k = 0; k < 2; ++k) \
;         acc[ai][bj][m][n] = __builtin_amdgcn_mfma_f32_16x16x32_bf16(Bt[n][k], At[m][k], acc[ai][bj][m][n], 0, 0, 0); __builtin_amdgcn_s_setprio(0); } while (0)
; template <class Epi, class Sched, bool ALIGN_EPI = false, bool SP2 = false>
; __device__ __forceinline__ void gemm_phase(PG8_LAS unsigned char* lds, const Gemm g, const Sched& S, const Epi& E) {
;     ...
;         for (int t = 0; t < nt; t += 2) {
;             const bool last = (t == nt - 2);
;             const char* a1 = cA + (size_t)(t + 1) * kstep;
;             const char* a2 = last ? nA : cA + (size_t)(t + 2) * kstep; const char* b2 = last ? nB : cB + (size_t)(t + 2) * kstep;
;             const char* a3 = a2 + kstep; const char* b3 = b2 + kstep;
;             if (last && has_next) S.a_ready(nxt);
;             if constexpr (SP2) {
;             PG8_LDB(B0, 0, 0); PG8_LDB(B1, 0, 1); PG8_SCHED; PG8_LDA(At, 0, 0); PG8_STAGE(PG8_SA(1, 1), a1 + hstep, voffA);
;     ...
;             PG8_LDB(B0, 1, 0); PG8_LDB(B1, 1, 1); PG8_SCHED; PG8_LDA(At, 1, 0); PG8_STAGE(PG8_SA(0, 1), a2 + hstep, voffA);
;             PG8_WAIT_V(8); PG8_WAIT_L(0); PG8_BAR; PG8_MMA(0, 0, At, B0); PG8_MMA(0, 1, At, B1); PG8_BAR; PG8_SCHED;
;             PG8_LDA(At, 1, 1); PG8_STAGE(PG8_SB(1, 0), b3, voffB); PG8_STAGE(PG8_SB(1, 1), b3 + hstep, voffB); PG8_STAGE(PG8_SA(1, 0), a3, voffA);
;             PG8_WAIT_V(8); PG8_WAIT_L(0); PG8_BAR; PG8_MMA(1, 0, At, B0); PG8_MMA(1, 1, At, B1); PG8_BAR; PG8_SCHED;
	s_add_i32 s22, s56, s25
	s_mov_b32 m0, s22
	ds_read_b128 v[216:219], v155 offset:49152
	ds_read_b128 v[220:223], v155 offset:50176
	ds_read_b128 v[224:227], v155 offset:51200
	ds_read_b128 v[228:231], v155 offset:52224
	ds_read_b128 v[232:235], v155 offset:53248
	ds_read_b128 v[236:239], v155 offset:54272
	ds_read_b128 v[240:243], v155 offset:55296
	ds_read_b128 v[244:247], v155 offset:56320
	s_add_u32 vcc_lo, s20, 0x80
	s_addc_u32 vcc_hi, s21, 0
	global_load_lds_dwordx4 v2, vcc
	s_add_i32 m0, s22, 0x2000
	s_add_u32 s20, s20, 0x80080
	s_addc_u32 s21, s21, 0
	s_add_i32 s22, s57, s25
	s_add_u32 vcc_lo, s20, 0xfff80000
	s_addc_u32 vcc_hi, s21, -1
	global_load_lds_dwordx4 v0, vcc
	s_mov_b32 m0, s22
	s_nop 0
	global_load_lds_dwordx4 v2, s[20:21]
	s_add_i32 m0, s22, 0x2000
	s_nop 0
	global_load_lds_dwordx4 v0, s[20:21]
	v_lshl_add_u64 v[150:151], v[250:251], 0, s[36:37]
	s_mov_b32 m0, s31
	s_nop 0
	global_load_lds_dwordx4 v[150:151], off
	v_lshl_add_u64 v[150:151], v[252:253], 0, s[36:37]
	s_mov_b32 m0, s34
	s_nop 0
	global_load_lds_dwordx4 v[150:151], off
	s_waitcnt vmcnt(8)
	s_waitcnt lgkmcnt(0)
	s_barrier
	s_setprio 1
	v_mfma_f32_16x16x32_bf16 v[64:67], v[184:187], v[216:219], v[64:67]
	v_mfma_f32_16x16x32_bf16 v[56:59], v[192:195], v[216:219], v[56:59]
	v_mfma_f32_16x16x32_bf16 v[48:51], v[184:187], v[224:227], v[48:51]
	v_mfma_f32_16x16x32_bf16 v[40:43], v[192:195], v[224:227], v[40:43]
	v_mfma_f32_16x16x32_bf16 v[32:35], v[184:187], v[232:235], v[32:35]
	v_mfma_f32_16x16x32_bf16 v[24:27], v[192:195], v[232:235], v[24:27]
	v_mfma_f32_16x16x32_bf16 v[16:19], v[184:187], v[240:243], v[16:19]
	v_mfma_f32_16x16x32_bf16 v[8:11], v[192:195], v[240:243], v[8:11]
	v_mfma_f32_16x16x32_bf16 v[64:67], v[188:191], v[220:223], v[64:67]
	v_mfma_f32_16x16x32_bf16 v[56:59], v[196:199], v[220:223], v[56:59]
	v_mfma_f32_16x16x32_bf16 v[48:51], v[188:191], v[228:231], v[48:51]
	v_mfma_f32_16x16x32_bf16 v[40:43], v[196:199], v[228:231], v[40:43]
	v_mfma_f32_16x16x32_bf16 v[32:35], v[188:191], v[236:239], v[32:35]
	v_mfma_f32_16x16x32_bf16 v[24:27], v[196:199], v[236:239], v[24:27]
	v_mfma_f32_16x16x32_bf16 v[16:19], v[188:191], v[244:247], v[16:19]
	v_mfma_f32_16x16x32_bf16 v[8:11], v[196:199], v[244:247], v[8:11]
	v_mfma_f32_16x16x32_bf16 v[60:63], v[200:203], v[216:219], v[60:63]
	v_mfma_f32_16x16x32_bf16 v[52:55], v[208:211], v[216:219], v[52:55]
	v_mfma_f32_16x16x32_bf16 v[44:47], v[200:203], v[224:227], v[44:47]
	v_mfma_f32_16x16x32_bf16 v[36:39], v[208:211], v[224:227], v[36:39]
	v_mfma_f32_16x16x32_bf16 v[28:31], v[200:203], v[232:235], v[28:31]
	v_mfma_f32_16x16x32_bf16 v[20:23], v[208:211], v[232:235], v[20:23]
	v_mfma_f32_16x16x32_bf16 v[12:15], v[200:203], v[240:243], v[12:15]
	v_mfma_f32_16x16x32_bf16 v[4:7], v[208:211], v[240:243], v[4:7]
	v_mfma_f32_16x16x32_bf16 v[60:63], v[204:207], v[220:223], v[60:63]
	v_mfma_f32_16x16x32_bf16 v[52:55], v[212:215], v[220:223], v[52:55]
	v_mfma_f32_16x16x32_bf16 v[44:47], v[204:207], v[228:231], v[44:47]
	v_mfma_f32_16x16x32_bf16 v[36:39], v[212:215], v[228:231], v[36:39]
	v_mfma_f32_16x16x32_bf16 v[28:31], v[204:207], v[236:239], v[28:31]
	v_mfma_f32_16x16x32_bf16 v[20:23], v[212:215], v[236:239], v[20:23]
	v_mfma_f32_16x16x32_bf16 v[12:15], v[204:207], v[244:247], v[12:15]
	v_mfma_f32_16x16x32_bf16 v[4:7], v[212:215], v[244:247], v[4:7]
	s_setprio 0
	s_barrier
	s_add_i32 s51, s51, 2
	s_add_u32 s18, s18, 0x100
	s_addc_u32 s19, s19, 0
	s_add_u32 s45, s45, 0x100
	s_addc_u32 s50, s50, 0
	s_cmp_gt_u32 s51, 29
.LBB0_85:
	s_add_u32 s20, s18, 0xfff80080
	s_addc_u32 s21, s19, -1
	s_add_i32 s56, 0, 0x10000
	s_cmp_eq_u32 s51, 28
	s_cselect_b32 s23, s11, s21
	s_cselect_b32 s22, s42, s20
	v_add_u32_e32 v150, s56, v153
	s_cselect_b32 s21, s9, s50
	s_cselect_b32 s20, s44, s45
	s_add_i32 s63, 0, 0x14000
	ds_read_b128 v[184:187], v150
	ds_read_b128 v[188:191], v150 offset:1024
	ds_read_b128 v[192:195], v150 offset:2048
	ds_read_b128 v[196:199], v150 offset:3072
	v_add_u32_e32 v150, s63, v153
	ds_read_b128 v[200:203], v150
	ds_read_b128 v[204:207], v150 offset:1024
	ds_read_b128 v[208:211], v150 offset:2048
	ds_read_b128 v[212:215], v150 offset:3072
	s_add_i32 m0, s27, 0xc000
	ds_read_b128 v[216:219], v155
	ds_read_b128 v[220:223], v155 offset:1024
	ds_read_b128 v[224:227], v155 offset:2048
	ds_read_b128 v[228:231], v155 offset:3072
	ds_read_b128 v[232:235], v155 offset:4096
	ds_read_b128 v[236:239], v155 offset:5120
	ds_read_b128 v[240:243], v155 offset:6144
	ds_read_b128 v[244:247], v155 offset:7168
	global_load_lds_dwordx4 v136, s[18:19]
	s_add_i32 m0, s27, 0xe000
	s_nop 0
	global_load_lds_dwordx4 v138, s[18:19]
	s_waitcnt vmcnt(8)
	s_waitcnt lgkmcnt(0)
	s_barrier
; #define PG8_STAGE(bufoff, gbase, voff) do { _Pragma("unroll") for (int _i = 0; _i < 2; ++_i) \
;         __builtin_amdgcn_global_load_lds((const unsigned*)((const char*)(gbase) + (voff)[_i]), (PG8_LAS unsigned*)(lds + (bufoff) + ldsw + _i * 8192), 16, 0, 0); } while (0)
; #define PG8_LDA(dst, b, h) do { _Pragma("unroll") for (int m = 0; m < 4; ++m) _Pragma("unroll") for (int k = 0; k < 2; ++k) dst[m][k] = *(const PG8_LAS bf16x8*)(lds + PG8_SA(b, h) + aoff + m * 2048 + k * 1024); } while (0)
; #define PG8_LDB(dst, b, h) do { _Pragma("unroll") for (int n = 0; n < 2; ++n) _Pragma("unroll") for (int k = 0; k < 2; ++k) dst[n][k] = *(const PG8_LAS bf16x8*)(lds + PG8_SB(b, h) + boff + n * 2048 + k * 1024); } while (0)
; #define PG8_MMA(ai, bj, At, Bt) do { __builtin_amdgcn_s_setprio(1); _Pragma("unroll") for (int m = 0; m < 4; ++m) _Pragma("unroll") for (int n = 0; n < 2; ++n) _Pragma("unroll") for (int k = 0; k < 2; ++k) \
;         acc[ai][bj][m][n] = __builtin_amdgcn_mfma_f32_16x16x32_bf16(Bt[n][k], At[m][k], acc[ai][bj][m][n], 0, 0, 0); __builtin_amdgcn_s_setprio(0); } while (0)
; #define PG8_WAIT_V(n) asm volatile("s_waitcnt vmcnt(" #n ")" ::: "memory")
; #define PG8_WAIT_L(n) asm volatile("s_waitcnt lgkmcnt(" #n ")" ::: "memory")
; #define PG8_BAR __builtin_amdgcn_s_barrier()
; #define PG8_SCHED __builtin_amdgcn_sched_barrier(0)
; template <class Epi, class Sched, bool ALIGN_EPI = false, bool SP2 = false>
; __device__ __forceinline__ void gemm_phase(PG8_LAS unsigned char* lds, const Gemm g, const Sched& S, const Epi& E) {
;     ...
;             PG8_LDB(B0, 0, 0); PG8_LDB(B1, 0, 1); PG8_SCHED; PG8_LDA(At, 0, 0); PG8_STAGE(PG8_SA(1, 1), a1 + hstep, voffA);
;             PG8_WAIT_V(8); PG8_WAIT_L(0); PG8_BAR; PG8_MMA(0, 0, At, B0); PG8_MMA(0, 1, At, B1); PG8_BAR; PG8_SCHED;
;             PG8_LDA(At, 0, 1); PG8_STAGE(PG8_SB(0, 0), b2, voffB); PG8_STAGE(PG8_SB(0, 1), b2 + hstep, voffB); PG8_STAGE(PG8_SA(0, 0), a2, voffA);
;             PG8_WAIT_V(8); PG8_WAIT_L(0); PG8_BAR; PG8_MMA(1, 0, At, B0); PG8_MMA(1, 1, At, B1); PG8_BAR; PG8_SCHED;
	s_setprio 1
	v_mfma_f32_16x16x32_bf16 v[128:131], v[184:187], v[216:219], v[128:131]
	v_mfma_f32_16x16x32_bf16 v[120:123], v[192:195], v[216:219], v[120:123]
	v_mfma_f32_16x16x32_bf16 v[112:115], v[184:187], v[224:227], v[112:115]
	v_mfma_f32_16x16x32_bf16 v[104:107], v[192:195], v[224:227], v[104:107]
	v_mfma_f32_16x16x32_bf16 v[96:99], v[184:187], v[232:235], v[96:99]
	v_mfma_f32_16x16x32_bf16 v[88:91], v[192:195], v[232:235], v[88:91]
	v_mfma_f32_16x16x32_bf16 v[80:83], v[184:187], v[240:243], v[80:83]
	v_mfma_f32_16x16x32_bf16 v[72:75], v[192:195], v[240:243], v[72:75]
	v_mfma_f32_16x16x32_bf16 v[128:131], v[188:191], v[220:223], v[128:131]
	v_mfma_f32_16x16x32_bf16 v[120:123], v[196:199], v[220:223], v[120:123]
	v_mfma_f32_16x16x32_bf16 v[112:115], v[188:191], v[228:231], v[112:115]
	v_mfma_f32_16x16x32_bf16 v[104:107], v[196:199], v[228:231], v[104:107]
	v_mfma_f32_16x16x32_bf16 v[96:99], v[188:191], v[236:239], v[96:99]
	v_mfma_f32_16x16x32_bf16 v[88:91], v[196:199], v[236:239], v[88:91]
	v_mfma_f32_16x16x32_bf16 v[80:83], v[188:191], v[244:247], v[80:83]
	v_mfma_f32_16x16x32_bf16 v[72:75], v[196:199], v[244:247], v[72:75]
	v_mfma_f32_16x16x32_bf16 v[124:127], v[200:203], v[216:219], v[124:127]
	v_mfma_f32_16x16x32_bf16 v[116:119], v[208:211], v[216:219], v[116:119]
	v_mfma_f32_16x16x32_bf16 v[108:111], v[200:203], v[224:227], v[108:111]
	v_mfma_f32_16x16x32_bf16 v[100:103], v[208:211], v[224:227], v[100:103]
	v_mfma_f32_16x16x32_bf16 v[92:95], v[200:203], v[232:235], v[92:95]
	v_mfma_f32_16x16x32_bf16 v[84:87], v[208:211], v[232:235], v[84:87]
	v_mfma_f32_16x16x32_bf16 v[76:79], v[200:203], v[240:243], v[76:79]
	v_mfma_f32_16x16x32_bf16 v[68:71], v[208:211], v[240:243], v[68:71]
	v_mfma_f32_16x16x32_bf16 v[124:127], v[204:207], v[220:223], v[124:127]
	v_mfma_f32_16x16x32_bf16 v[116:119], v[212:215], v[220:223], v[116:119]
	v_mfma_f32_16x16x32_bf16 v[108:111], v[204:207], v[228:231], v[108:111]
	v_mfma_f32_16x16x32_bf16 v[100:103], v[212:215], v[228:231], v[100:103]
	v_mfma_f32_16x16x32_bf16 v[92:95], v[204:207], v[236:239], v[92:95]
	v_mfma_f32_16x16x32_bf16 v[84:87], v[212:215], v[236:239], v[84:87]
	v_mfma_f32_16x16x32_bf16 v[76:79], v[204:207], v[244:247], v[76:79]
	v_mfma_f32_16x16x32_bf16 v[68:71], v[212:215], v[244:247], v[68:71]
	s_setprio 0
	s_barrier
	s_add_i32 s56, s56, s25
	s_mov_b32 m0, s56
	ds_read_b128 v[216:219], v155 offset:16384
	ds_read_b128 v[220:223], v155 offset:17408
	ds_read_b128 v[224:227], v155 offset:18432
	ds_read_b128 v[228:231], v155 offset:19456
	ds_read_b128 v[232:235], v155 offset:20480
	ds_read_b128 v[236:239], v155 offset:21504
	ds_read_b128 v[240:243], v155 offset:22528
	ds_read_b128 v[244:247], v155 offset:23552
	global_load_lds_dwordx4 v2, s[20:21]
	s_add_i32 m0, s56, 0x2000
	s_add_u32 s56, s20, 0x80000
	s_addc_u32 s57, s21, 0
	s_add_i32 s63, s63, s25
	global_load_lds_dwordx4 v0, s[20:21]
	s_mov_b32 m0, s63
	v_lshl_add_u64 v[252:253], s[22:23], 0, v[132:133]
	global_load_lds_dwordx4 v2, s[56:57]
	s_add_i32 m0, s63, 0x2000
	s_nop 0
	global_load_lds_dwordx4 v0, s[56:57]
	v_lshl_add_u64 v[250:251], s[22:23], 0, v[134:135]
	s_mov_b32 m0, s27
	s_nop 0
	global_load_lds_dwordx4 v[250:251], off
	s_mov_b32 m0, s28
	s_nop 0
	global_load_lds_dwordx4 v[252:253], off
	s_waitcnt vmcnt(8)
	s_waitcnt lgkmcnt(0)
	s_barrier
	s_setprio 1
	v_mfma_f32_16x16x32_bf16 v[64:67], v[184:187], v[216:219], v[64:67]
	v_mfma_f32_16x16x32_bf16 v[56:59], v[192:195], v[216:219], v[56:59]
	v_mfma_f32_16x16x32_bf16 v[48:51], v[184:187], v[224:227], v[48:51]
	v_mfma_f32_16x16x32_bf16 v[40:43], v[192:195], v[224:227], v[40:43]
	v_mfma_f32_16x16x32_bf16 v[32:35], v[184:187], v[232:235], v[32:35]
	v_mfma_f32_16x16x32_bf16 v[24:27], v[192:195], v[232:235], v[24:27]
	v_mfma_f32_16x16x32_bf16 v[16:19], v[184:187], v[240:243], v[16:19]
	v_mfma_f32_16x16x32_bf16 v[8:11], v[192:195], v[240:243], v[8:11]
	v_mfma_f32_16x16x32_bf16 v[64:67], v[188:191], v[220:223], v[64:67]
	v_mfma_f32_16x16x32_bf16 v[56:59], v[196:199], v[220:223], v[56:59]
	v_mfma_f32_16x16x32_bf16 v[48:51], v[188:191], v[228:231], v[48:51]
	v_mfma_f32_16x16x32_bf16 v[40:43], v[196:199], v[228:231], v[40:43]
	v_mfma_f32_16x16x32_bf16 v[32:35], v[188:191], v[236:239], v[32:35]
	v_mfma_f32_16x16x32_bf16 v[24:27], v[196:199], v[236:239], v[24:27]
	v_mfma_f32_16x16x32_bf16 v[16:19], v[188:191], v[244:247], v[16:19]
	v_mfma_f32_16x16x32_bf16 v[8:11], v[196:199], v[244:247], v[8:11]
	v_mfma_f32_16x16x32_bf16 v[60:63], v[200:203], v[216:219], v[60:63]
	v_mfma_f32_16x16x32_bf16 v[52:55], v[208:211], v[216:219], v[52:55]
	v_mfma_f32_16x16x32_bf16 v[44:47], v[200:203], v[224:227], v[44:47]
	v_mfma_f32_16x16x32_bf16 v[36:39], v[208:211], v[224:227], v[36:39]
	v_mfma_f32_16x16x32_bf16 v[28:31], v[200:203], v[232:235], v[28:31]
	v_mfma_f32_16x16x32_bf16 v[20:23], v[208:211], v[232:235], v[20:23]
	v_mfma_f32_16x16x32_bf16 v[12:15], v[200:203], v[240:243], v[12:15]
	v_mfma_f32_16x16x32_bf16 v[4:7], v[208:211], v[240:243], v[4:7]
	v_mfma_f32_16x16x32_bf16 v[60:63], v[204:207], v[220:223], v[60:63]
	v_mfma_f32_16x16x32_bf16 v[52:55], v[212:215], v[220:223], v[52:55]
	v_mfma_f32_16x16x32_bf16 v[44:47], v[204:207], v[228:231], v[44:47]
	v_mfma_f32_16x16x32_bf16 v[36:39], v[212:215], v[228:231], v[36:39]
	v_mfma_f32_16x16x32_bf16 v[28:31], v[204:207], v[236:239], v[28:31]
	v_mfma_f32_16x16x32_bf16 v[20:23], v[212:215], v[236:239], v[20:23]
	v_mfma_f32_16x16x32_bf16 v[12:15], v[204:207], v[244:247], v[12:15]
	v_mfma_f32_16x16x32_bf16 v[4:7], v[212:215], v[244:247], v[4:7]
	s_setprio 0
	s_barrier
; #define PG8_STAGE(bufoff, gbase, voff) do { _Pragma("unroll") for (int _i = 0; _i < 2; ++_i) \
;         __builtin_amdgcn_global_load_lds((const unsigned*)((const char*)(gbase) + (voff)[_i]), (PG8_LAS unsigned*)(lds + (bufoff) + ldsw + _i * 8192), 16, 0, 0); } while (0)
; #define PG8_LDA(dst, b, h) do { _Pragma("unroll") for (int m = 0; m < 4; ++m) _Pragma("unroll") for (int k = 0; k < 2; ++k) dst[m][k] = *(const PG8_LAS bf16x8*)(lds + PG8_SA(b, h) + aoff + m * 2048 + k * 1024); } while (0)
; #define PG8_LDB(dst, b, h) do { _Pragma("unroll") for (int n = 0; n < 2; ++n) _Pragma("unroll") for (int k = 0; k < 2; ++k) dst[n][k] = *(const PG8_LAS bf16x8*)(lds + PG8_SB(b, h) + boff + n * 2048 + k * 1024); } while (0)
; #define PG8_MMA(ai, bj, At, Bt) do { __builtin_amdgcn_s_setprio(1); _Pragma("unroll") for (int m = 0; m < 4; ++m) _Pragma("unroll") for (int n = 0; n < 2; ++n) _Pragma("unroll") for (int k = 0; k < 2; ++k) \
;         acc[ai][bj][m][n] = __builtin_amdgcn_mfma_f32_16x16x32_bf16(Bt[n][k], At[m][k], acc[ai][bj][m][n], 0, 0, 0); __builtin_amdgcn_s_setprio(0); } while (0)
; #define PG8_WAIT_V(n) asm volatile("s_waitcnt vmcnt(" #n ")" ::: "memory")
; #define PG8_WAIT_L(n) asm volatile("s_waitcnt lgkmcnt(" #n ")" ::: "memory")
; #define PG8_BAR __builtin_amdgcn_s_barrier()
; #define PG8_SCHED __builtin_amdgcn_sched_barrier(0)
; template <class Epi, class Sched, bool ALIGN_EPI = false, bool SP2 = false>
; __device__ __forceinline__ void gemm_phase(PG8_LAS unsigned char* lds, const Gemm g, const Sched& S, const Epi& E) {
;     ...
;             PG8_LDB(B0, 1, 0); PG8_LDB(B1, 1, 1); PG8_SCHED; PG8_LDA(At, 1, 0); PG8_STAGE(PG8_SA(0, 1), a2 + hstep, voffA);
;             PG8_WAIT_V(8); PG8_WAIT_L(0); PG8_BAR; PG8_MMA(0, 0, At, B0); PG8_MMA(0, 1, At, B1); PG8_BAR; PG8_SCHED;
;             PG8_LDA(At, 1, 1); PG8_STAGE(PG8_SB(1, 0), b3, voffB); PG8_STAGE(PG8_SB(1, 1), b3 + hstep, voffB); PG8_STAGE(PG8_SA(1, 0), a3, voffA);
;             PG8_WAIT_V(8); PG8_WAIT_L(0); PG8_BAR; PG8_MMA(1, 0, At, B0); PG8_MMA(1, 1, At, B1); PG8_BAR; PG8_SCHED;
;     ...
;         if constexpr (ALIGN_EPI) { if (wr == 0) PG8_BAR; }
	s_add_i32 s56, 0, 0x18000
	v_add_u32_e32 v161, s56, v153
	s_add_i32 s57, 0, 0x1c000
	ds_read_b128 v[184:187], v161
	ds_read_b128 v[188:191], v161 offset:1024
	ds_read_b128 v[192:195], v161 offset:2048
	ds_read_b128 v[196:199], v161 offset:3072
	v_add_u32_e32 v161, s57, v153
	ds_read_b128 v[200:203], v161
	ds_read_b128 v[204:207], v161 offset:1024
	ds_read_b128 v[208:211], v161 offset:2048
	ds_read_b128 v[212:215], v161 offset:3072
	s_add_u32 s22, s22, 0x80000
	s_addc_u32 s23, s23, 0
	s_mov_b32 m0, s29
	ds_read_b128 v[216:219], v155 offset:32768
	ds_read_b128 v[220:223], v155 offset:33792
	ds_read_b128 v[224:227], v155 offset:34816
	ds_read_b128 v[228:231], v155 offset:35840
	ds_read_b128 v[232:235], v155 offset:36864
	ds_read_b128 v[236:239], v155 offset:37888
	ds_read_b128 v[240:243], v155 offset:38912
	ds_read_b128 v[244:247], v155 offset:39936
	global_load_lds_dwordx4 v134, s[22:23]
	s_mov_b32 m0, s30
	s_nop 0
	global_load_lds_dwordx4 v132, s[22:23]
	s_waitcnt vmcnt(8)
	s_waitcnt lgkmcnt(0)
	s_barrier
	s_setprio 1
	v_mfma_f32_16x16x32_bf16 v[128:131], v[184:187], v[216:219], v[128:131]
	v_mfma_f32_16x16x32_bf16 v[120:123], v[192:195], v[216:219], v[120:123]
	v_mfma_f32_16x16x32_bf16 v[112:115], v[184:187], v[224:227], v[112:115]
	v_mfma_f32_16x16x32_bf16 v[104:107], v[192:195], v[224:227], v[104:107]
	v_mfma_f32_16x16x32_bf16 v[96:99], v[184:187], v[232:235], v[96:99]
	v_mfma_f32_16x16x32_bf16 v[88:91], v[192:195], v[232:235], v[88:91]
	v_mfma_f32_16x16x32_bf16 v[80:83], v[184:187], v[240:243], v[80:83]
	v_mfma_f32_16x16x32_bf16 v[72:75], v[192:195], v[240:243], v[72:75]
	v_mfma_f32_16x16x32_bf16 v[128:131], v[188:191], v[220:223], v[128:131]
	v_mfma_f32_16x16x32_bf16 v[120:123], v[196:199], v[220:223], v[120:123]
	v_mfma_f32_16x16x32_bf16 v[112:115], v[188:191], v[228:231], v[112:115]
	v_mfma_f32_16x16x32_bf16 v[104:107], v[196:199], v[228:231], v[104:107]
	v_mfma_f32_16x16x32_bf16 v[96:99], v[188:191], v[236:239], v[96:99]
	v_mfma_f32_16x16x32_bf16 v[88:91], v[196:199], v[236:239], v[88:91]
	v_mfma_f32_16x16x32_bf16 v[80:83], v[188:191], v[244:247], v[80:83]
	v_mfma_f32_16x16x32_bf16 v[72:75], v[196:199], v[244:247], v[72:75]
	v_mfma_f32_16x16x32_bf16 v[124:127], v[200:203], v[216:219], v[124:127]
	v_mfma_f32_16x16x32_bf16 v[116:119], v[208:211], v[216:219], v[116:119]
	v_mfma_f32_16x16x32_bf16 v[108:111], v[200:203], v[224:227], v[108:111]
	v_mfma_f32_16x16x32_bf16 v[100:103], v[208:211], v[224:227], v[100:103]
	v_mfma_f32_16x16x32_bf16 v[92:95], v[200:203], v[232:235], v[92:95]
	v_mfma_f32_16x16x32_bf16 v[84:87], v[208:211], v[232:235], v[84:87]
	v_mfma_f32_16x16x32_bf16 v[76:79], v[200:203], v[240:243], v[76:79]
	v_mfma_f32_16x16x32_bf16 v[68:71], v[208:211], v[240:243], v[68:71]
	v_mfma_f32_16x16x32_bf16 v[124:127], v[204:207], v[220:223], v[124:127]
	v_mfma_f32_16x16x32_bf16 v[116:119], v[212:215], v[220:223], v[116:119]
	v_mfma_f32_16x16x32_bf16 v[108:111], v[204:207], v[228:231], v[108:111]
	v_mfma_f32_16x16x32_bf16 v[100:103], v[212:215], v[228:231], v[100:103]
	v_mfma_f32_16x16x32_bf16 v[92:95], v[204:207], v[236:239], v[92:95]
	v_mfma_f32_16x16x32_bf16 v[84:87], v[212:215], v[236:239], v[84:87]
	v_mfma_f32_16x16x32_bf16 v[76:79], v[204:207], v[244:247], v[76:79]
	v_mfma_f32_16x16x32_bf16 v[68:71], v[212:215], v[244:247], v[68:71]
	s_setprio 0
	s_barrier
	s_add_i32 s22, s56, s25
	s_mov_b32 m0, s22
	ds_read_b128 v[216:219], v155 offset:49152
	ds_read_b128 v[220:223], v155 offset:50176
	ds_read_b128 v[224:227], v155 offset:51200
	ds_read_b128 v[228:231], v155 offset:52224
	ds_read_b128 v[232:235], v155 offset:53248
	ds_read_b128 v[236:239], v155 offset:54272
	ds_read_b128 v[240:243], v155 offset:55296
	ds_read_b128 v[244:247], v155 offset:56320
	s_add_u32 vcc_lo, s20, 0x80
	s_addc_u32 vcc_hi, s21, 0
	global_load_lds_dwordx4 v2, vcc
	s_add_i32 m0, s22, 0x2000
	s_add_u32 s20, s20, 0x80080
	s_addc_u32 s21, s21, 0
	s_add_i32 s22, s57, s25
	s_add_u32 vcc_lo, s20, 0xfff80000
	s_addc_u32 vcc_hi, s21, -1
	global_load_lds_dwordx4 v0, vcc
	s_mov_b32 m0, s22
	s_nop 0
	global_load_lds_dwordx4 v2, s[20:21]
	s_add_i32 m0, s22, 0x2000
	s_nop 0
	global_load_lds_dwordx4 v0, s[20:21]
	v_lshl_add_u64 v[150:151], v[250:251], 0, s[36:37]
	s_mov_b32 m0, s31
	s_nop 0
	global_load_lds_dwordx4 v[150:151], off
	v_lshl_add_u64 v[150:151], v[252:253], 0, s[36:37]
	s_mov_b32 m0, s34
	s_nop 0
	global_load_lds_dwordx4 v[150:151], off
	s_waitcnt vmcnt(8)
	s_waitcnt lgkmcnt(0)
	s_barrier
	s_setprio 1
	v_mfma_f32_16x16x32_bf16 v[64:67], v[184:187], v[216:219], v[64:67]
	v_mfma_f32_16x16x32_bf16 v[56:59], v[192:195], v[216:219], v[56:59]
	v_mfma_f32_16x16x32_bf16 v[48:51], v[184:187], v[224:227], v[48:51]
	v_mfma_f32_16x16x32_bf16 v[40:43], v[192:195], v[224:227], v[40:43]
	v_mfma_f32_16x16x32_bf16 v[32:35], v[184:187], v[232:235], v[32:35]
	v_mfma_f32_16x16x32_bf16 v[24:27], v[192:195], v[232:235], v[24:27]
	v_mfma_f32_16x16x32_bf16 v[16:19], v[184:187], v[240:243], v[16:19]
	v_mfma_f32_16x16x32_bf16 v[8:11], v[192:195], v[240:243], v[8:11]
	v_mfma_f32_16x16x32_bf16 v[64:67], v[188:191], v[220:223], v[64:67]
	v_mfma_f32_16x16x32_bf16 v[56:59], v[196:199], v[220:223], v[56:59]
	v_mfma_f32_16x16x32_bf16 v[48:51], v[188:191], v[228:231], v[48:51]
	v_mfma_f32_16x16x32_bf16 v[40:43], v[196:199], v[228:231], v[40:43]
	v_mfma_f32_16x16x32_bf16 v[32:35], v[188:191], v[236:239], v[32:35]
	v_mfma_f32_16x16x32_bf16 v[24:27], v[196:199], v[236:239], v[24:27]
	v_mfma_f32_16x16x32_bf16 v[16:19], v[188:191], v[244:247], v[16:19]
	v_mfma_f32_16x16x32_bf16 v[8:11], v[196:199], v[244:247], v[8:11]
	v_mfma_f32_16x16x32_bf16 v[60:63], v[200:203], v[216:219], v[60:63]
	v_mfma_f32_16x16x32_bf16 v[52:55], v[208:211], v[216:219], v[52:55]
	v_mfma_f32_16x16x32_bf16 v[44:47], v[200:203], v[224:227], v[44:47]
	v_mfma_f32_16x16x32_bf16 v[36:39], v[208:211], v[224:227], v[36:39]
	v_mfma_f32_16x16x32_bf16 v[28:31], v[200:203], v[232:235], v[28:31]
	v_mfma_f32_16x16x32_bf16 v[20:23], v[208:211], v[232:235], v[20:23]
	v_mfma_f32_16x16x32_bf16 v[12:15], v[200:203], v[240:243], v[12:15]
	v_mfma_f32_16x16x32_bf16 v[4:7], v[208:211], v[240:243], v[4:7]
	v_mfma_f32_16x16x32_bf16 v[60:63], v[204:207], v[220:223], v[60:63]
	v_mfma_f32_16x16x32_bf16 v[52:55], v[212:215], v[220:223], v[52:55]
	v_mfma_f32_16x16x32_bf16 v[44:47], v[204:207], v[228:231], v[44:47]
	v_mfma_f32_16x16x32_bf16 v[36:39], v[212:215], v[228:231], v[36:39]
	v_mfma_f32_16x16x32_bf16 v[28:31], v[204:207], v[236:239], v[28:31]
	v_mfma_f32_16x16x32_bf16 v[20:23], v[212:215], v[236:239], v[20:23]
	v_mfma_f32_16x16x32_bf16 v[12:15], v[204:207], v[244:247], v[12:15]
	v_mfma_f32_16x16x32_bf16 v[4:7], v[212:215], v[244:247], v[4:7]
	s_setprio 0
	s_barrier
	s_add_i32 s51, s51, 2
	s_add_u32 s18, s18, 0x100
	s_addc_u32 s19, s19, 0
	s_add_u32 s45, s45, 0x100
	s_addc_u32 s50, s50, 0
	s_cmp_gt_u32 s51, 29
	s_cbranch_scc0 .LBB0_85
	s_and_b64 vcc, exec, s[6:7]
	s_cbranch_vccz .LBB0_88
	s_barrier

; #define PG8_STAGE(bufoff, gbase, voff) do { _Pragma("unroll") for (int _i = 0; _i < 2; ++_i) \
;         __builtin_amdgcn_global_load_lds((const unsigned*)((const char*)(gbase) + (voff)[_i]), (PG8_LAS unsigned*)(lds + (bufoff) + ldsw + _i * 8192), 16, 0, 0); } while (0)
; #define PG8_LDA(dst, b, h) do { _Pragma("unroll") for (int m = 0; m < 4; ++m) _Pragma("unroll") for (int k = 0; k < 2; ++k) dst[m][k] = *(const PG8_LAS bf16x8*)(lds + PG8_SA(b, h) + aoff + m * 2048 + k * 1024); } while (0)
; #define PG8_LDB(dst, b, h) do { _Pragma("unroll") for (int n = 0; n < 2; ++n) _Pragma("unroll") for (int k = 0; k < 2; ++k) dst[n][k] = *(const PG8_LAS bf16x8*)(lds + PG8_SB(b, h) + boff + n * 2048 + k * 1024); } while (0)
; #define PG8_MMA(ai, bj, At, Bt) do { __builtin_amdgcn_s_setprio(1); _Pragma("unroll") for (int m = 0; m < 4; ++m) _Pragma("unroll") for (int n = 0; n < 2; ++n) _Pragma("unroll") for (int k = 0; k < 2; ++k) \
;         acc[ai][bj][m][n] = __builtin_amdgcn_mfma_f32_16x16x32_bf16(Bt[n][k], At[m][k], acc[ai][bj][m][n], 0, 0, 0); __builtin_amdgcn_s_setprio(0); } while (0)
; #define PG8_WAIT_V(n) asm volatile("s_waitcnt vmcnt(" #n ")" ::: "memory")
; #define PG8_BAR __builtin_amdgcn_s_barrier()
; template <class Epi, class Sched, bool ALIGN_EPI = false, bool SP2 = false>
; __device__ __forceinline__ void gemm_phase(PG8_LAS unsigned char* lds, const Gemm g, const Sched& S, const Epi& E) {
;     ...
;         for (int t = 0; t < nt; t += 2) {
;             const bool last = (t == nt - 2);
;             const char* a1 = cA + (size_t)(t + 1) * kstep;
;             const char* a2 = last ? nA : cA + (size_t)(t + 2) * kstep; const char* b2 = last ? nB : cB + (size_t)(t + 2) * kstep;
;             const char* a3 = a2 + kstep; const char* b3 = b2 + kstep;
;             if (last && has_next) S.a_ready(nxt);
;             if constexpr (SP2) {
;             PG8_LDB(B0, 0, 0); PG8_LDB(B1, 0, 1); PG8_SCHED; PG8_LDA(At, 0, 0); PG8_STAGE(PG8_SA(1, 1), a1 + hstep, voffA);
;             PG8_WAIT_V(8); PG8_WAIT_L(0); PG8_BAR; PG8_MMA(0, 0, At, B0); PG8_MMA(0, 1, At, B1); PG8_BAR; PG8_SCHED;
;             PG8_LDA(At, 0, 1); PG8_STAGE(PG8_SB(0, 0), b2, voffB); PG8_STAGE(PG8_SB(0, 1), b2 + hstep, voffB); PG8_STAGE(PG8_SA(0, 0), a2, voffA);
;             PG8_WAIT_V(8); PG8_WAIT_L(0); PG8_BAR; PG8_MMA(1, 0, At, B0); PG8_MMA(1, 1, At, B1); PG8_BAR; PG8_SCHED;
.LBB0_166:
	s_add_u32 s51, s16, 0x100
	s_addc_u32 s56, s17, 0
	s_mov_b32 s57, -2
	s_waitcnt lgkmcnt(0)
	s_add_u32 s16, s14, 0x100
	s_addc_u32 s17, s15, 0
	s_add_i32 s63, 0, 0x10000
	s_cmpk_eq_i32 s57, 0x54
	s_cselect_b32 s21, s7, s17
	s_cselect_b32 s20, s6, s16
	s_cselect_b32 s19, s13, s56
	s_cselect_b32 s18, s12, s51
	s_add_i32 s64, 0, 0x14000
	v_add_u32_e32 v162, s63, v185
	v_add_u32_e32 v166, s64, v185
	ds_read_b128 v[132:135], v162
	ds_read_b128 v[136:139], v162 offset:1024
	ds_read_b128 v[158:161], v162 offset:2048
	ds_read_b128 v[162:165], v162 offset:3072
	ds_read_b128 v[188:191], v166
	ds_read_b128 v[192:195], v166 offset:1024
	ds_read_b128 v[196:199], v166 offset:2048
	ds_read_b128 v[200:203], v166 offset:3072
	s_add_i32 m0, s26, 0xc000
	ds_read_b128 v[204:207], v187
	ds_read_b128 v[208:211], v187 offset:1024
	ds_read_b128 v[212:215], v187 offset:2048
	ds_read_b128 v[216:219], v187 offset:3072
	ds_read_b128 v[220:223], v187 offset:4096
	ds_read_b128 v[224:227], v187 offset:5120
	ds_read_b128 v[228:231], v187 offset:6144
	ds_read_b128 v[232:235], v187 offset:7168
	global_load_lds_dwordx4 v154, s[14:15]
	s_add_i32 m0, s26, 0xe000
	s_nop 0
	global_load_lds_dwordx4 v156, s[14:15]
	s_waitcnt vmcnt(8)
	s_waitcnt lgkmcnt(0)
	s_barrier
	s_setprio 1
	v_mfma_f32_16x16x32_bf16 v[128:131], v[132:135], v[204:207], 0
	v_mfma_f32_16x16x32_bf16 v[124:127], v[158:161], v[204:207], 0
	v_mfma_f32_16x16x32_bf16 v[112:115], v[132:135], v[212:215], 0
	v_mfma_f32_16x16x32_bf16 v[108:111], v[158:161], v[212:215], 0
	v_mfma_f32_16x16x32_bf16 v[96:99], v[132:135], v[220:223], 0
	v_mfma_f32_16x16x32_bf16 v[92:95], v[158:161], v[220:223], 0
	v_mfma_f32_16x16x32_bf16 v[80:83], v[132:135], v[228:231], 0
	v_mfma_f32_16x16x32_bf16 v[76:79], v[158:161], v[228:231], 0
	v_mfma_f32_16x16x32_bf16 v[128:131], v[136:139], v[208:211], v[128:131]
	v_mfma_f32_16x16x32_bf16 v[124:127], v[162:165], v[208:211], v[124:127]
	v_mfma_f32_16x16x32_bf16 v[112:115], v[136:139], v[216:219], v[112:115]
	v_mfma_f32_16x16x32_bf16 v[108:111], v[162:165], v[216:219], v[108:111]
	v_mfma_f32_16x16x32_bf16 v[96:99], v[136:139], v[224:227], v[96:99]
	v_mfma_f32_16x16x32_bf16 v[92:95], v[162:165], v[224:227], v[92:95]
	v_mfma_f32_16x16x32_bf16 v[80:83], v[136:139], v[232:235], v[80:83]
	v_mfma_f32_16x16x32_bf16 v[76:79], v[162:165], v[232:235], v[76:79]
	v_mfma_f32_16x16x32_bf16 v[120:123], v[188:191], v[204:207], 0
	v_mfma_f32_16x16x32_bf16 v[116:119], v[196:199], v[204:207], 0
	v_mfma_f32_16x16x32_bf16 v[104:107], v[188:191], v[212:215], 0
	v_mfma_f32_16x16x32_bf16 v[100:103], v[196:199], v[212:215], 0
	v_mfma_f32_16x16x32_bf16 v[88:91], v[188:191], v[220:223], 0
	v_mfma_f32_16x16x32_bf16 v[84:87], v[196:199], v[220:223], 0
	v_mfma_f32_16x16x32_bf16 v[72:75], v[188:191], v[228:231], 0
	v_mfma_f32_16x16x32_bf16 v[68:71], v[196:199], v[228:231], 0
	v_mfma_f32_16x16x32_bf16 v[120:123], v[192:195], v[208:211], v[120:123]
	v_mfma_f32_16x16x32_bf16 v[116:119], v[200:203], v[208:211], v[116:119]
	v_mfma_f32_16x16x32_bf16 v[104:107], v[192:195], v[216:219], v[104:107]
	v_mfma_f32_16x16x32_bf16 v[100:103], v[200:203], v[216:219], v[100:103]
	v_mfma_f32_16x16x32_bf16 v[88:91], v[192:195], v[224:227], v[88:91]
	v_mfma_f32_16x16x32_bf16 v[84:87], v[200:203], v[224:227], v[84:87]
	v_mfma_f32_16x16x32_bf16 v[72:75], v[192:195], v[232:235], v[72:75]
	v_mfma_f32_16x16x32_bf16 v[68:71], v[200:203], v[232:235], v[68:71]
	s_setprio 0
	s_barrier
	s_add_i32 s14, s63, s25
	s_mov_b32 m0, s14
	ds_read_b128 v[204:207], v187 offset:16384
	ds_read_b128 v[208:211], v187 offset:17408
	ds_read_b128 v[212:215], v187 offset:18432
	ds_read_b128 v[216:219], v187 offset:19456
	ds_read_b128 v[220:223], v187 offset:20480
	ds_read_b128 v[224:227], v187 offset:21504
	ds_read_b128 v[228:231], v187 offset:22528
	ds_read_b128 v[232:235], v187 offset:23552
	global_load_lds_dwordx4 v2, s[18:19]
	s_add_i32 m0, s14, 0x2000
	s_add_u32 s14, s18, 0x160000
	v_lshl_add_u64 v[236:237], s[18:19], 0, v[152:153]
	s_addc_u32 s15, s19, 0
	s_add_i32 s63, s64, s25
	global_load_lds_dwordx4 v[236:237], off
	s_mov_b32 m0, s63
	global_load_lds_dwordx4 v2, s[14:15]
	s_add_i32 m0, s63, 0x2000
	s_nop 0
	global_load_lds_dwordx4 v152, s[14:15]
	s_mov_b32 m0, s26
	s_nop 0
	global_load_lds_dwordx4 v0, s[20:21]
	s_mov_b32 m0, s27
	s_nop 0
	global_load_lds_dwordx4 v150, s[20:21]
	s_waitcnt vmcnt(8)
	s_waitcnt lgkmcnt(0)
	s_barrier
	s_setprio 1
	v_mfma_f32_16x16x32_bf16 v[64:67], v[132:135], v[204:207], 0
	v_mfma_f32_16x16x32_bf16 v[60:63], v[158:161], v[204:207], 0
	v_mfma_f32_16x16x32_bf16 v[48:51], v[132:135], v[212:215], 0
	v_mfma_f32_16x16x32_bf16 v[44:47], v[158:161], v[212:215], 0
	v_mfma_f32_16x16x32_bf16 v[32:35], v[132:135], v[220:223], 0
	v_mfma_f32_16x16x32_bf16 v[28:31], v[158:161], v[220:223], 0
	v_mfma_f32_16x16x32_bf16 v[16:19], v[132:135], v[228:231], 0
	v_mfma_f32_16x16x32_bf16 v[12:15], v[158:161], v[228:231], 0
	v_mfma_f32_16x16x32_bf16 v[64:67], v[136:139], v[208:211], v[64:67]
	v_mfma_f32_16x16x32_bf16 v[60:63], v[162:165], v[208:211], v[60:63]
	v_mfma_f32_16x16x32_bf16 v[48:51], v[136:139], v[216:219], v[48:51]
	v_mfma_f32_16x16x32_bf16 v[44:47], v[162:165], v[216:219], v[44:47]
	v_mfma_f32_16x16x32_bf16 v[32:35], v[136:139], v[224:227], v[32:35]
	v_mfma_f32_16x16x32_bf16 v[28:31], v[162:165], v[224:227], v[28:31]
	v_mfma_f32_16x16x32_bf16 v[16:19], v[136:139], v[232:235], v[16:19]
	v_mfma_f32_16x16x32_bf16 v[12:15], v[162:165], v[232:235], v[12:15]
	v_mfma_f32_16x16x32_bf16 v[56:59], v[188:191], v[204:207], 0
	v_mfma_f32_16x16x32_bf16 v[52:55], v[196:199], v[204:207], 0
	v_mfma_f32_16x16x32_bf16 v[40:43], v[188:191], v[212:215], 0
	v_mfma_f32_16x16x32_bf16 v[36:39], v[196:199], v[212:215], 0
	v_mfma_f32_16x16x32_bf16 v[24:27], v[188:191], v[220:223], 0
	v_mfma_f32_16x16x32_bf16 v[20:23], v[196:199], v[220:223], 0
	v_mfma_f32_16x16x32_bf16 v[8:11], v[188:191], v[228:231], 0
	v_mfma_f32_16x16x32_bf16 v[4:7], v[196:199], v[228:231], 0
	v_mfma_f32_16x16x32_bf16 v[56:59], v[192:195], v[208:211], v[56:59]
	v_mfma_f32_16x16x32_bf16 v[52:55], v[200:203], v[208:211], v[52:55]
	v_mfma_f32_16x16x32_bf16 v[40:43], v[192:195], v[216:219], v[40:43]
	v_mfma_f32_16x16x32_bf16 v[36:39], v[200:203], v[216:219], v[36:39]
	v_mfma_f32_16x16x32_bf16 v[24:27], v[192:195], v[224:227], v[24:27]
	v_mfma_f32_16x16x32_bf16 v[20:23], v[200:203], v[224:227], v[20:23]
	v_mfma_f32_16x16x32_bf16 v[8:11], v[192:195], v[232:235], v[8:11]
	v_mfma_f32_16x16x32_bf16 v[4:7], v[200:203], v[232:235], v[4:7]
	s_setprio 0
	s_barrier
; #define PG8_STAGE(bufoff, gbase, voff) do { _Pragma("unroll") for (int _i = 0; _i < 2; ++_i) \
;         __builtin_amdgcn_global_load_lds((const unsigned*)((const char*)(gbase) + (voff)[_i]), (PG8_LAS unsigned*)(lds + (bufoff) + ldsw + _i * 8192), 16, 0, 0); } while (0)
; #define PG8_LDA(dst, b, h) do { _Pragma("unroll") for (int m = 0; m < 4; ++m) _Pragma("unroll") for (int k = 0; k < 2; ++k) dst[m][k] = *(const PG8_LAS bf16x8*)(lds + PG8_SA(b, h) + aoff + m * 2048 + k * 1024); } while (0)
; #define PG8_LDB(dst, b, h) do { _Pragma("unroll") for (int n = 0; n < 2; ++n) _Pragma("unroll") for (int k = 0; k < 2; ++k) dst[n][k] = *(const PG8_LAS bf16x8*)(lds + PG8_SB(b, h) + boff + n * 2048 + k * 1024); } while (0)
; #define PG8_MMA(ai, bj, At, Bt) do { __builtin_amdgcn_s_setprio(1); _Pragma("unroll") for (int m = 0; m < 4; ++m) _Pragma("unroll") for (int n = 0; n < 2; ++n) _Pragma("unroll") for (int k = 0; k < 2; ++k) \
;         acc[ai][bj][m][n] = __builtin_amdgcn_mfma_f32_16x16x32_bf16(Bt[n][k], At[m][k], acc[ai][bj][m][n], 0, 0, 0); __builtin_amdgcn_s_setprio(0); } while (0)
; #define PG8_WAIT_V(n) asm volatile("s_waitcnt vmcnt(" #n ")" ::: "memory")
; #define PG8_WAIT_L(n) asm volatile("s_waitcnt lgkmcnt(" #n ")" ::: "memory")
; #define PG8_BAR __builtin_amdgcn_s_barrier()
; #define PG8_SCHED __builtin_amdgcn_sched_barrier(0)
; template <class Epi, class Sched, bool ALIGN_EPI = false, bool SP2 = false>
; __device__ __forceinline__ void gemm_phase(PG8_LAS unsigned char* lds, const Gemm g, const Sched& S, const Epi& E) {
;     ...
;             PG8_LDB(B0, 1, 0); PG8_LDB(B1, 1, 1); PG8_SCHED; PG8_LDA(At, 1, 0); PG8_STAGE(PG8_SA(0, 1), a2 + hstep, voffA);
;             PG8_WAIT_V(8); PG8_WAIT_L(0); PG8_BAR; PG8_MMA(0, 0, At, B0); PG8_MMA(0, 1, At, B1); PG8_BAR; PG8_SCHED;
;             PG8_LDA(At, 1, 1); PG8_STAGE(PG8_SB(1, 0), b3, voffB); PG8_STAGE(PG8_SB(1, 1), b3 + hstep, voffB); PG8_STAGE(PG8_SA(1, 0), a3, voffA);
;             PG8_WAIT_V(8); PG8_WAIT_L(0); PG8_BAR; PG8_MMA(1, 0, At, B0); PG8_MMA(1, 1, At, B1); PG8_BAR; PG8_SCHED;
	s_add_i32 s63, 0, 0x18000
	s_add_i32 s64, 0, 0x1c000
	v_add_u32_e32 v162, s63, v185
	v_add_u32_e32 v200, s64, v185
	ds_read_b128 v[132:135], v162
	ds_read_b128 v[136:139], v162 offset:1024
	ds_read_b128 v[158:161], v162 offset:2048
	ds_read_b128 v[162:165], v162 offset:3072
	ds_read_b128 v[188:191], v200
	ds_read_b128 v[192:195], v200 offset:1024
	ds_read_b128 v[196:199], v200 offset:2048
	ds_read_b128 v[200:203], v200 offset:3072
	s_add_u32 s14, s20, 0x160000
	s_addc_u32 s15, s21, 0
	s_mov_b32 m0, s28
	ds_read_b128 v[204:207], v187 offset:32768
	ds_read_b128 v[208:211], v187 offset:33792
	ds_read_b128 v[212:215], v187 offset:34816
	ds_read_b128 v[216:219], v187 offset:35840
	ds_read_b128 v[220:223], v187 offset:36864
	ds_read_b128 v[224:227], v187 offset:37888
	ds_read_b128 v[228:231], v187 offset:38912
	ds_read_b128 v[232:235], v187 offset:39936
	global_load_lds_dwordx4 v0, s[14:15]
	s_mov_b32 m0, s29
	s_nop 0
	global_load_lds_dwordx4 v150, s[14:15]
	s_waitcnt vmcnt(8)
	s_waitcnt lgkmcnt(0)
	s_barrier
	s_setprio 1
	v_mfma_f32_16x16x32_bf16 v[128:131], v[132:135], v[204:207], v[128:131]
	v_mfma_f32_16x16x32_bf16 v[124:127], v[158:161], v[204:207], v[124:127]
	v_mfma_f32_16x16x32_bf16 v[112:115], v[132:135], v[212:215], v[112:115]
	v_mfma_f32_16x16x32_bf16 v[108:111], v[158:161], v[212:215], v[108:111]
	v_mfma_f32_16x16x32_bf16 v[96:99], v[132:135], v[220:223], v[96:99]
	v_mfma_f32_16x16x32_bf16 v[92:95], v[158:161], v[220:223], v[92:95]
	v_mfma_f32_16x16x32_bf16 v[80:83], v[132:135], v[228:231], v[80:83]
	v_mfma_f32_16x16x32_bf16 v[76:79], v[158:161], v[228:231], v[76:79]
	v_mfma_f32_16x16x32_bf16 v[128:131], v[136:139], v[208:211], v[128:131]
	v_mfma_f32_16x16x32_bf16 v[124:127], v[162:165], v[208:211], v[124:127]
	v_mfma_f32_16x16x32_bf16 v[112:115], v[136:139], v[216:219], v[112:115]
	v_mfma_f32_16x16x32_bf16 v[108:111], v[162:165], v[216:219], v[108:111]
	v_mfma_f32_16x16x32_bf16 v[96:99], v[136:139], v[224:227], v[96:99]
	v_mfma_f32_16x16x32_bf16 v[92:95], v[162:165], v[224:227], v[92:95]
	v_mfma_f32_16x16x32_bf16 v[80:83], v[136:139], v[232:235], v[80:83]
	v_mfma_f32_16x16x32_bf16 v[76:79], v[162:165], v[232:235], v[76:79]
	v_mfma_f32_16x16x32_bf16 v[120:123], v[188:191], v[204:207], v[120:123]
	v_mfma_f32_16x16x32_bf16 v[116:119], v[196:199], v[204:207], v[116:119]
	v_mfma_f32_16x16x32_bf16 v[104:107], v[188:191], v[212:215], v[104:107]
	v_mfma_f32_16x16x32_bf16 v[100:103], v[196:199], v[212:215], v[100:103]
	v_mfma_f32_16x16x32_bf16 v[88:91], v[188:191], v[220:223], v[88:91]
	v_mfma_f32_16x16x32_bf16 v[84:87], v[196:199], v[220:223], v[84:87]
	v_mfma_f32_16x16x32_bf16 v[72:75], v[188:191], v[228:231], v[72:75]
	v_mfma_f32_16x16x32_bf16 v[68:71], v[196:199], v[228:231], v[68:71]
	v_mfma_f32_16x16x32_bf16 v[120:123], v[192:195], v[208:211], v[120:123]
	v_mfma_f32_16x16x32_bf16 v[116:119], v[200:203], v[208:211], v[116:119]
	v_mfma_f32_16x16x32_bf16 v[104:107], v[192:195], v[216:219], v[104:107]
	v_mfma_f32_16x16x32_bf16 v[100:103], v[200:203], v[216:219], v[100:103]
	v_mfma_f32_16x16x32_bf16 v[88:91], v[192:195], v[224:227], v[88:91]
	v_mfma_f32_16x16x32_bf16 v[84:87], v[200:203], v[224:227], v[84:87]
	v_mfma_f32_16x16x32_bf16 v[72:75], v[192:195], v[232:235], v[72:75]
	v_mfma_f32_16x16x32_bf16 v[68:71], v[200:203], v[232:235], v[68:71]
	s_setprio 0
	s_barrier
	s_add_i32 s14, s63, s25
	s_mov_b32 m0, s14
	ds_read_b128 v[204:207], v187 offset:49152
	ds_read_b128 v[208:211], v187 offset:50176
	ds_read_b128 v[212:215], v187 offset:51200
	ds_read_b128 v[216:219], v187 offset:52224
	ds_read_b128 v[220:223], v187 offset:53248
	ds_read_b128 v[224:227], v187 offset:54272
	ds_read_b128 v[228:231], v187 offset:55296
	ds_read_b128 v[232:235], v187 offset:56320
	s_add_u32 vcc_lo, s18, 0x80
	s_addc_u32 vcc_hi, s19, 0
	global_load_lds_dwordx4 v2, vcc
	s_add_i32 m0, s14, 0x2000
	s_add_u32 s14, s18, 0x160080
	v_lshl_add_u64 v[166:167], v[236:237], 0, s[36:37]
	s_addc_u32 s15, s19, 0
	s_add_i32 s18, s64, s25
	global_load_lds_dwordx4 v[166:167], off
	s_mov_b32 m0, s18
	s_nop 0
	global_load_lds_dwordx4 v2, s[14:15]
	v_lshl_add_u64 v[166:167], s[14:15], 0, v[152:153]
	s_add_i32 m0, s18, 0x2000
	s_nop 0
	global_load_lds_dwordx4 v[166:167], off
	s_mov_b32 m0, s30
	s_nop 0
	s_add_u32 vcc_lo, s20, 0x80
	s_addc_u32 vcc_hi, s21, 0
	global_load_lds_dwordx4 v0, vcc
	s_mov_b32 m0, s31
	s_nop 0
	s_add_u32 vcc_lo, s20, 0x80
	s_addc_u32 vcc_hi, s21, 0
	global_load_lds_dwordx4 v150, vcc
	s_waitcnt vmcnt(8)
	s_waitcnt lgkmcnt(0)
	s_barrier
	s_setprio 1
	v_mfma_f32_16x16x32_bf16 v[64:67], v[132:135], v[204:207], v[64:67]
	v_mfma_f32_16x16x32_bf16 v[60:63], v[158:161], v[204:207], v[60:63]
	v_mfma_f32_16x16x32_bf16 v[48:51], v[132:135], v[212:215], v[48:51]
	v_mfma_f32_16x16x32_bf16 v[44:47], v[158:161], v[212:215], v[44:47]
	v_mfma_f32_16x16x32_bf16 v[32:35], v[132:135], v[220:223], v[32:35]
	v_mfma_f32_16x16x32_bf16 v[28:31], v[158:161], v[220:223], v[28:31]
	v_mfma_f32_16x16x32_bf16 v[16:19], v[132:135], v[228:231], v[16:19]
	v_mfma_f32_16x16x32_bf16 v[12:15], v[158:161], v[228:231], v[12:15]
	v_mfma_f32_16x16x32_bf16 v[64:67], v[136:139], v[208:211], v[64:67]
	v_mfma_f32_16x16x32_bf16 v[60:63], v[162:165], v[208:211], v[60:63]
	v_mfma_f32_16x16x32_bf16 v[48:51], v[136:139], v[216:219], v[48:51]
	v_mfma_f32_16x16x32_bf16 v[44:47], v[162:165], v[216:219], v[44:47]
	v_mfma_f32_16x16x32_bf16 v[32:35], v[136:139], v[224:227], v[32:35]
	v_mfma_f32_16x16x32_bf16 v[28:31], v[162:165], v[224:227], v[28:31]
	v_mfma_f32_16x16x32_bf16 v[16:19], v[136:139], v[232:235], v[16:19]
	v_mfma_f32_16x16x32_bf16 v[12:15], v[162:165], v[232:235], v[12:15]
	v_mfma_f32_16x16x32_bf16 v[56:59], v[188:191], v[204:207], v[56:59]
	v_mfma_f32_16x16x32_bf16 v[52:55], v[196:199], v[204:207], v[52:55]
	v_mfma_f32_16x16x32_bf16 v[40:43], v[188:191], v[212:215], v[40:43]
	v_mfma_f32_16x16x32_bf16 v[36:39], v[196:199], v[212:215], v[36:39]
	v_mfma_f32_16x16x32_bf16 v[24:27], v[188:191], v[220:223], v[24:27]
	v_mfma_f32_16x16x32_bf16 v[20:23], v[196:199], v[220:223], v[20:23]
	v_mfma_f32_16x16x32_bf16 v[8:11], v[188:191], v[228:231], v[8:11]
	v_mfma_f32_16x16x32_bf16 v[4:7], v[196:199], v[228:231], v[4:7]
	v_mfma_f32_16x16x32_bf16 v[56:59], v[192:195], v[208:211], v[56:59]
	v_mfma_f32_16x16x32_bf16 v[52:55], v[200:203], v[208:211], v[52:55]
	v_mfma_f32_16x16x32_bf16 v[40:43], v[192:195], v[216:219], v[40:43]
	v_mfma_f32_16x16x32_bf16 v[36:39], v[200:203], v[216:219], v[36:39]
	v_mfma_f32_16x16x32_bf16 v[24:27], v[192:195], v[224:227], v[24:27]
	v_mfma_f32_16x16x32_bf16 v[20:23], v[200:203], v[224:227], v[20:23]
	v_mfma_f32_16x16x32_bf16 v[8:11], v[192:195], v[232:235], v[8:11]
	v_mfma_f32_16x16x32_bf16 v[4:7], v[200:203], v[232:235], v[4:7]
	s_setprio 0
	s_barrier
	s_add_i32 s57, s57, 2
	s_add_u32 s51, s51, 0x100
	s_addc_u32 s56, s56, 0
	s_cmpk_gt_u32 s57, 0x55
	s_mov_b64 s[14:15], s[16:17]
; #define PG8_STAGE(bufoff, gbase, voff) do { _Pragma("unroll") for (int _i = 0; _i < 2; ++_i) \
;         __builtin_amdgcn_global_load_lds((const unsigned*)((const char*)(gbase) + (voff)[_i]), (PG8_LAS unsigned*)(lds + (bufoff) + ldsw + _i * 8192), 16, 0, 0); } while (0)
; #define PG8_LDA(dst, b, h) do { _Pragma("unroll") for (int m = 0; m < 4; ++m) _Pragma("unroll") for (int k = 0; k < 2; ++k) dst[m][k] = *(const PG8_LAS bf16x8*)(lds + PG8_SA(b, h) + aoff + m * 2048 + k * 1024); } while (0)
; #define PG8_LDB(dst, b, h) do { _Pragma("unroll") for (int n = 0; n < 2; ++n) _Pragma("unroll") for (int k = 0; k < 2; ++k) dst[n][k] = *(const PG8_LAS bf16x8*)(lds + PG8_SB(b, h) + boff + n * 2048 + k * 1024); } while (0)
; #define PG8_MMA(ai, bj, At, Bt) do { __builtin_amdgcn_s_setprio(1); _Pragma("unroll") for (int m = 0; m < 4; ++m) _Pragma("unroll") for (int n = 0; n < 2; ++n) _Pragma("unroll") for (int k = 0; k < 2; ++k) \
;         acc[ai][bj][m][n] = __builtin_amdgcn_mfma_f32_16x16x32_bf16(Bt[n][k], At[m][k], acc[ai][bj][m][n], 0, 0, 0); __builtin_amdgcn_s_setprio(0); } while (0)
; #define PG8_WAIT_V(n) asm volatile("s_waitcnt vmcnt(" #n ")" ::: "memory")
; #define PG8_BAR __builtin_amdgcn_s_barrier()
; template <class Epi, class Sched, bool ALIGN_EPI = false, bool SP2 = false>
; __device__ __forceinline__ void gemm_phase(PG8_LAS unsigned char* lds, const Gemm g, const Sched& S, const Epi& E) {
;     ...
;         for (int t = 0; t < nt; t += 2) {
;             const bool last = (t == nt - 2);
;             const char* a1 = cA + (size_t)(t + 1) * kstep;
;             const char* a2 = last ? nA : cA + (size_t)(t + 2) * kstep; const char* b2 = last ? nB : cB + (size_t)(t + 2) * kstep;
;             const char* a3 = a2 + kstep; const char* b3 = b2 + kstep;
;             if (last && has_next) S.a_ready(nxt);
;             if constexpr (SP2) {
;             PG8_LDB(B0, 0, 0); PG8_LDB(B1, 0, 1); PG8_SCHED; PG8_LDA(At, 0, 0); PG8_STAGE(PG8_SA(1, 1), a1 + hstep, voffA);
;             PG8_WAIT_V(8); PG8_WAIT_L(0); PG8_BAR; PG8_MMA(0, 0, At, B0); PG8_MMA(0, 1, At, B1); PG8_BAR; PG8_SCHED;
;             PG8_LDA(At, 0, 1); PG8_STAGE(PG8_SB(0, 0), b2, voffB); PG8_STAGE(PG8_SB(0, 1), b2 + hstep, voffB); PG8_STAGE(PG8_SA(0, 0), a2, voffA);
;             PG8_WAIT_V(8); PG8_WAIT_L(0); PG8_BAR; PG8_MMA(1, 0, At, B0); PG8_MMA(1, 1, At, B1); PG8_BAR; PG8_SCHED;
.LBB0_167:
	s_add_u32 s16, s14, 0x100
	s_addc_u32 s17, s15, 0
	s_add_i32 s63, 0, 0x10000
	s_cmpk_eq_i32 s57, 0x54
	s_cselect_b32 s21, s7, s17
	s_cselect_b32 s20, s6, s16
	s_cselect_b32 s19, s13, s56
	s_cselect_b32 s18, s12, s51
	s_add_i32 s64, 0, 0x14000
	v_add_u32_e32 v162, s63, v185
	v_add_u32_e32 v166, s64, v185
	ds_read_b128 v[132:135], v162
	ds_read_b128 v[136:139], v162 offset:1024
	ds_read_b128 v[158:161], v162 offset:2048
	ds_read_b128 v[162:165], v162 offset:3072
	ds_read_b128 v[188:191], v166
	ds_read_b128 v[192:195], v166 offset:1024
	ds_read_b128 v[196:199], v166 offset:2048
	ds_read_b128 v[200:203], v166 offset:3072
	s_add_i32 m0, s26, 0xc000
	ds_read_b128 v[204:207], v187
	ds_read_b128 v[208:211], v187 offset:1024
	ds_read_b128 v[212:215], v187 offset:2048
	ds_read_b128 v[216:219], v187 offset:3072
	ds_read_b128 v[220:223], v187 offset:4096
	ds_read_b128 v[224:227], v187 offset:5120
	ds_read_b128 v[228:231], v187 offset:6144
	ds_read_b128 v[232:235], v187 offset:7168
	global_load_lds_dwordx4 v154, s[14:15]
	s_add_i32 m0, s26, 0xe000
	s_nop 0
	global_load_lds_dwordx4 v156, s[14:15]
	s_waitcnt vmcnt(8)
	s_waitcnt lgkmcnt(0)
	s_barrier
	s_setprio 1
	v_mfma_f32_16x16x32_bf16 v[128:131], v[132:135], v[204:207], v[128:131]
	v_mfma_f32_16x16x32_bf16 v[124:127], v[158:161], v[204:207], v[124:127]
	v_mfma_f32_16x16x32_bf16 v[112:115], v[132:135], v[212:215], v[112:115]
	v_mfma_f32_16x16x32_bf16 v[108:111], v[158:161], v[212:215], v[108:111]
	v_mfma_f32_16x16x32_bf16 v[96:99], v[132:135], v[220:223], v[96:99]
	v_mfma_f32_16x16x32_bf16 v[92:95], v[158:161], v[220:223], v[92:95]
	v_mfma_f32_16x16x32_bf16 v[80:83], v[132:135], v[228:231], v[80:83]
	v_mfma_f32_16x16x32_bf16 v[76:79], v[158:161], v[228:231], v[76:79]
	v_mfma_f32_16x16x32_bf16 v[128:131], v[136:139], v[208:211], v[128:131]
	v_mfma_f32_16x16x32_bf16 v[124:127], v[162:165], v[208:211], v[124:127]
	v_mfma_f32_16x16x32_bf16 v[112:115], v[136:139], v[216:219], v[112:115]
	v_mfma_f32_16x16x32_bf16 v[108:111], v[162:165], v[216:219], v[108:111]
	v_mfma_f32_16x16x32_bf16 v[96:99], v[136:139], v[224:227], v[96:99]
	v_mfma_f32_16x16x32_bf16 v[92:95], v[162:165], v[224:227], v[92:95]
	v_mfma_f32_16x16x32_bf16 v[80:83], v[136:139], v[232:235], v[80:83]
	v_mfma_f32_16x16x32_bf16 v[76:79], v[162:165], v[232:235], v[76:79]
	v_mfma_f32_16x16x32_bf16 v[120:123], v[188:191], v[204:207], v[120:123]
	v_mfma_f32_16x16x32_bf16 v[116:119], v[196:199], v[204:207], v[116:119]
	v_mfma_f32_16x16x32_bf16 v[104:107], v[188:191], v[212:215], v[104:107]
	v_mfma_f32_16x16x32_bf16 v[100:103], v[196:199], v[212:215], v[100:103]
	v_mfma_f32_16x16x32_bf16 v[88:91], v[188:191], v[220:223], v[88:91]
	v_mfma_f32_16x16x32_bf16 v[84:87], v[196:199], v[220:223], v[84:87]
	v_mfma_f32_16x16x32_bf16 v[72:75], v[188:191], v[228:231], v[72:75]
	v_mfma_f32_16x16x32_bf16 v[68:71], v[196:199], v[228:231], v[68:71]
	v_mfma_f32_16x16x32_bf16 v[120:123], v[192:195], v[208:211], v[120:123]
	v_mfma_f32_16x16x32_bf16 v[116:119], v[200:203], v[208:211], v[116:119]
	v_mfma_f32_16x16x32_bf16 v[104:107], v[192:195], v[216:219], v[104:107]
	v_mfma_f32_16x16x32_bf16 v[100:103], v[200:203], v[216:219], v[100:103]
	v_mfma_f32_16x16x32_bf16 v[88:91], v[192:195], v[224:227], v[88:91]
	v_mfma_f32_16x16x32_bf16 v[84:87], v[200:203], v[224:227], v[84:87]
	v_mfma_f32_16x16x32_bf16 v[72:75], v[192:195], v[232:235], v[72:75]
	v_mfma_f32_16x16x32_bf16 v[68:71], v[200:203], v[232:235], v[68:71]
	s_setprio 0
	s_barrier
	s_add_i32 s14, s63, s25
	s_mov_b32 m0, s14
	ds_read_b128 v[204:207], v187 offset:16384
	ds_read_b128 v[208:211], v187 offset:17408
	ds_read_b128 v[212:215], v187 offset:18432
	ds_read_b128 v[216:219], v187 offset:19456
	ds_read_b128 v[220:223], v187 offset:20480
	ds_read_b128 v[224:227], v187 offset:21504
	ds_read_b128 v[228:231], v187 offset:22528
	ds_read_b128 v[232:235], v187 offset:23552
	global_load_lds_dwordx4 v2, s[18:19]
	s_add_i32 m0, s14, 0x2000
	s_add_u32 s14, s18, 0x160000
	v_lshl_add_u64 v[236:237], s[18:19], 0, v[152:153]
	s_addc_u32 s15, s19, 0
	s_add_i32 s63, s64, s25
	global_load_lds_dwordx4 v[236:237], off
	s_mov_b32 m0, s63
	global_load_lds_dwordx4 v2, s[14:15]
	s_add_i32 m0, s63, 0x2000
	s_nop 0
	global_load_lds_dwordx4 v152, s[14:15]
	s_mov_b32 m0, s26
	s_nop 0
	global_load_lds_dwordx4 v0, s[20:21]
	s_mov_b32 m0, s27
	s_nop 0
	global_load_lds_dwordx4 v150, s[20:21]
	s_waitcnt vmcnt(8)
	s_waitcnt lgkmcnt(0)
	s_barrier
	s_setprio 1
	v_mfma_f32_16x16x32_bf16 v[64:67], v[132:135], v[204:207], v[64:67]
	v_mfma_f32_16x16x32_bf16 v[60:63], v[158:161], v[204:207], v[60:63]
	v_mfma_f32_16x16x32_bf16 v[48:51], v[132:135], v[212:215], v[48:51]
	v_mfma_f32_16x16x32_bf16 v[44:47], v[158:161], v[212:215], v[44:47]
	v_mfma_f32_16x16x32_bf16 v[32:35], v[132:135], v[220:223], v[32:35]
	v_mfma_f32_16x16x32_bf16 v[28:31], v[158:161], v[220:223], v[28:31]
	v_mfma_f32_16x16x32_bf16 v[16:19], v[132:135], v[228:231], v[16:19]
	v_mfma_f32_16x16x32_bf16 v[12:15], v[158:161], v[228:231], v[12:15]
	v_mfma_f32_16x16x32_bf16 v[64:67], v[136:139], v[208:211], v[64:67]
	v_mfma_f32_16x16x32_bf16 v[60:63], v[162:165], v[208:211], v[60:63]
	v_mfma_f32_16x16x32_bf16 v[48:51], v[136:139], v[216:219], v[48:51]
	v_mfma_f32_16x16x32_bf16 v[44:47], v[162:165], v[216:219], v[44:47]
	v_mfma_f32_16x16x32_bf16 v[32:35], v[136:139], v[224:227], v[32:35]
	v_mfma_f32_16x16x32_bf16 v[28:31], v[162:165], v[224:227], v[28:31]
	v_mfma_f32_16x16x32_bf16 v[16:19], v[136:139], v[232:235], v[16:19]
	v_mfma_f32_16x16x32_bf16 v[12:15], v[162:165], v[232:235], v[12:15]
	v_mfma_f32_16x16x32_bf16 v[56:59], v[188:191], v[204:207], v[56:59]
	v_mfma_f32_16x16x32_bf16 v[52:55], v[196:199], v[204:207], v[52:55]
	v_mfma_f32_16x16x32_bf16 v[40:43], v[188:191], v[212:215], v[40:43]
	v_mfma_f32_16x16x32_bf16 v[36:39], v[196:199], v[212:215], v[36:39]
	v_mfma_f32_16x16x32_bf16 v[24:27], v[188:191], v[220:223], v[24:27]
	v_mfma_f32_16x16x32_bf16 v[20:23], v[196:199], v[220:223], v[20:23]
	v_mfma_f32_16x16x32_bf16 v[8:11], v[188:191], v[228:231], v[8:11]
	v_mfma_f32_16x16x32_bf16 v[4:7], v[196:199], v[228:231], v[4:7]
	v_mfma_f32_16x16x32_bf16 v[56:59], v[192:195], v[208:211], v[56:59]
	v_mfma_f32_16x16x32_bf16 v[52:55], v[200:203], v[208:211], v[52:55]
	v_mfma_f32_16x16x32_bf16 v[40:43], v[192:195], v[216:219], v[40:43]
	v_mfma_f32_16x16x32_bf16 v[36:39], v[200:203], v[216:219], v[36:39]
	v_mfma_f32_16x16x32_bf16 v[24:27], v[192:195], v[224:227], v[24:27]
	v_mfma_f32_16x16x32_bf16 v[20:23], v[200:203], v[224:227], v[20:23]
	v_mfma_f32_16x16x32_bf16 v[8:11], v[192:195], v[232:235], v[8:11]
	v_mfma_f32_16x16x32_bf16 v[4:7], v[200:203], v[232:235], v[4:7]
	s_setprio 0
	s_barrier
; #define PG8_STAGE(bufoff, gbase, voff) do { _Pragma("unroll") for (int _i = 0; _i < 2; ++_i) \
;         __builtin_amdgcn_global_load_lds((const unsigned*)((const char*)(gbase) + (voff)[_i]), (PG8_LAS unsigned*)(lds + (bufoff) + ldsw + _i * 8192), 16, 0, 0); } while (0)
; #define PG8_LDA(dst, b, h) do { _Pragma("unroll") for (int m = 0; m < 4; ++m) _Pragma("unroll") for (int k = 0; k < 2; ++k) dst[m][k] = *(const PG8_LAS bf16x8*)(lds + PG8_SA(b, h) + aoff + m * 2048 + k * 1024); } while (0)
; #define PG8_LDB(dst, b, h) do { _Pragma("unroll") for (int n = 0; n < 2; ++n) _Pragma("unroll") for (int k = 0; k < 2; ++k) dst[n][k] = *(const PG8_LAS bf16x8*)(lds + PG8_SB(b, h) + boff + n * 2048 + k * 1024); } while (0)
; #define PG8_MMA(ai, bj, At, Bt) do { __builtin_amdgcn_s_setprio(1); _Pragma("unroll") for (int m = 0; m < 4; ++m) _Pragma("unroll") for (int n = 0; n < 2; ++n) _Pragma("unroll") for (int k = 0; k < 2; ++k) \
;         acc[ai][bj][m][n] = __builtin_amdgcn_mfma_f32_16x16x32_bf16(Bt[n][k], At[m][k], acc[ai][bj][m][n], 0, 0, 0); __builtin_amdgcn_s_setprio(0); } while (0)
; #define PG8_WAIT_V(n) asm volatile("s_waitcnt vmcnt(" #n ")" ::: "memory")
; #define PG8_WAIT_L(n) asm volatile("s_waitcnt lgkmcnt(" #n ")" ::: "memory")
; #define PG8_BAR __builtin_amdgcn_s_barrier()
; #define PG8_SCHED __builtin_amdgcn_sched_barrier(0)
; template <class Epi, class Sched, bool ALIGN_EPI = false, bool SP2 = false>
; __device__ __forceinline__ void gemm_phase(PG8_LAS unsigned char* lds, const Gemm g, const Sched& S, const Epi& E) {
;     ...
;             PG8_LDB(B0, 1, 0); PG8_LDB(B1, 1, 1); PG8_SCHED; PG8_LDA(At, 1, 0); PG8_STAGE(PG8_SA(0, 1), a2 + hstep, voffA);
;             PG8_WAIT_V(8); PG8_WAIT_L(0); PG8_BAR; PG8_MMA(0, 0, At, B0); PG8_MMA(0, 1, At, B1); PG8_BAR; PG8_SCHED;
;             PG8_LDA(At, 1, 1); PG8_STAGE(PG8_SB(1, 0), b3, voffB); PG8_STAGE(PG8_SB(1, 1), b3 + hstep, voffB); PG8_STAGE(PG8_SA(1, 0), a3, voffA);
;             PG8_WAIT_V(8); PG8_WAIT_L(0); PG8_BAR; PG8_MMA(1, 0, At, B0); PG8_MMA(1, 1, At, B1); PG8_BAR; PG8_SCHED;
;     ...
;         if constexpr (ALIGN_EPI) { if (wr == 0) PG8_BAR; }
	s_add_i32 s63, 0, 0x18000
	s_add_i32 s64, 0, 0x1c000
	v_add_u32_e32 v162, s63, v185
	v_add_u32_e32 v200, s64, v185
	ds_read_b128 v[132:135], v162
	ds_read_b128 v[136:139], v162 offset:1024
	ds_read_b128 v[158:161], v162 offset:2048
	ds_read_b128 v[162:165], v162 offset:3072
	ds_read_b128 v[188:191], v200
	ds_read_b128 v[192:195], v200 offset:1024
	ds_read_b128 v[196:199], v200 offset:2048
	ds_read_b128 v[200:203], v200 offset:3072
	s_add_u32 s14, s20, 0x160000
	s_addc_u32 s15, s21, 0
	s_mov_b32 m0, s28
	ds_read_b128 v[204:207], v187 offset:32768
	ds_read_b128 v[208:211], v187 offset:33792
	ds_read_b128 v[212:215], v187 offset:34816
	ds_read_b128 v[216:219], v187 offset:35840
	ds_read_b128 v[220:223], v187 offset:36864
	ds_read_b128 v[224:227], v187 offset:37888
	ds_read_b128 v[228:231], v187 offset:38912
	ds_read_b128 v[232:235], v187 offset:39936
	global_load_lds_dwordx4 v0, s[14:15]
	s_mov_b32 m0, s29
	s_nop 0
	global_load_lds_dwordx4 v150, s[14:15]
	s_waitcnt vmcnt(8)
	s_waitcnt lgkmcnt(0)
	s_barrier
	s_setprio 1
	v_mfma_f32_16x16x32_bf16 v[128:131], v[132:135], v[204:207], v[128:131]
	v_mfma_f32_16x16x32_bf16 v[124:127], v[158:161], v[204:207], v[124:127]
	v_mfma_f32_16x16x32_bf16 v[112:115], v[132:135], v[212:215], v[112:115]
	v_mfma_f32_16x16x32_bf16 v[108:111], v[158:161], v[212:215], v[108:111]
	v_mfma_f32_16x16x32_bf16 v[96:99], v[132:135], v[220:223], v[96:99]
	v_mfma_f32_16x16x32_bf16 v[92:95], v[158:161], v[220:223], v[92:95]
	v_mfma_f32_16x16x32_bf16 v[80:83], v[132:135], v[228:231], v[80:83]
	v_mfma_f32_16x16x32_bf16 v[76:79], v[158:161], v[228:231], v[76:79]
	v_mfma_f32_16x16x32_bf16 v[128:131], v[136:139], v[208:211], v[128:131]
	v_mfma_f32_16x16x32_bf16 v[124:127], v[162:165], v[208:211], v[124:127]
	v_mfma_f32_16x16x32_bf16 v[112:115], v[136:139], v[216:219], v[112:115]
	v_mfma_f32_16x16x32_bf16 v[108:111], v[162:165], v[216:219], v[108:111]
	v_mfma_f32_16x16x32_bf16 v[96:99], v[136:139], v[224:227], v[96:99]
	v_mfma_f32_16x16x32_bf16 v[92:95], v[162:165], v[224:227], v[92:95]
	v_mfma_f32_16x16x32_bf16 v[80:83], v[136:139], v[232:235], v[80:83]
	v_mfma_f32_16x16x32_bf16 v[76:79], v[162:165], v[232:235], v[76:79]
	v_mfma_f32_16x16x32_bf16 v[120:123], v[188:191], v[204:207], v[120:123]
	v_mfma_f32_16x16x32_bf16 v[116:119], v[196:199], v[204:207], v[116:119]
	v_mfma_f32_16x16x32_bf16 v[104:107], v[188:191], v[212:215], v[104:107]
	v_mfma_f32_16x16x32_bf16 v[100:103], v[196:199], v[212:215], v[100:103]
	v_mfma_f32_16x16x32_bf16 v[88:91], v[188:191], v[220:223], v[88:91]
	v_mfma_f32_16x16x32_bf16 v[84:87], v[196:199], v[220:223], v[84:87]
	v_mfma_f32_16x16x32_bf16 v[72:75], v[188:191], v[228:231], v[72:75]
	v_mfma_f32_16x16x32_bf16 v[68:71], v[196:199], v[228:231], v[68:71]
	v_mfma_f32_16x16x32_bf16 v[120:123], v[192:195], v[208:211], v[120:123]
	v_mfma_f32_16x16x32_bf16 v[116:119], v[200:203], v[208:211], v[116:119]
	v_mfma_f32_16x16x32_bf16 v[104:107], v[192:195], v[216:219], v[104:107]
	v_mfma_f32_16x16x32_bf16 v[100:103], v[200:203], v[216:219], v[100:103]
	v_mfma_f32_16x16x32_bf16 v[88:91], v[192:195], v[224:227], v[88:91]
	v_mfma_f32_16x16x32_bf16 v[84:87], v[200:203], v[224:227], v[84:87]
	v_mfma_f32_16x16x32_bf16 v[72:75], v[192:195], v[232:235], v[72:75]
	v_mfma_f32_16x16x32_bf16 v[68:71], v[200:203], v[232:235], v[68:71]
	s_setprio 0
	s_barrier
	s_add_i32 s14, s63, s25
	s_mov_b32 m0, s14
	ds_read_b128 v[204:207], v187 offset:49152
	ds_read_b128 v[208:211], v187 offset:50176
	ds_read_b128 v[212:215], v187 offset:51200
	ds_read_b128 v[216:219], v187 offset:52224
	ds_read_b128 v[220:223], v187 offset:53248
	ds_read_b128 v[224:227], v187 offset:54272
	ds_read_b128 v[228:231], v187 offset:55296
	ds_read_b128 v[232:235], v187 offset:56320
	s_add_u32 vcc_lo, s18, 0x80
	s_addc_u32 vcc_hi, s19, 0
	global_load_lds_dwordx4 v2, vcc
	s_add_i32 m0, s14, 0x2000
	s_add_u32 s14, s18, 0x160080
	v_lshl_add_u64 v[166:167], v[236:237], 0, s[36:37]
	s_addc_u32 s15, s19, 0
	s_add_i32 s18, s64, s25
	global_load_lds_dwordx4 v[166:167], off
	s_mov_b32 m0, s18
	s_nop 0
	global_load_lds_dwordx4 v2, s[14:15]
	v_lshl_add_u64 v[166:167], s[14:15], 0, v[152:153]
	s_add_i32 m0, s18, 0x2000
	s_nop 0
	global_load_lds_dwordx4 v[166:167], off
	s_mov_b32 m0, s30
	s_nop 0
	s_add_u32 vcc_lo, s20, 0x80
	s_addc_u32 vcc_hi, s21, 0
	global_load_lds_dwordx4 v0, vcc
	s_mov_b32 m0, s31
	s_nop 0
	s_add_u32 vcc_lo, s20, 0x80
	s_addc_u32 vcc_hi, s21, 0
	global_load_lds_dwordx4 v150, vcc
	s_waitcnt vmcnt(8)
	s_waitcnt lgkmcnt(0)
	s_barrier
	s_setprio 1
	v_mfma_f32_16x16x32_bf16 v[64:67], v[132:135], v[204:207], v[64:67]
	v_mfma_f32_16x16x32_bf16 v[60:63], v[158:161], v[204:207], v[60:63]
	v_mfma_f32_16x16x32_bf16 v[48:51], v[132:135], v[212:215], v[48:51]
	v_mfma_f32_16x16x32_bf16 v[44:47], v[158:161], v[212:215], v[44:47]
	v_mfma_f32_16x16x32_bf16 v[32:35], v[132:135], v[220:223], v[32:35]
	v_mfma_f32_16x16x32_bf16 v[28:31], v[158:161], v[220:223], v[28:31]
	v_mfma_f32_16x16x32_bf16 v[16:19], v[132:135], v[228:231], v[16:19]
	v_mfma_f32_16x16x32_bf16 v[12:15], v[158:161], v[228:231], v[12:15]
	v_mfma_f32_16x16x32_bf16 v[64:67], v[136:139], v[208:211], v[64:67]
	v_mfma_f32_16x16x32_bf16 v[60:63], v[162:165], v[208:211], v[60:63]
	v_mfma_f32_16x16x32_bf16 v[48:51], v[136:139], v[216:219], v[48:51]
	v_mfma_f32_16x16x32_bf16 v[44:47], v[162:165], v[216:219], v[44:47]
	v_mfma_f32_16x16x32_bf16 v[32:35], v[136:139], v[224:227], v[32:35]
	v_mfma_f32_16x16x32_bf16 v[28:31], v[162:165], v[224:227], v[28:31]
	v_mfma_f32_16x16x32_bf16 v[16:19], v[136:139], v[232:235], v[16:19]
	v_mfma_f32_16x16x32_bf16 v[12:15], v[162:165], v[232:235], v[12:15]
	v_mfma_f32_16x16x32_bf16 v[56:59], v[188:191], v[204:207], v[56:59]
	v_mfma_f32_16x16x32_bf16 v[52:55], v[196:199], v[204:207], v[52:55]
	v_mfma_f32_16x16x32_bf16 v[40:43], v[188:191], v[212:215], v[40:43]
	v_mfma_f32_16x16x32_bf16 v[36:39], v[196:199], v[212:215], v[36:39]
	v_mfma_f32_16x16x32_bf16 v[24:27], v[188:191], v[220:223], v[24:27]
	v_mfma_f32_16x16x32_bf16 v[20:23], v[196:199], v[220:223], v[20:23]
	v_mfma_f32_16x16x32_bf16 v[8:11], v[188:191], v[228:231], v[8:11]
	v_mfma_f32_16x16x32_bf16 v[4:7], v[196:199], v[228:231], v[4:7]
	v_mfma_f32_16x16x32_bf16 v[56:59], v[192:195], v[208:211], v[56:59]
	v_mfma_f32_16x16x32_bf16 v[52:55], v[200:203], v[208:211], v[52:55]
	v_mfma_f32_16x16x32_bf16 v[40:43], v[192:195], v[216:219], v[40:43]
	v_mfma_f32_16x16x32_bf16 v[36:39], v[200:203], v[216:219], v[36:39]
	v_mfma_f32_16x16x32_bf16 v[24:27], v[192:195], v[224:227], v[24:27]
	v_mfma_f32_16x16x32_bf16 v[20:23], v[200:203], v[224:227], v[20:23]
	v_mfma_f32_16x16x32_bf16 v[8:11], v[192:195], v[232:235], v[8:11]
	v_mfma_f32_16x16x32_bf16 v[4:7], v[200:203], v[232:235], v[4:7]
	s_setprio 0
	s_barrier
	s_add_i32 s57, s57, 2
	s_add_u32 s51, s51, 0x100
	s_addc_u32 s56, s56, 0
	s_cmpk_gt_u32 s57, 0x55
	s_mov_b64 s[14:15], s[16:17]
	s_cbranch_scc0 .LBB0_167
	s_and_b64 vcc, exec, s[10:11]
	s_cbranch_vccz .LBB0_170
	s_barrier

; #define PG8_STAGE(bufoff, gbase, voff) do { _Pragma("unroll") for (int _i = 0; _i < 2; ++_i) \
;         __builtin_amdgcn_global_load_lds((const unsigned*)((const char*)(gbase) + (voff)[_i]), (PG8_LAS unsigned*)(lds + (bufoff) + ldsw + _i * 8192), 16, 0, 0); } while (0)
; #define PG8_LDA(dst, b, h) do { _Pragma("unroll") for (int m = 0; m < 4; ++m) _Pragma("unroll") for (int k = 0; k < 2; ++k) dst[m][k] = *(const PG8_LAS bf16x8*)(lds + PG8_SA(b, h) + aoff + m * 2048 + k * 1024); } while (0)
; #define PG8_LDB(dst, b, h) do { _Pragma("unroll") for (int n = 0; n < 2; ++n) _Pragma("unroll") for (int k = 0; k < 2; ++k) dst[n][k] = *(const PG8_LAS bf16x8*)(lds + PG8_SB(b, h) + boff + n * 2048 + k * 1024); } while (0)
; #define PG8_WAIT_V(n) asm volatile("s_waitcnt vmcnt(" #n ")" ::: "memory")
; #define PG8_WAIT_L(n) asm volatile("s_waitcnt lgkmcnt(" #n ")" ::: "memory")
; #define PG8_BAR __builtin_amdgcn_s_barrier()
; #define PG8_SCHED __builtin_amdgcn_sched_barrier(0)
; template <class Epi, class Sched, bool ALIGN_EPI = false, bool SP2 = false>
; __device__ __forceinline__ void gemm_phase(PG8_LAS unsigned char* lds, const Gemm g, const Sched& S, const Epi& E) {
;     ...
;         const bool has_next = S.next(ui + 1, nxt);
;         const char* nA = has_next ? (const char*)g.A + (size_t)nxt.pm * tstep : cA; const char* nB = has_next ? (const char*)g.Bt + (size_t)nxt.pn * tstep : cB;
;         for (int t = 0; t < nt; t += 2) {
;             const bool last = (t == nt - 2);
;             const char* a1 = cA + (size_t)(t + 1) * kstep;
;             const char* a2 = last ? nA : cA + (size_t)(t + 2) * kstep; const char* b2 = last ? nB : cB + (size_t)(t + 2) * kstep;
;             const char* a3 = a2 + kstep; const char* b3 = b2 + kstep;
;             if (last && has_next) S.a_ready(nxt);
;             if constexpr (SP2) {
;             PG8_LDB(B0, 0, 0); PG8_LDB(B1, 0, 1); PG8_SCHED; PG8_LDA(At, 0, 0); PG8_STAGE(PG8_SA(1, 1), a1 + hstep, voffA);
;             PG8_WAIT_V(8); PG8_WAIT_L(0); PG8_BAR; PG8_MMA(0, 0, At, B0); PG8_MMA(0, 1, At, B1); PG8_BAR; PG8_SCHED;
;             PG8_LDA(At, 0, 1); PG8_STAGE(PG8_SB(0, 0), b2, voffB); PG8_STAGE(PG8_SB(0, 1), b2 + hstep, voffB); PG8_STAGE(PG8_SA(0, 0), a2, voffA);
;             PG8_WAIT_V(8); PG8_WAIT_L(0); PG8_BAR; PG8_MMA(1, 0, At, B0); PG8_MMA(1, 1, At, B1); PG8_BAR; PG8_SCHED;
.LBB0_250:
	s_ashr_i32 s11, s10, 31
	s_lshl_b64 s[12:13], s[10:11], 20
	s_add_u32 s12, s46, s12
	s_addc_u32 s13, s47, s13
	s_and_b64 s[14:15], s[2:3], exec
	s_cselect_b32 s11, s13, s19
	s_cselect_b32 s45, s12, s18
	s_ashr_i32 s7, s6, 31
	s_lshl_b64 s[14:15], s[6:7], 20
	s_add_u32 s14, s25, s14
	s_addc_u32 s15, s26, s15
	s_and_b64 s[22:23], s[2:3], exec
	s_cselect_b32 s7, s15, s21
	s_cselect_b32 s50, s14, s20
	s_add_u32 s18, s18, 0x80080
	s_addc_u32 s19, s19, 0
	s_add_u32 s51, s20, 0x100
	s_addc_u32 s56, s21, 0
	s_mov_b32 s57, -2
	s_add_u32 s20, s18, 0xfff80080
	s_addc_u32 s21, s19, -1
	s_add_i32 s63, 0, 0x10000
	s_cmp_eq_u32 s57, 28
	s_cselect_b32 s23, s11, s21
	s_cselect_b32 s22, s45, s20
	v_add_u32_e32 v151, s63, v156
	s_cselect_b32 s21, s7, s56
	s_cselect_b32 s20, s50, s51
	s_add_i32 s66, 0, 0x14000
	ds_read_b128 v[184:187], v151
	ds_read_b128 v[188:191], v151 offset:1024
	ds_read_b128 v[192:195], v151 offset:2048
	ds_read_b128 v[196:199], v151 offset:3072
	v_add_u32_e32 v151, s66, v156
	ds_read_b128 v[200:203], v151
	ds_read_b128 v[204:207], v151 offset:1024
	ds_read_b128 v[208:211], v151 offset:2048
	ds_read_b128 v[212:215], v151 offset:3072
	s_add_i32 m0, s17, 0xc000
	ds_read_b128 v[216:219], v160
	ds_read_b128 v[220:223], v160 offset:1024
	ds_read_b128 v[224:227], v160 offset:2048
	ds_read_b128 v[228:231], v160 offset:3072
	ds_read_b128 v[232:235], v160 offset:4096
	ds_read_b128 v[236:239], v160 offset:5120
	ds_read_b128 v[240:243], v160 offset:6144
	ds_read_b128 v[244:247], v160 offset:7168
	global_load_lds_dwordx4 v136, s[18:19]
	s_add_i32 m0, s17, 0xe000
	s_nop 0
	global_load_lds_dwordx4 v138, s[18:19]
	s_waitcnt vmcnt(8)
	s_waitcnt lgkmcnt(0)
	s_barrier
	s_setprio 1
	v_mfma_f32_16x16x32_bf16 v[128:131], v[184:187], v[216:219], 0
	v_mfma_f32_16x16x32_bf16 v[124:127], v[192:195], v[216:219], 0
	v_mfma_f32_16x16x32_bf16 v[112:115], v[184:187], v[224:227], 0
	v_mfma_f32_16x16x32_bf16 v[108:111], v[192:195], v[224:227], 0
	v_mfma_f32_16x16x32_bf16 v[96:99], v[184:187], v[232:235], 0
	v_mfma_f32_16x16x32_bf16 v[92:95], v[192:195], v[232:235], 0
	v_mfma_f32_16x16x32_bf16 v[80:83], v[184:187], v[240:243], 0
	v_mfma_f32_16x16x32_bf16 v[76:79], v[192:195], v[240:243], 0
	v_mfma_f32_16x16x32_bf16 v[128:131], v[188:191], v[220:223], v[128:131]
	v_mfma_f32_16x16x32_bf16 v[124:127], v[196:199], v[220:223], v[124:127]
	v_mfma_f32_16x16x32_bf16 v[112:115], v[188:191], v[228:231], v[112:115]
	v_mfma_f32_16x16x32_bf16 v[108:111], v[196:199], v[228:231], v[108:111]
	v_mfma_f32_16x16x32_bf16 v[96:99], v[188:191], v[236:239], v[96:99]
	v_mfma_f32_16x16x32_bf16 v[92:95], v[196:199], v[236:239], v[92:95]
	v_mfma_f32_16x16x32_bf16 v[80:83], v[188:191], v[244:247], v[80:83]
	v_mfma_f32_16x16x32_bf16 v[76:79], v[196:199], v[244:247], v[76:79]
	v_mfma_f32_16x16x32_bf16 v[120:123], v[200:203], v[216:219], 0
	v_mfma_f32_16x16x32_bf16 v[116:119], v[208:211], v[216:219], 0
	v_mfma_f32_16x16x32_bf16 v[104:107], v[200:203], v[224:227], 0
	v_mfma_f32_16x16x32_bf16 v[100:103], v[208:211], v[224:227], 0
	v_mfma_f32_16x16x32_bf16 v[88:91], v[200:203], v[232:235], 0
	v_mfma_f32_16x16x32_bf16 v[84:87], v[208:211], v[232:235], 0
	v_mfma_f32_16x16x32_bf16 v[72:75], v[200:203], v[240:243], 0
	v_mfma_f32_16x16x32_bf16 v[68:71], v[208:211], v[240:243], 0
	v_mfma_f32_16x16x32_bf16 v[120:123], v[204:207], v[220:223], v[120:123]
	v_mfma_f32_16x16x32_bf16 v[116:119], v[212:215], v[220:223], v[116:119]
	v_mfma_f32_16x16x32_bf16 v[104:107], v[204:207], v[228:231], v[104:107]
	v_mfma_f32_16x16x32_bf16 v[100:103], v[212:215], v[228:231], v[100:103]
	v_mfma_f32_16x16x32_bf16 v[88:91], v[204:207], v[236:239], v[88:91]
	v_mfma_f32_16x16x32_bf16 v[84:87], v[212:215], v[236:239], v[84:87]
	v_mfma_f32_16x16x32_bf16 v[72:75], v[204:207], v[244:247], v[72:75]
	v_mfma_f32_16x16x32_bf16 v[68:71], v[212:215], v[244:247], v[68:71]
	s_setprio 0
	s_barrier
	s_add_i32 s63, s63, s27
	s_mov_b32 m0, s63
	ds_read_b128 v[216:219], v160 offset:16384
	ds_read_b128 v[220:223], v160 offset:17408
	ds_read_b128 v[224:227], v160 offset:18432
	ds_read_b128 v[228:231], v160 offset:19456
	ds_read_b128 v[232:235], v160 offset:20480
	ds_read_b128 v[236:239], v160 offset:21504
	ds_read_b128 v[240:243], v160 offset:22528
	ds_read_b128 v[244:247], v160 offset:23552
	global_load_lds_dwordx4 v2, s[20:21]
	s_add_i32 m0, s63, 0x2000
	s_add_u32 s64, s20, 0x80000
	s_addc_u32 s65, s21, 0
	s_add_i32 s63, s66, s27
	global_load_lds_dwordx4 v0, s[20:21]
	s_mov_b32 m0, s63
	v_lshl_add_u64 v[250:251], s[22:23], 0, v[132:133]
	global_load_lds_dwordx4 v2, s[64:65]
	s_add_i32 m0, s63, 0x2000
	s_nop 0
	global_load_lds_dwordx4 v0, s[64:65]
	v_lshl_add_u64 v[248:249], s[22:23], 0, v[134:135]
	s_mov_b32 m0, s17
	s_nop 0
	global_load_lds_dwordx4 v[248:249], off
	s_mov_b32 m0, s29
	s_nop 0
	global_load_lds_dwordx4 v[250:251], off
	s_waitcnt vmcnt(8)
	s_waitcnt lgkmcnt(0)
	s_barrier
; #define PG8_STAGE(bufoff, gbase, voff) do { _Pragma("unroll") for (int _i = 0; _i < 2; ++_i) \
;         __builtin_amdgcn_global_load_lds((const unsigned*)((const char*)(gbase) + (voff)[_i]), (PG8_LAS unsigned*)(lds + (bufoff) + ldsw + _i * 8192), 16, 0, 0); } while (0)
; #define PG8_LDA(dst, b, h) do { _Pragma("unroll") for (int m = 0; m < 4; ++m) _Pragma("unroll") for (int k = 0; k < 2; ++k) dst[m][k] = *(const PG8_LAS bf16x8*)(lds + PG8_SA(b, h) + aoff + m * 2048 + k * 1024); } while (0)
; #define PG8_LDB(dst, b, h) do { _Pragma("unroll") for (int n = 0; n < 2; ++n) _Pragma("unroll") for (int k = 0; k < 2; ++k) dst[n][k] = *(const PG8_LAS bf16x8*)(lds + PG8_SB(b, h) + boff + n * 2048 + k * 1024); } while (0)
; #define PG8_MMA(ai, bj, At, Bt) do { __builtin_amdgcn_s_setprio(1); _Pragma("unroll") for (int m = 0; m < 4; ++m) _Pragma("unroll") for (int n = 0; n < 2; ++n) _Pragma("unroll") for (int k = 0; k < 2; ++k) \
;         acc[ai][bj][m][n] = __builtin_amdgcn_mfma_f32_16x16x32_bf16(Bt[n][k], At[m][k], acc[ai][bj][m][n], 0, 0, 0); __builtin_amdgcn_s_setprio(0); } while (0)
; #define PG8_WAIT_V(n) asm volatile("s_waitcnt vmcnt(" #n ")" ::: "memory")
; #define PG8_WAIT_L(n) asm volatile("s_waitcnt lgkmcnt(" #n ")" ::: "memory")
; #define PG8_BAR __builtin_amdgcn_s_barrier()
; #define PG8_SCHED __builtin_amdgcn_sched_barrier(0)
; template <class Epi, class Sched, bool ALIGN_EPI = false, bool SP2 = false>
; __device__ __forceinline__ void gemm_phase(PG8_LAS unsigned char* lds, const Gemm g, const Sched& S, const Epi& E) {
;     ...
;             PG8_WAIT_V(8); PG8_WAIT_L(0); PG8_BAR; PG8_MMA(1, 0, At, B0); PG8_MMA(1, 1, At, B1); PG8_BAR; PG8_SCHED;
;             PG8_LDB(B0, 1, 0); PG8_LDB(B1, 1, 1); PG8_SCHED; PG8_LDA(At, 1, 0); PG8_STAGE(PG8_SA(0, 1), a2 + hstep, voffA);
;             PG8_WAIT_V(8); PG8_WAIT_L(0); PG8_BAR; PG8_MMA(0, 0, At, B0); PG8_MMA(0, 1, At, B1); PG8_BAR; PG8_SCHED;
	s_setprio 1
	v_mfma_f32_16x16x32_bf16 v[64:67], v[184:187], v[216:219], 0
	v_mfma_f32_16x16x32_bf16 v[60:63], v[192:195], v[216:219], 0
	v_mfma_f32_16x16x32_bf16 v[48:51], v[184:187], v[224:227], 0
	v_mfma_f32_16x16x32_bf16 v[44:47], v[192:195], v[224:227], 0
	v_mfma_f32_16x16x32_bf16 v[32:35], v[184:187], v[232:235], 0
	v_mfma_f32_16x16x32_bf16 v[28:31], v[192:195], v[232:235], 0
	v_mfma_f32_16x16x32_bf16 v[16:19], v[184:187], v[240:243], 0
	v_mfma_f32_16x16x32_bf16 v[12:15], v[192:195], v[240:243], 0
	v_mfma_f32_16x16x32_bf16 v[64:67], v[188:191], v[220:223], v[64:67]
	v_mfma_f32_16x16x32_bf16 v[60:63], v[196:199], v[220:223], v[60:63]
	v_mfma_f32_16x16x32_bf16 v[48:51], v[188:191], v[228:231], v[48:51]
	v_mfma_f32_16x16x32_bf16 v[44:47], v[196:199], v[228:231], v[44:47]
	v_mfma_f32_16x16x32_bf16 v[32:35], v[188:191], v[236:239], v[32:35]
	v_mfma_f32_16x16x32_bf16 v[28:31], v[196:199], v[236:239], v[28:31]
	v_mfma_f32_16x16x32_bf16 v[16:19], v[188:191], v[244:247], v[16:19]
	v_mfma_f32_16x16x32_bf16 v[12:15], v[196:199], v[244:247], v[12:15]
	v_mfma_f32_16x16x32_bf16 v[56:59], v[200:203], v[216:219], 0
	v_mfma_f32_16x16x32_bf16 v[52:55], v[208:211], v[216:219], 0
	v_mfma_f32_16x16x32_bf16 v[40:43], v[200:203], v[224:227], 0
	v_mfma_f32_16x16x32_bf16 v[36:39], v[208:211], v[224:227], 0
	v_mfma_f32_16x16x32_bf16 v[24:27], v[200:203], v[232:235], 0
	v_mfma_f32_16x16x32_bf16 v[20:23], v[208:211], v[232:235], 0
	v_mfma_f32_16x16x32_bf16 v[8:11], v[200:203], v[240:243], 0
	v_mfma_f32_16x16x32_bf16 v[4:7], v[208:211], v[240:243], 0
	v_mfma_f32_16x16x32_bf16 v[56:59], v[204:207], v[220:223], v[56:59]
	v_mfma_f32_16x16x32_bf16 v[52:55], v[212:215], v[220:223], v[52:55]
	v_mfma_f32_16x16x32_bf16 v[40:43], v[204:207], v[228:231], v[40:43]
	v_mfma_f32_16x16x32_bf16 v[36:39], v[212:215], v[228:231], v[36:39]
	v_mfma_f32_16x16x32_bf16 v[24:27], v[204:207], v[236:239], v[24:27]
	v_mfma_f32_16x16x32_bf16 v[20:23], v[212:215], v[236:239], v[20:23]
	v_mfma_f32_16x16x32_bf16 v[8:11], v[204:207], v[244:247], v[8:11]
	v_mfma_f32_16x16x32_bf16 v[4:7], v[212:215], v[244:247], v[4:7]
	s_setprio 0
	s_barrier
	s_add_i32 s63, 0, 0x18000
	v_add_u32_e32 v151, s63, v156
	s_add_i32 s64, 0, 0x1c000
	ds_read_b128 v[184:187], v151
	ds_read_b128 v[188:191], v151 offset:1024
	ds_read_b128 v[192:195], v151 offset:2048
	ds_read_b128 v[196:199], v151 offset:3072
	v_add_u32_e32 v151, s64, v156
	ds_read_b128 v[200:203], v151
	ds_read_b128 v[204:207], v151 offset:1024
	ds_read_b128 v[208:211], v151 offset:2048
	ds_read_b128 v[212:215], v151 offset:3072
	s_add_u32 s22, s22, 0x80000
	s_addc_u32 s23, s23, 0
	s_mov_b32 m0, s30
	ds_read_b128 v[216:219], v160 offset:32768
	ds_read_b128 v[220:223], v160 offset:33792
	ds_read_b128 v[224:227], v160 offset:34816
	ds_read_b128 v[228:231], v160 offset:35840
	ds_read_b128 v[232:235], v160 offset:36864
	ds_read_b128 v[236:239], v160 offset:37888
	ds_read_b128 v[240:243], v160 offset:38912
	ds_read_b128 v[244:247], v160 offset:39936
	global_load_lds_dwordx4 v134, s[22:23]
	s_mov_b32 m0, s31
	s_nop 0
	global_load_lds_dwordx4 v132, s[22:23]
	s_waitcnt vmcnt(8)
	s_waitcnt lgkmcnt(0)
	s_barrier
	s_setprio 1
	v_mfma_f32_16x16x32_bf16 v[128:131], v[184:187], v[216:219], v[128:131]
	v_mfma_f32_16x16x32_bf16 v[124:127], v[192:195], v[216:219], v[124:127]
	v_mfma_f32_16x16x32_bf16 v[112:115], v[184:187], v[224:227], v[112:115]
	v_mfma_f32_16x16x32_bf16 v[108:111], v[192:195], v[224:227], v[108:111]
	v_mfma_f32_16x16x32_bf16 v[96:99], v[184:187], v[232:235], v[96:99]
	v_mfma_f32_16x16x32_bf16 v[92:95], v[192:195], v[232:235], v[92:95]
	v_mfma_f32_16x16x32_bf16 v[80:83], v[184:187], v[240:243], v[80:83]
	v_mfma_f32_16x16x32_bf16 v[76:79], v[192:195], v[240:243], v[76:79]
	v_mfma_f32_16x16x32_bf16 v[128:131], v[188:191], v[220:223], v[128:131]
	v_mfma_f32_16x16x32_bf16 v[124:127], v[196:199], v[220:223], v[124:127]
	v_mfma_f32_16x16x32_bf16 v[112:115], v[188:191], v[228:231], v[112:115]
	v_mfma_f32_16x16x32_bf16 v[108:111], v[196:199], v[228:231], v[108:111]
	v_mfma_f32_16x16x32_bf16 v[96:99], v[188:191], v[236:239], v[96:99]
	v_mfma_f32_16x16x32_bf16 v[92:95], v[196:199], v[236:239], v[92:95]
	v_mfma_f32_16x16x32_bf16 v[80:83], v[188:191], v[244:247], v[80:83]
	v_mfma_f32_16x16x32_bf16 v[76:79], v[196:199], v[244:247], v[76:79]
	v_mfma_f32_16x16x32_bf16 v[120:123], v[200:203], v[216:219], v[120:123]
	v_mfma_f32_16x16x32_bf16 v[116:119], v[208:211], v[216:219], v[116:119]
	v_mfma_f32_16x16x32_bf16 v[104:107], v[200:203], v[224:227], v[104:107]
	v_mfma_f32_16x16x32_bf16 v[100:103], v[208:211], v[224:227], v[100:103]
	v_mfma_f32_16x16x32_bf16 v[88:91], v[200:203], v[232:235], v[88:91]
	v_mfma_f32_16x16x32_bf16 v[84:87], v[208:211], v[232:235], v[84:87]
	v_mfma_f32_16x16x32_bf16 v[72:75], v[200:203], v[240:243], v[72:75]
	v_mfma_f32_16x16x32_bf16 v[68:71], v[208:211], v[240:243], v[68:71]
	v_mfma_f32_16x16x32_bf16 v[120:123], v[204:207], v[220:223], v[120:123]
	v_mfma_f32_16x16x32_bf16 v[116:119], v[212:215], v[220:223], v[116:119]
	v_mfma_f32_16x16x32_bf16 v[104:107], v[204:207], v[228:231], v[104:107]
	v_mfma_f32_16x16x32_bf16 v[100:103], v[212:215], v[228:231], v[100:103]
	v_mfma_f32_16x16x32_bf16 v[88:91], v[204:207], v[236:239], v[88:91]
	v_mfma_f32_16x16x32_bf16 v[84:87], v[212:215], v[236:239], v[84:87]
	v_mfma_f32_16x16x32_bf16 v[72:75], v[204:207], v[244:247], v[72:75]
	v_mfma_f32_16x16x32_bf16 v[68:71], v[212:215], v[244:247], v[68:71]
	s_setprio 0
	s_barrier
; #define PG8_STAGE(bufoff, gbase, voff) do { _Pragma("unroll") for (int _i = 0; _i < 2; ++_i) \
;         __builtin_amdgcn_global_load_lds((const unsigned*)((const char*)(gbase) + (voff)[_i]), (PG8_LAS unsigned*)(lds + (bufoff) + ldsw + _i * 8192), 16, 0, 0); } while (0)
; #define PG8_LDA(dst, b, h) do { _Pragma("unroll") for (int m = 0; m < 4; ++m) _Pragma("unroll") for (int k = 0; k < 2; ++k) dst[m][k] = *(const PG8_LAS bf16x8*)(lds + PG8_SA(b, h) + aoff + m * 2048 + k * 1024); } while (0)
; #define PG8_LDB(dst, b, h) do { _Pragma("unroll") for (int n = 0; n < 2; ++n) _Pragma("unroll") for (int k = 0; k < 2; ++k) dst[n][k] = *(const PG8_LAS bf16x8*)(lds + PG8_SB(b, h) + boff + n * 2048 + k * 1024); } while (0)
; #define PG8_MMA(ai, bj, At, Bt) do { __builtin_amdgcn_s_setprio(1); _Pragma("unroll") for (int m = 0; m < 4; ++m) _Pragma("unroll") for (int n = 0; n < 2; ++n) _Pragma("unroll") for (int k = 0; k < 2; ++k) \
;         acc[ai][bj][m][n] = __builtin_amdgcn_mfma_f32_16x16x32_bf16(Bt[n][k], At[m][k], acc[ai][bj][m][n], 0, 0, 0); __builtin_amdgcn_s_setprio(0); } while (0)
; #define PG8_WAIT_V(n) asm volatile("s_waitcnt vmcnt(" #n ")" ::: "memory")
; template <class Epi, class Sched, bool ALIGN_EPI = false, bool SP2 = false>
; __device__ __forceinline__ void gemm_phase(PG8_LAS unsigned char* lds, const Gemm g, const Sched& S, const Epi& E) {
;     ...
;             PG8_LDB(B0, 0, 0); PG8_LDB(B1, 0, 1); PG8_SCHED; PG8_LDA(At, 0, 0); PG8_STAGE(PG8_SA(1, 1), a1 + hstep, voffA);
;             PG8_WAIT_V(8); PG8_WAIT_L(0); PG8_BAR; PG8_MMA(0, 0, At, B0); PG8_MMA(0, 1, At, B1); PG8_BAR; PG8_SCHED;
;             PG8_LDA(At, 0, 1); PG8_STAGE(PG8_SB(0, 0), b2, voffB); PG8_STAGE(PG8_SB(0, 1), b2 + hstep, voffB); PG8_STAGE(PG8_SA(0, 0), a2, voffA);
;             PG8_WAIT_V(8); PG8_WAIT_L(0); PG8_BAR; PG8_MMA(1, 0, At, B0); PG8_MMA(1, 1, At, B1); PG8_BAR; PG8_SCHED;
;             PG8_LDB(B0, 1, 0); PG8_LDB(B1, 1, 1); PG8_SCHED; PG8_LDA(At, 1, 0); PG8_STAGE(PG8_SA(0, 1), a2 + hstep, voffA);
;             PG8_WAIT_V(8); PG8_WAIT_L(0); PG8_BAR; PG8_MMA(0, 0, At, B0); PG8_MMA(0, 1, At, B1); PG8_BAR; PG8_SCHED;
;             PG8_LDA(At, 1, 1); PG8_STAGE(PG8_SB(1, 0), b3, voffB); PG8_STAGE(PG8_SB(1, 1), b3 + hstep, voffB); PG8_STAGE(PG8_SA(1, 0), a3, voffA);
;             PG8_WAIT_V(8); PG8_WAIT_L(0); PG8_BAR; PG8_MMA(1, 0, At, B0); PG8_MMA(1, 1, At, B1); PG8_BAR; PG8_SCHED;
	s_add_i32 s22, s63, s27
	s_mov_b32 m0, s22
	ds_read_b128 v[216:219], v160 offset:49152
	ds_read_b128 v[220:223], v160 offset:50176
	ds_read_b128 v[224:227], v160 offset:51200
	ds_read_b128 v[228:231], v160 offset:52224
	ds_read_b128 v[232:235], v160 offset:53248
	ds_read_b128 v[236:239], v160 offset:54272
	ds_read_b128 v[240:243], v160 offset:55296
	ds_read_b128 v[244:247], v160 offset:56320
	s_add_u32 vcc_lo, s20, 0x80
	s_addc_u32 vcc_hi, s21, 0
	global_load_lds_dwordx4 v2, vcc
	s_add_i32 m0, s22, 0x2000
	s_add_u32 s20, s20, 0x80080
	s_addc_u32 s21, s21, 0
	s_add_i32 s22, s64, s27
	s_add_u32 vcc_lo, s20, 0xfff80000
	s_addc_u32 vcc_hi, s21, -1
	global_load_lds_dwordx4 v0, vcc
	s_mov_b32 m0, s22
	s_nop 0
	global_load_lds_dwordx4 v2, s[20:21]
	s_add_i32 m0, s22, 0x2000
	s_nop 0
	global_load_lds_dwordx4 v0, s[20:21]
	v_lshl_add_u64 v[152:153], v[248:249], 0, s[36:37]
	s_mov_b32 m0, s34
	s_nop 0
	global_load_lds_dwordx4 v[152:153], off
	v_lshl_add_u64 v[152:153], v[250:251], 0, s[36:37]
	s_mov_b32 m0, s35
	s_nop 0
	global_load_lds_dwordx4 v[152:153], off
	s_waitcnt vmcnt(8)
	s_waitcnt lgkmcnt(0)
	s_barrier
	s_setprio 1
	v_mfma_f32_16x16x32_bf16 v[64:67], v[184:187], v[216:219], v[64:67]
	v_mfma_f32_16x16x32_bf16 v[60:63], v[192:195], v[216:219], v[60:63]
	v_mfma_f32_16x16x32_bf16 v[48:51], v[184:187], v[224:227], v[48:51]
	v_mfma_f32_16x16x32_bf16 v[44:47], v[192:195], v[224:227], v[44:47]
	v_mfma_f32_16x16x32_bf16 v[32:35], v[184:187], v[232:235], v[32:35]
	v_mfma_f32_16x16x32_bf16 v[28:31], v[192:195], v[232:235], v[28:31]
	v_mfma_f32_16x16x32_bf16 v[16:19], v[184:187], v[240:243], v[16:19]
	v_mfma_f32_16x16x32_bf16 v[12:15], v[192:195], v[240:243], v[12:15]
	v_mfma_f32_16x16x32_bf16 v[64:67], v[188:191], v[220:223], v[64:67]
	v_mfma_f32_16x16x32_bf16 v[60:63], v[196:199], v[220:223], v[60:63]
	v_mfma_f32_16x16x32_bf16 v[48:51], v[188:191], v[228:231], v[48:51]
	v_mfma_f32_16x16x32_bf16 v[44:47], v[196:199], v[228:231], v[44:47]
	v_mfma_f32_16x16x32_bf16 v[32:35], v[188:191], v[236:239], v[32:35]
	v_mfma_f32_16x16x32_bf16 v[28:31], v[196:199], v[236:239], v[28:31]
	v_mfma_f32_16x16x32_bf16 v[16:19], v[188:191], v[244:247], v[16:19]
	v_mfma_f32_16x16x32_bf16 v[12:15], v[196:199], v[244:247], v[12:15]
	v_mfma_f32_16x16x32_bf16 v[56:59], v[200:203], v[216:219], v[56:59]
	v_mfma_f32_16x16x32_bf16 v[52:55], v[208:211], v[216:219], v[52:55]
	v_mfma_f32_16x16x32_bf16 v[40:43], v[200:203], v[224:227], v[40:43]
	v_mfma_f32_16x16x32_bf16 v[36:39], v[208:211], v[224:227], v[36:39]
	v_mfma_f32_16x16x32_bf16 v[24:27], v[200:203], v[232:235], v[24:27]
	v_mfma_f32_16x16x32_bf16 v[20:23], v[208:211], v[232:235], v[20:23]
	v_mfma_f32_16x16x32_bf16 v[8:11], v[200:203], v[240:243], v[8:11]
	v_mfma_f32_16x16x32_bf16 v[4:7], v[208:211], v[240:243], v[4:7]
	v_mfma_f32_16x16x32_bf16 v[56:59], v[204:207], v[220:223], v[56:59]
	v_mfma_f32_16x16x32_bf16 v[52:55], v[212:215], v[220:223], v[52:55]
	v_mfma_f32_16x16x32_bf16 v[40:43], v[204:207], v[228:231], v[40:43]
	v_mfma_f32_16x16x32_bf16 v[36:39], v[212:215], v[228:231], v[36:39]
	v_mfma_f32_16x16x32_bf16 v[24:27], v[204:207], v[236:239], v[24:27]
	v_mfma_f32_16x16x32_bf16 v[20:23], v[212:215], v[236:239], v[20:23]
	v_mfma_f32_16x16x32_bf16 v[8:11], v[204:207], v[244:247], v[8:11]
	v_mfma_f32_16x16x32_bf16 v[4:7], v[212:215], v[244:247], v[4:7]
	s_setprio 0
	s_barrier
	s_add_i32 s57, s57, 2
	s_add_u32 s18, s18, 0x100
	s_addc_u32 s19, s19, 0
	s_add_u32 s51, s51, 0x100
	s_addc_u32 s56, s56, 0
	s_cmp_gt_u32 s57, 29
.LBB0_251:
	s_add_u32 s20, s18, 0xfff80080
	s_addc_u32 s21, s19, -1
	s_add_i32 s63, 0, 0x10000
	s_cmp_eq_u32 s57, 28
	s_cselect_b32 s23, s11, s21
	s_cselect_b32 s22, s45, s20
	v_add_u32_e32 v151, s63, v156
	s_cselect_b32 s21, s7, s56
	s_cselect_b32 s20, s50, s51
	s_add_i32 s66, 0, 0x14000
	ds_read_b128 v[184:187], v151
	ds_read_b128 v[188:191], v151 offset:1024
	ds_read_b128 v[192:195], v151 offset:2048
	ds_read_b128 v[196:199], v151 offset:3072
	v_add_u32_e32 v151, s66, v156
	ds_read_b128 v[200:203], v151
	ds_read_b128 v[204:207], v151 offset:1024
	ds_read_b128 v[208:211], v151 offset:2048
	ds_read_b128 v[212:215], v151 offset:3072
	s_add_i32 m0, s17, 0xc000
	ds_read_b128 v[216:219], v160
	ds_read_b128 v[220:223], v160 offset:1024
	ds_read_b128 v[224:227], v160 offset:2048
	ds_read_b128 v[228:231], v160 offset:3072
	ds_read_b128 v[232:235], v160 offset:4096
	ds_read_b128 v[236:239], v160 offset:5120
	ds_read_b128 v[240:243], v160 offset:6144
	ds_read_b128 v[244:247], v160 offset:7168
	global_load_lds_dwordx4 v136, s[18:19]
	s_add_i32 m0, s17, 0xe000
	s_nop 0
	global_load_lds_dwordx4 v138, s[18:19]
	s_waitcnt vmcnt(8)
	s_waitcnt lgkmcnt(0)
	s_barrier
; #define PG8_STAGE(bufoff, gbase, voff) do { _Pragma("unroll") for (int _i = 0; _i < 2; ++_i) \
;         __builtin_amdgcn_global_load_lds((const unsigned*)((const char*)(gbase) + (voff)[_i]), (PG8_LAS unsigned*)(lds + (bufoff) + ldsw + _i * 8192), 16, 0, 0); } while (0)
; #define PG8_LDA(dst, b, h) do { _Pragma("unroll") for (int m = 0; m < 4; ++m) _Pragma("unroll") for (int k = 0; k < 2; ++k) dst[m][k] = *(const PG8_LAS bf16x8*)(lds + PG8_SA(b, h) + aoff + m * 2048 + k * 1024); } while (0)
; #define PG8_LDB(dst, b, h) do { _Pragma("unroll") for (int n = 0; n < 2; ++n) _Pragma("unroll") for (int k = 0; k < 2; ++k) dst[n][k] = *(const PG8_LAS bf16x8*)(lds + PG8_SB(b, h) + boff + n * 2048 + k * 1024); } while (0)
; #define PG8_MMA(ai, bj, At, Bt) do { __builtin_amdgcn_s_setprio(1); _Pragma("unroll") for (int m = 0; m < 4; ++m) _Pragma("unroll") for (int n = 0; n < 2; ++n) _Pragma("unroll") for (int k = 0; k < 2; ++k) \
;         acc[ai][bj][m][n] = __builtin_amdgcn_mfma_f32_16x16x32_bf16(Bt[n][k], At[m][k], acc[ai][bj][m][n], 0, 0, 0); __builtin_amdgcn_s_setprio(0); } while (0)
; #define PG8_WAIT_V(n) asm volatile("s_waitcnt vmcnt(" #n ")" ::: "memory")
; #define PG8_WAIT_L(n) asm volatile("s_waitcnt lgkmcnt(" #n ")" ::: "memory")
; #define PG8_BAR __builtin_amdgcn_s_barrier()
; #define PG8_SCHED __builtin_amdgcn_sched_barrier(0)
; template <class Epi, class Sched, bool ALIGN_EPI = false, bool SP2 = false>
; __device__ __forceinline__ void gemm_phase(PG8_LAS unsigned char* lds, const Gemm g, const Sched& S, const Epi& E) {
;     ...
;             PG8_LDB(B0, 0, 0); PG8_LDB(B1, 0, 1); PG8_SCHED; PG8_LDA(At, 0, 0); PG8_STAGE(PG8_SA(1, 1), a1 + hstep, voffA);
;             PG8_WAIT_V(8); PG8_WAIT_L(0); PG8_BAR; PG8_MMA(0, 0, At, B0); PG8_MMA(0, 1, At, B1); PG8_BAR; PG8_SCHED;
;             PG8_LDA(At, 0, 1); PG8_STAGE(PG8_SB(0, 0), b2, voffB); PG8_STAGE(PG8_SB(0, 1), b2 + hstep, voffB); PG8_STAGE(PG8_SA(0, 0), a2, voffA);
;             PG8_WAIT_V(8); PG8_WAIT_L(0); PG8_BAR; PG8_MMA(1, 0, At, B0); PG8_MMA(1, 1, At, B1); PG8_BAR; PG8_SCHED;
	s_setprio 1
	v_mfma_f32_16x16x32_bf16 v[128:131], v[184:187], v[216:219], v[128:131]
	v_mfma_f32_16x16x32_bf16 v[124:127], v[192:195], v[216:219], v[124:127]
	v_mfma_f32_16x16x32_bf16 v[112:115], v[184:187], v[224:227], v[112:115]
	v_mfma_f32_16x16x32_bf16 v[108:111], v[192:195], v[224:227], v[108:111]
	v_mfma_f32_16x16x32_bf16 v[96:99], v[184:187], v[232:235], v[96:99]
	v_mfma_f32_16x16x32_bf16 v[92:95], v[192:195], v[232:235], v[92:95]
	v_mfma_f32_16x16x32_bf16 v[80:83], v[184:187], v[240:243], v[80:83]
	v_mfma_f32_16x16x32_bf16 v[76:79], v[192:195], v[240:243], v[76:79]
	v_mfma_f32_16x16x32_bf16 v[128:131], v[188:191], v[220:223], v[128:131]
	v_mfma_f32_16x16x32_bf16 v[124:127], v[196:199], v[220:223], v[124:127]
	v_mfma_f32_16x16x32_bf16 v[112:115], v[188:191], v[228:231], v[112:115]
	v_mfma_f32_16x16x32_bf16 v[108:111], v[196:199], v[228:231], v[108:111]
	v_mfma_f32_16x16x32_bf16 v[96:99], v[188:191], v[236:239], v[96:99]
	v_mfma_f32_16x16x32_bf16 v[92:95], v[196:199], v[236:239], v[92:95]
	v_mfma_f32_16x16x32_bf16 v[80:83], v[188:191], v[244:247], v[80:83]
	v_mfma_f32_16x16x32_bf16 v[76:79], v[196:199], v[244:247], v[76:79]
	v_mfma_f32_16x16x32_bf16 v[120:123], v[200:203], v[216:219], v[120:123]
	v_mfma_f32_16x16x32_bf16 v[116:119], v[208:211], v[216:219], v[116:119]
	v_mfma_f32_16x16x32_bf16 v[104:107], v[200:203], v[224:227], v[104:107]
	v_mfma_f32_16x16x32_bf16 v[100:103], v[208:211], v[224:227], v[100:103]
	v_mfma_f32_16x16x32_bf16 v[88:91], v[200:203], v[232:235], v[88:91]
	v_mfma_f32_16x16x32_bf16 v[84:87], v[208:211], v[232:235], v[84:87]
	v_mfma_f32_16x16x32_bf16 v[72:75], v[200:203], v[240:243], v[72:75]
	v_mfma_f32_16x16x32_bf16 v[68:71], v[208:211], v[240:243], v[68:71]
	v_mfma_f32_16x16x32_bf16 v[120:123], v[204:207], v[220:223], v[120:123]
	v_mfma_f32_16x16x32_bf16 v[116:119], v[212:215], v[220:223], v[116:119]
	v_mfma_f32_16x16x32_bf16 v[104:107], v[204:207], v[228:231], v[104:107]
	v_mfma_f32_16x16x32_bf16 v[100:103], v[212:215], v[228:231], v[100:103]
	v_mfma_f32_16x16x32_bf16 v[88:91], v[204:207], v[236:239], v[88:91]
	v_mfma_f32_16x16x32_bf16 v[84:87], v[212:215], v[236:239], v[84:87]
	v_mfma_f32_16x16x32_bf16 v[72:75], v[204:207], v[244:247], v[72:75]
	v_mfma_f32_16x16x32_bf16 v[68:71], v[212:215], v[244:247], v[68:71]
	s_setprio 0
	s_barrier
	s_add_i32 s63, s63, s27
	s_mov_b32 m0, s63
	ds_read_b128 v[216:219], v160 offset:16384
	ds_read_b128 v[220:223], v160 offset:17408
	ds_read_b128 v[224:227], v160 offset:18432
	ds_read_b128 v[228:231], v160 offset:19456
	ds_read_b128 v[232:235], v160 offset:20480
	ds_read_b128 v[236:239], v160 offset:21504
	ds_read_b128 v[240:243], v160 offset:22528
	ds_read_b128 v[244:247], v160 offset:23552
	global_load_lds_dwordx4 v2, s[20:21]
	s_add_i32 m0, s63, 0x2000
	s_add_u32 s64, s20, 0x80000
	s_addc_u32 s65, s21, 0
	s_add_i32 s63, s66, s27
	global_load_lds_dwordx4 v0, s[20:21]
	s_mov_b32 m0, s63
	v_lshl_add_u64 v[250:251], s[22:23], 0, v[132:133]
	global_load_lds_dwordx4 v2, s[64:65]
	s_add_i32 m0, s63, 0x2000
	s_nop 0
	global_load_lds_dwordx4 v0, s[64:65]
	v_lshl_add_u64 v[248:249], s[22:23], 0, v[134:135]
	s_mov_b32 m0, s17
	s_nop 0
	global_load_lds_dwordx4 v[248:249], off
	s_mov_b32 m0, s29
	s_nop 0
	global_load_lds_dwordx4 v[250:251], off
	s_waitcnt vmcnt(8)
	s_waitcnt lgkmcnt(0)
	s_barrier
	s_setprio 1
	v_mfma_f32_16x16x32_bf16 v[64:67], v[184:187], v[216:219], v[64:67]
	v_mfma_f32_16x16x32_bf16 v[60:63], v[192:195], v[216:219], v[60:63]
	v_mfma_f32_16x16x32_bf16 v[48:51], v[184:187], v[224:227], v[48:51]
	v_mfma_f32_16x16x32_bf16 v[44:47], v[192:195], v[224:227], v[44:47]
	v_mfma_f32_16x16x32_bf16 v[32:35], v[184:187], v[232:235], v[32:35]
	v_mfma_f32_16x16x32_bf16 v[28:31], v[192:195], v[232:235], v[28:31]
	v_mfma_f32_16x16x32_bf16 v[16:19], v[184:187], v[240:243], v[16:19]
	v_mfma_f32_16x16x32_bf16 v[12:15], v[192:195], v[240:243], v[12:15]
	v_mfma_f32_16x16x32_bf16 v[64:67], v[188:191], v[220:223], v[64:67]
	v_mfma_f32_16x16x32_bf16 v[60:63], v[196:199], v[220:223], v[60:63]
	v_mfma_f32_16x16x32_bf16 v[48:51], v[188:191], v[228:231], v[48:51]
	v_mfma_f32_16x16x32_bf16 v[44:47], v[196:199], v[228:231], v[44:47]
	v_mfma_f32_16x16x32_bf16 v[32:35], v[188:191], v[236:239], v[32:35]
	v_mfma_f32_16x16x32_bf16 v[28:31], v[196:199], v[236:239], v[28:31]
	v_mfma_f32_16x16x32_bf16 v[16:19], v[188:191], v[244:247], v[16:19]
	v_mfma_f32_16x16x32_bf16 v[12:15], v[196:199], v[244:247], v[12:15]
	v_mfma_f32_16x16x32_bf16 v[56:59], v[200:203], v[216:219], v[56:59]
	v_mfma_f32_16x16x32_bf16 v[52:55], v[208:211], v[216:219], v[52:55]
	v_mfma_f32_16x16x32_bf16 v[40:43], v[200:203], v[224:227], v[40:43]
	v_mfma_f32_16x16x32_bf16 v[36:39], v[208:211], v[224:227], v[36:39]
	v_mfma_f32_16x16x32_bf16 v[24:27], v[200:203], v[232:235], v[24:27]
	v_mfma_f32_16x16x32_bf16 v[20:23], v[208:211], v[232:235], v[20:23]
	v_mfma_f32_16x16x32_bf16 v[8:11], v[200:203], v[240:243], v[8:11]
	v_mfma_f32_16x16x32_bf16 v[4:7], v[208:211], v[240:243], v[4:7]
	v_mfma_f32_16x16x32_bf16 v[56:59], v[204:207], v[220:223], v[56:59]
	v_mfma_f32_16x16x32_bf16 v[52:55], v[212:215], v[220:223], v[52:55]
	v_mfma_f32_16x16x32_bf16 v[40:43], v[204:207], v[228:231], v[40:43]
	v_mfma_f32_16x16x32_bf16 v[36:39], v[212:215], v[228:231], v[36:39]
	v_mfma_f32_16x16x32_bf16 v[24:27], v[204:207], v[236:239], v[24:27]
	v_mfma_f32_16x16x32_bf16 v[20:23], v[212:215], v[236:239], v[20:23]
	v_mfma_f32_16x16x32_bf16 v[8:11], v[204:207], v[244:247], v[8:11]
	v_mfma_f32_16x16x32_bf16 v[4:7], v[212:215], v[244:247], v[4:7]
	s_setprio 0
	s_barrier
; #define PG8_STAGE(bufoff, gbase, voff) do { _Pragma("unroll") for (int _i = 0; _i < 2; ++_i) \
;         __builtin_amdgcn_global_load_lds((const unsigned*)((const char*)(gbase) + (voff)[_i]), (PG8_LAS unsigned*)(lds + (bufoff) + ldsw + _i * 8192), 16, 0, 0); } while (0)
; #define PG8_LDA(dst, b, h) do { _Pragma("unroll") for (int m = 0; m < 4; ++m) _Pragma("unroll") for (int k = 0; k < 2; ++k) dst[m][k] = *(const PG8_LAS bf16x8*)(lds + PG8_SA(b, h) + aoff + m * 2048 + k * 1024); } while (0)
; #define PG8_LDB(dst, b, h) do { _Pragma("unroll") for (int n = 0; n < 2; ++n) _Pragma("unroll") for (int k = 0; k < 2; ++k) dst[n][k] = *(const PG8_LAS bf16x8*)(lds + PG8_SB(b, h) + boff + n * 2048 + k * 1024); } while (0)
; #define PG8_MMA(ai, bj, At, Bt) do { __builtin_amdgcn_s_setprio(1); _Pragma("unroll") for (int m = 0; m < 4; ++m) _Pragma("unroll") for (int n = 0; n < 2; ++n) _Pragma("unroll") for (int k = 0; k < 2; ++k) \
;         acc[ai][bj][m][n] = __builtin_amdgcn_mfma_f32_16x16x32_bf16(Bt[n][k], At[m][k], acc[ai][bj][m][n], 0, 0, 0); __builtin_amdgcn_s_setprio(0); } while (0)
; #define PG8_WAIT_V(n) asm volatile("s_waitcnt vmcnt(" #n ")" ::: "memory")
; #define PG8_WAIT_L(n) asm volatile("s_waitcnt lgkmcnt(" #n ")" ::: "memory")
; #define PG8_BAR __builtin_amdgcn_s_barrier()
; #define PG8_SCHED __builtin_amdgcn_sched_barrier(0)
; template <class Epi, class Sched, bool ALIGN_EPI = false, bool SP2 = false>
; __device__ __forceinline__ void gemm_phase(PG8_LAS unsigned char* lds, const Gemm g, const Sched& S, const Epi& E) {
;     ...
;             PG8_LDB(B0, 1, 0); PG8_LDB(B1, 1, 1); PG8_SCHED; PG8_LDA(At, 1, 0); PG8_STAGE(PG8_SA(0, 1), a2 + hstep, voffA);
;             PG8_WAIT_V(8); PG8_WAIT_L(0); PG8_BAR; PG8_MMA(0, 0, At, B0); PG8_MMA(0, 1, At, B1); PG8_BAR; PG8_SCHED;
;             PG8_LDA(At, 1, 1); PG8_STAGE(PG8_SB(1, 0), b3, voffB); PG8_STAGE(PG8_SB(1, 1), b3 + hstep, voffB); PG8_STAGE(PG8_SA(1, 0), a3, voffA);
;             PG8_WAIT_V(8); PG8_WAIT_L(0); PG8_BAR; PG8_MMA(1, 0, At, B0); PG8_MMA(1, 1, At, B1); PG8_BAR; PG8_SCHED;
;     ...
;         if constexpr (ALIGN_EPI) { if (wr == 0) PG8_BAR; }
	s_add_i32 s63, 0, 0x18000
	v_add_u32_e32 v151, s63, v156
	s_add_i32 s64, 0, 0x1c000
	ds_read_b128 v[184:187], v151
	ds_read_b128 v[188:191], v151 offset:1024
	ds_read_b128 v[192:195], v151 offset:2048
	ds_read_b128 v[196:199], v151 offset:3072
	v_add_u32_e32 v151, s64, v156
	ds_read_b128 v[200:203], v151
	ds_read_b128 v[204:207], v151 offset:1024
	ds_read_b128 v[208:211], v151 offset:2048
	ds_read_b128 v[212:215], v151 offset:3072
	s_add_u32 s22, s22, 0x80000
	s_addc_u32 s23, s23, 0
	s_mov_b32 m0, s30
	ds_read_b128 v[216:219], v160 offset:32768
	ds_read_b128 v[220:223], v160 offset:33792
	ds_read_b128 v[224:227], v160 offset:34816
	ds_read_b128 v[228:231], v160 offset:35840
	ds_read_b128 v[232:235], v160 offset:36864
	ds_read_b128 v[236:239], v160 offset:37888
	ds_read_b128 v[240:243], v160 offset:38912
	ds_read_b128 v[244:247], v160 offset:39936
	global_load_lds_dwordx4 v134, s[22:23]
	s_mov_b32 m0, s31
	s_nop 0
	global_load_lds_dwordx4 v132, s[22:23]
	s_waitcnt vmcnt(8)
	s_waitcnt lgkmcnt(0)
	s_barrier
	s_setprio 1
	v_mfma_f32_16x16x32_bf16 v[128:131], v[184:187], v[216:219], v[128:131]
	v_mfma_f32_16x16x32_bf16 v[124:127], v[192:195], v[216:219], v[124:127]
	v_mfma_f32_16x16x32_bf16 v[112:115], v[184:187], v[224:227], v[112:115]
	v_mfma_f32_16x16x32_bf16 v[108:111], v[192:195], v[224:227], v[108:111]
	v_mfma_f32_16x16x32_bf16 v[96:99], v[184:187], v[232:235], v[96:99]
	v_mfma_f32_16x16x32_bf16 v[92:95], v[192:195], v[232:235], v[92:95]
	v_mfma_f32_16x16x32_bf16 v[80:83], v[184:187], v[240:243], v[80:83]
	v_mfma_f32_16x16x32_bf16 v[76:79], v[192:195], v[240:243], v[76:79]
	v_mfma_f32_16x16x32_bf16 v[128:131], v[188:191], v[220:223], v[128:131]
	v_mfma_f32_16x16x32_bf16 v[124:127], v[196:199], v[220:223], v[124:127]
	v_mfma_f32_16x16x32_bf16 v[112:115], v[188:191], v[228:231], v[112:115]
	v_mfma_f32_16x16x32_bf16 v[108:111], v[196:199], v[228:231], v[108:111]
	v_mfma_f32_16x16x32_bf16 v[96:99], v[188:191], v[236:239], v[96:99]
	v_mfma_f32_16x16x32_bf16 v[92:95], v[196:199], v[236:239], v[92:95]
	v_mfma_f32_16x16x32_bf16 v[80:83], v[188:191], v[244:247], v[80:83]
	v_mfma_f32_16x16x32_bf16 v[76:79], v[196:199], v[244:247], v[76:79]
	v_mfma_f32_16x16x32_bf16 v[120:123], v[200:203], v[216:219], v[120:123]
	v_mfma_f32_16x16x32_bf16 v[116:119], v[208:211], v[216:219], v[116:119]
	v_mfma_f32_16x16x32_bf16 v[104:107], v[200:203], v[224:227], v[104:107]
	v_mfma_f32_16x16x32_bf16 v[100:103], v[208:211], v[224:227], v[100:103]
	v_mfma_f32_16x16x32_bf16 v[88:91], v[200:203], v[232:235], v[88:91]
	v_mfma_f32_16x16x32_bf16 v[84:87], v[208:211], v[232:235], v[84:87]
	v_mfma_f32_16x16x32_bf16 v[72:75], v[200:203], v[240:243], v[72:75]
	v_mfma_f32_16x16x32_bf16 v[68:71], v[208:211], v[240:243], v[68:71]
	v_mfma_f32_16x16x32_bf16 v[120:123], v[204:207], v[220:223], v[120:123]
	v_mfma_f32_16x16x32_bf16 v[116:119], v[212:215], v[220:223], v[116:119]
	v_mfma_f32_16x16x32_bf16 v[104:107], v[204:207], v[228:231], v[104:107]
	v_mfma_f32_16x16x32_bf16 v[100:103], v[212:215], v[228:231], v[100:103]
	v_mfma_f32_16x16x32_bf16 v[88:91], v[204:207], v[236:239], v[88:91]
	v_mfma_f32_16x16x32_bf16 v[84:87], v[212:215], v[236:239], v[84:87]
	v_mfma_f32_16x16x32_bf16 v[72:75], v[204:207], v[244:247], v[72:75]
	v_mfma_f32_16x16x32_bf16 v[68:71], v[212:215], v[244:247], v[68:71]
	s_setprio 0
	s_barrier
	s_add_i32 s22, s63, s27
	s_mov_b32 m0, s22
	ds_read_b128 v[216:219], v160 offset:49152
	ds_read_b128 v[220:223], v160 offset:50176
	ds_read_b128 v[224:227], v160 offset:51200
	ds_read_b128 v[228:231], v160 offset:52224
	ds_read_b128 v[232:235], v160 offset:53248
	ds_read_b128 v[236:239], v160 offset:54272
	ds_read_b128 v[240:243], v160 offset:55296
	ds_read_b128 v[244:247], v160 offset:56320
	s_add_u32 vcc_lo, s20, 0x80
	s_addc_u32 vcc_hi, s21, 0
	global_load_lds_dwordx4 v2, vcc
	s_add_i32 m0, s22, 0x2000
	s_add_u32 s20, s20, 0x80080
	s_addc_u32 s21, s21, 0
	s_add_i32 s22, s64, s27
	s_add_u32 vcc_lo, s20, 0xfff80000
	s_addc_u32 vcc_hi, s21, -1
	global_load_lds_dwordx4 v0, vcc
	s_mov_b32 m0, s22
	s_nop 0
	global_load_lds_dwordx4 v2, s[20:21]
	s_add_i32 m0, s22, 0x2000
	s_nop 0
	global_load_lds_dwordx4 v0, s[20:21]
	v_lshl_add_u64 v[152:153], v[248:249], 0, s[36:37]
	s_mov_b32 m0, s34
	s_nop 0
	global_load_lds_dwordx4 v[152:153], off
	v_lshl_add_u64 v[152:153], v[250:251], 0, s[36:37]
	s_mov_b32 m0, s35
	s_nop 0
	global_load_lds_dwordx4 v[152:153], off
	s_waitcnt vmcnt(8)
	s_waitcnt lgkmcnt(0)
	s_barrier
	s_setprio 1
	v_mfma_f32_16x16x32_bf16 v[64:67], v[184:187], v[216:219], v[64:67]
	v_mfma_f32_16x16x32_bf16 v[60:63], v[192:195], v[216:219], v[60:63]
	v_mfma_f32_16x16x32_bf16 v[48:51], v[184:187], v[224:227], v[48:51]
	v_mfma_f32_16x16x32_bf16 v[44:47], v[192:195], v[224:227], v[44:47]
	v_mfma_f32_16x16x32_bf16 v[32:35], v[184:187], v[232:235], v[32:35]
	v_mfma_f32_16x16x32_bf16 v[28:31], v[192:195], v[232:235], v[28:31]
	v_mfma_f32_16x16x32_bf16 v[16:19], v[184:187], v[240:243], v[16:19]
	v_mfma_f32_16x16x32_bf16 v[12:15], v[192:195], v[240:243], v[12:15]
	v_mfma_f32_16x16x32_bf16 v[64:67], v[188:191], v[220:223], v[64:67]
	v_mfma_f32_16x16x32_bf16 v[60:63], v[196:199], v[220:223], v[60:63]
	v_mfma_f32_16x16x32_bf16 v[48:51], v[188:191], v[228:231], v[48:51]
	v_mfma_f32_16x16x32_bf16 v[44:47], v[196:199], v[228:231], v[44:47]
	v_mfma_f32_16x16x32_bf16 v[32:35], v[188:191], v[236:239], v[32:35]
	v_mfma_f32_16x16x32_bf16 v[28:31], v[196:199], v[236:239], v[28:31]
	v_mfma_f32_16x16x32_bf16 v[16:19], v[188:191], v[244:247], v[16:19]
	v_mfma_f32_16x16x32_bf16 v[12:15], v[196:199], v[244:247], v[12:15]
	v_mfma_f32_16x16x32_bf16 v[56:59], v[200:203], v[216:219], v[56:59]
	v_mfma_f32_16x16x32_bf16 v[52:55], v[208:211], v[216:219], v[52:55]
	v_mfma_f32_16x16x32_bf16 v[40:43], v[200:203], v[224:227], v[40:43]
	v_mfma_f32_16x16x32_bf16 v[36:39], v[208:211], v[224:227], v[36:39]
	v_mfma_f32_16x16x32_bf16 v[24:27], v[200:203], v[232:235], v[24:27]
	v_mfma_f32_16x16x32_bf16 v[20:23], v[208:211], v[232:235], v[20:23]
	v_mfma_f32_16x16x32_bf16 v[8:11], v[200:203], v[240:243], v[8:11]
	v_mfma_f32_16x16x32_bf16 v[4:7], v[208:211], v[240:243], v[4:7]
	v_mfma_f32_16x16x32_bf16 v[56:59], v[204:207], v[220:223], v[56:59]
	v_mfma_f32_16x16x32_bf16 v[52:55], v[212:215], v[220:223], v[52:55]
	v_mfma_f32_16x16x32_bf16 v[40:43], v[204:207], v[228:231], v[40:43]
	v_mfma_f32_16x16x32_bf16 v[36:39], v[212:215], v[228:231], v[36:39]
	v_mfma_f32_16x16x32_bf16 v[24:27], v[204:207], v[236:239], v[24:27]
	v_mfma_f32_16x16x32_bf16 v[20:23], v[212:215], v[236:239], v[20:23]
	v_mfma_f32_16x16x32_bf16 v[8:11], v[204:207], v[244:247], v[8:11]
	v_mfma_f32_16x16x32_bf16 v[4:7], v[212:215], v[244:247], v[4:7]
	s_setprio 0
	s_barrier
	s_add_i32 s57, s57, 2
	s_add_u32 s18, s18, 0x100
	s_addc_u32 s19, s19, 0
	s_add_u32 s51, s51, 0x100
	s_addc_u32 s56, s56, 0
	s_cmp_gt_u32 s57, 29
	s_cbranch_scc0 .LBB0_251
	s_and_b64 vcc, exec, s[4:5]
	s_cbranch_vccz .LBB0_254
	s_barrier

; #define PG8_STAGE(bufoff, gbase, voff) do { _Pragma("unroll") for (int _i = 0; _i < 2; ++_i) \
;         __builtin_amdgcn_global_load_lds((const unsigned*)((const char*)(gbase) + (voff)[_i]), (PG8_LAS unsigned*)(lds + (bufoff) + ldsw + _i * 8192), 16, 0, 0); } while (0)
; #define PG8_LDA(dst, b, h) do { _Pragma("unroll") for (int m = 0; m < 4; ++m) _Pragma("unroll") for (int k = 0; k < 2; ++k) dst[m][k] = *(const PG8_LAS bf16x8*)(lds + PG8_SA(b, h) + aoff + m * 2048 + k * 1024); } while (0)
; #define PG8_LDB(dst, b, h) do { _Pragma("unroll") for (int n = 0; n < 2; ++n) _Pragma("unroll") for (int k = 0; k < 2; ++k) dst[n][k] = *(const PG8_LAS bf16x8*)(lds + PG8_SB(b, h) + boff + n * 2048 + k * 1024); } while (0)
; #define PG8_WAIT_V(n) asm volatile("s_waitcnt vmcnt(" #n ")" ::: "memory")
; #define PG8_WAIT_L(n) asm volatile("s_waitcnt lgkmcnt(" #n ")" ::: "memory")
; #define PG8_BAR __builtin_amdgcn_s_barrier()
; #define PG8_SCHED __builtin_amdgcn_sched_barrier(0)
; template <class Epi, class Sched, bool ALIGN_EPI = false, bool SP2 = false>
; __device__ __forceinline__ void gemm_phase(PG8_LAS unsigned char* lds, const Gemm g, const Sched& S, const Epi& E) {
;     ...
;         const bool has_next = S.next(ui + 1, nxt);
;         const char* nA = has_next ? (const char*)g.A + (size_t)nxt.pm * tstep : cA; const char* nB = has_next ? (const char*)g.Bt + (size_t)nxt.pn * tstep : cB;
;         for (int t = 0; t < nt; t += 2) {
;             const bool last = (t == nt - 2);
;             const char* a1 = cA + (size_t)(t + 1) * kstep;
;             const char* a2 = last ? nA : cA + (size_t)(t + 2) * kstep; const char* b2 = last ? nB : cB + (size_t)(t + 2) * kstep;
;             const char* a3 = a2 + kstep; const char* b3 = b2 + kstep;
;             if (last && has_next) S.a_ready(nxt);
;             if constexpr (SP2) {
;             PG8_LDB(B0, 0, 0); PG8_LDB(B1, 0, 1); PG8_SCHED; PG8_LDA(At, 0, 0); PG8_STAGE(PG8_SA(1, 1), a1 + hstep, voffA);
;             PG8_WAIT_V(8); PG8_WAIT_L(0); PG8_BAR; PG8_MMA(0, 0, At, B0); PG8_MMA(0, 1, At, B1); PG8_BAR; PG8_SCHED;
;             PG8_LDA(At, 0, 1); PG8_STAGE(PG8_SB(0, 0), b2, voffB); PG8_STAGE(PG8_SB(0, 1), b2 + hstep, voffB); PG8_STAGE(PG8_SA(0, 0), a2, voffA);
;             PG8_WAIT_V(8); PG8_WAIT_L(0); PG8_BAR; PG8_MMA(1, 0, At, B0); PG8_MMA(1, 1, At, B1); PG8_BAR; PG8_SCHED;
.LBB0_482:
	s_ashr_i32 s13, s12, 31
	s_lshl_b64 s[14:15], s[12:13], 20
	s_add_u32 s14, s54, s14
	s_addc_u32 s15, s55, s15
	s_and_b64 s[16:17], s[4:5], exec
	s_cselect_b32 s13, s15, s23
	s_cselect_b32 s19, s14, s22
	s_ashr_i32 s11, s10, 31
	s_lshl_b64 s[16:17], s[10:11], 20
	s_add_u32 s16, s29, s16
	s_addc_u32 s17, s30, s17
	s_and_b64 s[26:27], s[4:5], exec
	s_cselect_b32 s11, s17, s25
	s_cselect_b32 s56, s16, s24
	s_add_u32 s22, s22, 0x80080
	s_addc_u32 s23, s23, 0
	s_add_u32 s57, s24, 0x100
	s_addc_u32 s63, s25, 0
	s_mov_b32 s64, -2
	s_waitcnt lgkmcnt(0)
	s_add_u32 s24, s22, 0xfff80080
	s_addc_u32 s25, s23, -1
	s_add_i32 s65, 0, 0x10000
	s_cmp_eq_u32 s64, 28
	s_cselect_b32 s27, s13, s25
	s_cselect_b32 s26, s19, s24
	s_cselect_b32 s25, s11, s63
	s_cselect_b32 s24, s56, s57
	s_add_i32 s76, 0, 0x14000
	v_add_u32_e32 v162, s65, v185
	v_add_u32_e32 v166, s76, v185
	ds_read_b128 v[132:135], v162
	ds_read_b128 v[136:139], v162 offset:1024
	ds_read_b128 v[158:161], v162 offset:2048
	ds_read_b128 v[162:165], v162 offset:3072
	ds_read_b128 v[188:191], v166
	ds_read_b128 v[192:195], v166 offset:1024
	ds_read_b128 v[196:199], v166 offset:2048
	ds_read_b128 v[200:203], v166 offset:3072
	s_add_i32 m0, s21, 0xc000
	ds_read_b128 v[204:207], v187
	ds_read_b128 v[208:211], v187 offset:1024
	ds_read_b128 v[212:215], v187 offset:2048
	ds_read_b128 v[216:219], v187 offset:3072
	ds_read_b128 v[220:223], v187 offset:4096
	ds_read_b128 v[224:227], v187 offset:5120
	ds_read_b128 v[228:231], v187 offset:6144
	ds_read_b128 v[232:235], v187 offset:7168
	global_load_lds_dwordx4 v154, s[22:23]
	s_add_i32 m0, s21, 0xe000
	s_nop 0
	global_load_lds_dwordx4 v156, s[22:23]
	s_waitcnt vmcnt(8)
	s_waitcnt lgkmcnt(0)
	s_barrier
	s_setprio 1
	v_mfma_f32_16x16x32_bf16 v[128:131], v[132:135], v[204:207], 0
	v_mfma_f32_16x16x32_bf16 v[124:127], v[158:161], v[204:207], 0
	v_mfma_f32_16x16x32_bf16 v[112:115], v[132:135], v[212:215], 0
	v_mfma_f32_16x16x32_bf16 v[108:111], v[158:161], v[212:215], 0
	v_mfma_f32_16x16x32_bf16 v[96:99], v[132:135], v[220:223], 0
	v_mfma_f32_16x16x32_bf16 v[92:95], v[158:161], v[220:223], 0
	v_mfma_f32_16x16x32_bf16 v[80:83], v[132:135], v[228:231], 0
	v_mfma_f32_16x16x32_bf16 v[76:79], v[158:161], v[228:231], 0
	v_mfma_f32_16x16x32_bf16 v[128:131], v[136:139], v[208:211], v[128:131]
	v_mfma_f32_16x16x32_bf16 v[124:127], v[162:165], v[208:211], v[124:127]
	v_mfma_f32_16x16x32_bf16 v[112:115], v[136:139], v[216:219], v[112:115]
	v_mfma_f32_16x16x32_bf16 v[108:111], v[162:165], v[216:219], v[108:111]
	v_mfma_f32_16x16x32_bf16 v[96:99], v[136:139], v[224:227], v[96:99]
	v_mfma_f32_16x16x32_bf16 v[92:95], v[162:165], v[224:227], v[92:95]
	v_mfma_f32_16x16x32_bf16 v[80:83], v[136:139], v[232:235], v[80:83]
	v_mfma_f32_16x16x32_bf16 v[76:79], v[162:165], v[232:235], v[76:79]
	v_mfma_f32_16x16x32_bf16 v[120:123], v[188:191], v[204:207], 0
	v_mfma_f32_16x16x32_bf16 v[116:119], v[196:199], v[204:207], 0
	v_mfma_f32_16x16x32_bf16 v[104:107], v[188:191], v[212:215], 0
	v_mfma_f32_16x16x32_bf16 v[100:103], v[196:199], v[212:215], 0
	v_mfma_f32_16x16x32_bf16 v[88:91], v[188:191], v[220:223], 0
	v_mfma_f32_16x16x32_bf16 v[84:87], v[196:199], v[220:223], 0
	v_mfma_f32_16x16x32_bf16 v[72:75], v[188:191], v[228:231], 0
	v_mfma_f32_16x16x32_bf16 v[68:71], v[196:199], v[228:231], 0
	v_mfma_f32_16x16x32_bf16 v[120:123], v[192:195], v[208:211], v[120:123]
	v_mfma_f32_16x16x32_bf16 v[116:119], v[200:203], v[208:211], v[116:119]
	v_mfma_f32_16x16x32_bf16 v[104:107], v[192:195], v[216:219], v[104:107]
	v_mfma_f32_16x16x32_bf16 v[100:103], v[200:203], v[216:219], v[100:103]
	v_mfma_f32_16x16x32_bf16 v[88:91], v[192:195], v[224:227], v[88:91]
	v_mfma_f32_16x16x32_bf16 v[84:87], v[200:203], v[224:227], v[84:87]
	v_mfma_f32_16x16x32_bf16 v[72:75], v[192:195], v[232:235], v[72:75]
	v_mfma_f32_16x16x32_bf16 v[68:71], v[200:203], v[232:235], v[68:71]
	s_setprio 0
	s_barrier
	s_add_i32 s65, s65, s31
	s_mov_b32 m0, s65
	ds_read_b128 v[204:207], v187 offset:16384
	ds_read_b128 v[208:211], v187 offset:17408
	ds_read_b128 v[212:215], v187 offset:18432
	ds_read_b128 v[216:219], v187 offset:19456
	ds_read_b128 v[220:223], v187 offset:20480
	ds_read_b128 v[224:227], v187 offset:21504
	ds_read_b128 v[228:231], v187 offset:22528
	ds_read_b128 v[232:235], v187 offset:23552
	global_load_lds_dwordx4 v2, s[24:25]
	s_add_i32 m0, s65, 0x2000
	s_add_u32 s66, s24, 0x80000
	s_addc_u32 s67, s25, 0
	s_add_i32 s65, s76, s31
	global_load_lds_dwordx4 v152, s[24:25]
	s_mov_b32 m0, s65
	v_lshl_add_u64 v[240:241], s[26:27], 0, v[150:151]
	global_load_lds_dwordx4 v2, s[66:67]
	s_add_i32 m0, s65, 0x2000
	s_nop 0
	global_load_lds_dwordx4 v152, s[66:67]
	v_lshl_add_u64 v[238:239], s[26:27], 0, v[0:1]
	s_mov_b32 m0, s21
	s_nop 0
	global_load_lds_dwordx4 v[238:239], off
	s_mov_b32 m0, s34
	s_nop 0
	global_load_lds_dwordx4 v[240:241], off
	s_waitcnt vmcnt(8)
	s_waitcnt lgkmcnt(0)
	s_barrier
; #define PG8_STAGE(bufoff, gbase, voff) do { _Pragma("unroll") for (int _i = 0; _i < 2; ++_i) \
;         __builtin_amdgcn_global_load_lds((const unsigned*)((const char*)(gbase) + (voff)[_i]), (PG8_LAS unsigned*)(lds + (bufoff) + ldsw + _i * 8192), 16, 0, 0); } while (0)
; #define PG8_LDA(dst, b, h) do { _Pragma("unroll") for (int m = 0; m < 4; ++m) _Pragma("unroll") for (int k = 0; k < 2; ++k) dst[m][k] = *(const PG8_LAS bf16x8*)(lds + PG8_SA(b, h) + aoff + m * 2048 + k * 1024); } while (0)
; #define PG8_LDB(dst, b, h) do { _Pragma("unroll") for (int n = 0; n < 2; ++n) _Pragma("unroll") for (int k = 0; k < 2; ++k) dst[n][k] = *(const PG8_LAS bf16x8*)(lds + PG8_SB(b, h) + boff + n * 2048 + k * 1024); } while (0)
; #define PG8_MMA(ai, bj, At, Bt) do { __builtin_amdgcn_s_setprio(1); _Pragma("unroll") for (int m = 0; m < 4; ++m) _Pragma("unroll") for (int n = 0; n < 2; ++n) _Pragma("unroll") for (int k = 0; k < 2; ++k) \
;         acc[ai][bj][m][n] = __builtin_amdgcn_mfma_f32_16x16x32_bf16(Bt[n][k], At[m][k], acc[ai][bj][m][n], 0, 0, 0); __builtin_amdgcn_s_setprio(0); } while (0)
; #define PG8_WAIT_V(n) asm volatile("s_waitcnt vmcnt(" #n ")" ::: "memory")
; #define PG8_WAIT_L(n) asm volatile("s_waitcnt lgkmcnt(" #n ")" ::: "memory")
; #define PG8_BAR __builtin_amdgcn_s_barrier()
; #define PG8_SCHED __builtin_amdgcn_sched_barrier(0)
; template <class Epi, class Sched, bool ALIGN_EPI = false, bool SP2 = false>
; __device__ __forceinline__ void gemm_phase(PG8_LAS unsigned char* lds, const Gemm g, const Sched& S, const Epi& E) {
;     ...
;             PG8_WAIT_V(8); PG8_WAIT_L(0); PG8_BAR; PG8_MMA(1, 0, At, B0); PG8_MMA(1, 1, At, B1); PG8_BAR; PG8_SCHED;
;             PG8_LDB(B0, 1, 0); PG8_LDB(B1, 1, 1); PG8_SCHED; PG8_LDA(At, 1, 0); PG8_STAGE(PG8_SA(0, 1), a2 + hstep, voffA);
;             PG8_WAIT_V(8); PG8_WAIT_L(0); PG8_BAR; PG8_MMA(0, 0, At, B0); PG8_MMA(0, 1, At, B1); PG8_BAR; PG8_SCHED;
	s_setprio 1
	v_mfma_f32_16x16x32_bf16 v[64:67], v[132:135], v[204:207], 0
	v_mfma_f32_16x16x32_bf16 v[60:63], v[158:161], v[204:207], 0
	v_mfma_f32_16x16x32_bf16 v[48:51], v[132:135], v[212:215], 0
	v_mfma_f32_16x16x32_bf16 v[44:47], v[158:161], v[212:215], 0
	v_mfma_f32_16x16x32_bf16 v[32:35], v[132:135], v[220:223], 0
	v_mfma_f32_16x16x32_bf16 v[28:31], v[158:161], v[220:223], 0
	v_mfma_f32_16x16x32_bf16 v[16:19], v[132:135], v[228:231], 0
	v_mfma_f32_16x16x32_bf16 v[12:15], v[158:161], v[228:231], 0
	v_mfma_f32_16x16x32_bf16 v[64:67], v[136:139], v[208:211], v[64:67]
	v_mfma_f32_16x16x32_bf16 v[60:63], v[162:165], v[208:211], v[60:63]
	v_mfma_f32_16x16x32_bf16 v[48:51], v[136:139], v[216:219], v[48:51]
	v_mfma_f32_16x16x32_bf16 v[44:47], v[162:165], v[216:219], v[44:47]
	v_mfma_f32_16x16x32_bf16 v[32:35], v[136:139], v[224:227], v[32:35]
	v_mfma_f32_16x16x32_bf16 v[28:31], v[162:165], v[224:227], v[28:31]
	v_mfma_f32_16x16x32_bf16 v[16:19], v[136:139], v[232:235], v[16:19]
	v_mfma_f32_16x16x32_bf16 v[12:15], v[162:165], v[232:235], v[12:15]
	v_mfma_f32_16x16x32_bf16 v[56:59], v[188:191], v[204:207], 0
	v_mfma_f32_16x16x32_bf16 v[52:55], v[196:199], v[204:207], 0
	v_mfma_f32_16x16x32_bf16 v[40:43], v[188:191], v[212:215], 0
	v_mfma_f32_16x16x32_bf16 v[36:39], v[196:199], v[212:215], 0
	v_mfma_f32_16x16x32_bf16 v[24:27], v[188:191], v[220:223], 0
	v_mfma_f32_16x16x32_bf16 v[20:23], v[196:199], v[220:223], 0
	v_mfma_f32_16x16x32_bf16 v[8:11], v[188:191], v[228:231], 0
	v_mfma_f32_16x16x32_bf16 v[4:7], v[196:199], v[228:231], 0
	v_mfma_f32_16x16x32_bf16 v[56:59], v[192:195], v[208:211], v[56:59]
	v_mfma_f32_16x16x32_bf16 v[52:55], v[200:203], v[208:211], v[52:55]
	v_mfma_f32_16x16x32_bf16 v[40:43], v[192:195], v[216:219], v[40:43]
	v_mfma_f32_16x16x32_bf16 v[36:39], v[200:203], v[216:219], v[36:39]
	v_mfma_f32_16x16x32_bf16 v[24:27], v[192:195], v[224:227], v[24:27]
	v_mfma_f32_16x16x32_bf16 v[20:23], v[200:203], v[224:227], v[20:23]
	v_mfma_f32_16x16x32_bf16 v[8:11], v[192:195], v[232:235], v[8:11]
	v_mfma_f32_16x16x32_bf16 v[4:7], v[200:203], v[232:235], v[4:7]
	s_setprio 0
	s_barrier
	s_add_i32 s65, 0, 0x18000
	s_add_i32 s66, 0, 0x1c000
	v_add_u32_e32 v162, s65, v185
	v_add_u32_e32 v200, s66, v185
	ds_read_b128 v[132:135], v162
	ds_read_b128 v[136:139], v162 offset:1024
	ds_read_b128 v[158:161], v162 offset:2048
	ds_read_b128 v[162:165], v162 offset:3072
	ds_read_b128 v[188:191], v200
	ds_read_b128 v[192:195], v200 offset:1024
	ds_read_b128 v[196:199], v200 offset:2048
	ds_read_b128 v[200:203], v200 offset:3072
	s_add_u32 s26, s26, 0x80000
	s_addc_u32 s27, s27, 0
	s_mov_b32 m0, s35
	ds_read_b128 v[204:207], v187 offset:32768
	ds_read_b128 v[208:211], v187 offset:33792
	ds_read_b128 v[212:215], v187 offset:34816
	ds_read_b128 v[216:219], v187 offset:35840
	ds_read_b128 v[220:223], v187 offset:36864
	ds_read_b128 v[224:227], v187 offset:37888
	ds_read_b128 v[228:231], v187 offset:38912
	ds_read_b128 v[232:235], v187 offset:39936
	global_load_lds_dwordx4 v0, s[26:27]
	s_mov_b32 m0, s42
	s_nop 0
	global_load_lds_dwordx4 v150, s[26:27]
	s_waitcnt vmcnt(8)
	s_waitcnt lgkmcnt(0)
	s_barrier
	s_setprio 1
	v_mfma_f32_16x16x32_bf16 v[128:131], v[132:135], v[204:207], v[128:131]
	v_mfma_f32_16x16x32_bf16 v[124:127], v[158:161], v[204:207], v[124:127]
	v_mfma_f32_16x16x32_bf16 v[112:115], v[132:135], v[212:215], v[112:115]
	v_mfma_f32_16x16x32_bf16 v[108:111], v[158:161], v[212:215], v[108:111]
	v_mfma_f32_16x16x32_bf16 v[96:99], v[132:135], v[220:223], v[96:99]
	v_mfma_f32_16x16x32_bf16 v[92:95], v[158:161], v[220:223], v[92:95]
	v_mfma_f32_16x16x32_bf16 v[80:83], v[132:135], v[228:231], v[80:83]
	v_mfma_f32_16x16x32_bf16 v[76:79], v[158:161], v[228:231], v[76:79]
	v_mfma_f32_16x16x32_bf16 v[128:131], v[136:139], v[208:211], v[128:131]
	v_mfma_f32_16x16x32_bf16 v[124:127], v[162:165], v[208:211], v[124:127]
	v_mfma_f32_16x16x32_bf16 v[112:115], v[136:139], v[216:219], v[112:115]
	v_mfma_f32_16x16x32_bf16 v[108:111], v[162:165], v[216:219], v[108:111]
	v_mfma_f32_16x16x32_bf16 v[96:99], v[136:139], v[224:227], v[96:99]
	v_mfma_f32_16x16x32_bf16 v[92:95], v[162:165], v[224:227], v[92:95]
	v_mfma_f32_16x16x32_bf16 v[80:83], v[136:139], v[232:235], v[80:83]
	v_mfma_f32_16x16x32_bf16 v[76:79], v[162:165], v[232:235], v[76:79]
	v_mfma_f32_16x16x32_bf16 v[120:123], v[188:191], v[204:207], v[120:123]
	v_mfma_f32_16x16x32_bf16 v[116:119], v[196:199], v[204:207], v[116:119]
	v_mfma_f32_16x16x32_bf16 v[104:107], v[188:191], v[212:215], v[104:107]
	v_mfma_f32_16x16x32_bf16 v[100:103], v[196:199], v[212:215], v[100:103]
	v_mfma_f32_16x16x32_bf16 v[88:91], v[188:191], v[220:223], v[88:91]
	v_mfma_f32_16x16x32_bf16 v[84:87], v[196:199], v[220:223], v[84:87]
	v_mfma_f32_16x16x32_bf16 v[72:75], v[188:191], v[228:231], v[72:75]
	v_mfma_f32_16x16x32_bf16 v[68:71], v[196:199], v[228:231], v[68:71]
	v_mfma_f32_16x16x32_bf16 v[120:123], v[192:195], v[208:211], v[120:123]
	v_mfma_f32_16x16x32_bf16 v[116:119], v[200:203], v[208:211], v[116:119]
	v_mfma_f32_16x16x32_bf16 v[104:107], v[192:195], v[216:219], v[104:107]
	v_mfma_f32_16x16x32_bf16 v[100:103], v[200:203], v[216:219], v[100:103]
	v_mfma_f32_16x16x32_bf16 v[88:91], v[192:195], v[224:227], v[88:91]
	v_mfma_f32_16x16x32_bf16 v[84:87], v[200:203], v[224:227], v[84:87]
	v_mfma_f32_16x16x32_bf16 v[72:75], v[192:195], v[232:235], v[72:75]
	v_mfma_f32_16x16x32_bf16 v[68:71], v[200:203], v[232:235], v[68:71]
	s_setprio 0
	s_barrier
; #define PG8_STAGE(bufoff, gbase, voff) do { _Pragma("unroll") for (int _i = 0; _i < 2; ++_i) \
;         __builtin_amdgcn_global_load_lds((const unsigned*)((const char*)(gbase) + (voff)[_i]), (PG8_LAS unsigned*)(lds + (bufoff) + ldsw + _i * 8192), 16, 0, 0); } while (0)
; #define PG8_LDA(dst, b, h) do { _Pragma("unroll") for (int m = 0; m < 4; ++m) _Pragma("unroll") for (int k = 0; k < 2; ++k) dst[m][k] = *(const PG8_LAS bf16x8*)(lds + PG8_SA(b, h) + aoff + m * 2048 + k * 1024); } while (0)
; #define PG8_LDB(dst, b, h) do { _Pragma("unroll") for (int n = 0; n < 2; ++n) _Pragma("unroll") for (int k = 0; k < 2; ++k) dst[n][k] = *(const PG8_LAS bf16x8*)(lds + PG8_SB(b, h) + boff + n * 2048 + k * 1024); } while (0)
; #define PG8_MMA(ai, bj, At, Bt) do { __builtin_amdgcn_s_setprio(1); _Pragma("unroll") for (int m = 0; m < 4; ++m) _Pragma("unroll") for (int n = 0; n < 2; ++n) _Pragma("unroll") for (int k = 0; k < 2; ++k) \
;         acc[ai][bj][m][n] = __builtin_amdgcn_mfma_f32_16x16x32_bf16(Bt[n][k], At[m][k], acc[ai][bj][m][n], 0, 0, 0); __builtin_amdgcn_s_setprio(0); } while (0)
; #define PG8_WAIT_V(n) asm volatile("s_waitcnt vmcnt(" #n ")" ::: "memory")
; template <class Epi, class Sched, bool ALIGN_EPI = false, bool SP2 = false>
; __device__ __forceinline__ void gemm_phase(PG8_LAS unsigned char* lds, const Gemm g, const Sched& S, const Epi& E) {
;     ...
;             PG8_LDB(B0, 0, 0); PG8_LDB(B1, 0, 1); PG8_SCHED; PG8_LDA(At, 0, 0); PG8_STAGE(PG8_SA(1, 1), a1 + hstep, voffA);
;             PG8_WAIT_V(8); PG8_WAIT_L(0); PG8_BAR; PG8_MMA(0, 0, At, B0); PG8_MMA(0, 1, At, B1); PG8_BAR; PG8_SCHED;
;             PG8_LDA(At, 0, 1); PG8_STAGE(PG8_SB(0, 0), b2, voffB); PG8_STAGE(PG8_SB(0, 1), b2 + hstep, voffB); PG8_STAGE(PG8_SA(0, 0), a2, voffA);
;             PG8_WAIT_V(8); PG8_WAIT_L(0); PG8_BAR; PG8_MMA(1, 0, At, B0); PG8_MMA(1, 1, At, B1); PG8_BAR; PG8_SCHED;
;             PG8_LDB(B0, 1, 0); PG8_LDB(B1, 1, 1); PG8_SCHED; PG8_LDA(At, 1, 0); PG8_STAGE(PG8_SA(0, 1), a2 + hstep, voffA);
;             PG8_WAIT_V(8); PG8_WAIT_L(0); PG8_BAR; PG8_MMA(0, 0, At, B0); PG8_MMA(0, 1, At, B1); PG8_BAR; PG8_SCHED;
;             PG8_LDA(At, 1, 1); PG8_STAGE(PG8_SB(1, 0), b3, voffB); PG8_STAGE(PG8_SB(1, 1), b3 + hstep, voffB); PG8_STAGE(PG8_SA(1, 0), a3, voffA);
;             PG8_WAIT_V(8); PG8_WAIT_L(0); PG8_BAR; PG8_MMA(1, 0, At, B0); PG8_MMA(1, 1, At, B1); PG8_BAR; PG8_SCHED;
	s_add_i32 s26, s65, s31
	s_mov_b32 m0, s26
	ds_read_b128 v[204:207], v187 offset:49152
	ds_read_b128 v[208:211], v187 offset:50176
	ds_read_b128 v[212:215], v187 offset:51200
	ds_read_b128 v[216:219], v187 offset:52224
	ds_read_b128 v[220:223], v187 offset:53248
	ds_read_b128 v[224:227], v187 offset:54272
	ds_read_b128 v[228:231], v187 offset:55296
	ds_read_b128 v[232:235], v187 offset:56320
	s_add_u32 vcc_lo, s24, 0x80
	s_addc_u32 vcc_hi, s25, 0
	global_load_lds_dwordx4 v2, vcc
	s_add_i32 m0, s26, 0x2000
	s_add_u32 s24, s24, 0x80080
	s_addc_u32 s25, s25, 0
	s_add_i32 s26, s66, s31
	s_add_u32 vcc_lo, s24, 0xfff80000
	s_addc_u32 vcc_hi, s25, -1
	global_load_lds_dwordx4 v152, vcc
	s_mov_b32 m0, s26
	s_nop 0
	global_load_lds_dwordx4 v2, s[24:25]
	s_add_i32 m0, s26, 0x2000
	s_nop 0
	global_load_lds_dwordx4 v152, s[24:25]
	v_lshl_add_u64 v[166:167], v[238:239], 0, s[36:37]
	s_mov_b32 m0, s44
	s_nop 0
	global_load_lds_dwordx4 v[166:167], off
	v_lshl_add_u64 v[166:167], v[240:241], 0, s[36:37]
	s_mov_b32 m0, s45
	s_nop 0
	global_load_lds_dwordx4 v[166:167], off
	s_waitcnt vmcnt(8)
	s_waitcnt lgkmcnt(0)
	s_barrier
	s_setprio 1
	v_mfma_f32_16x16x32_bf16 v[64:67], v[132:135], v[204:207], v[64:67]
	v_mfma_f32_16x16x32_bf16 v[60:63], v[158:161], v[204:207], v[60:63]
	v_mfma_f32_16x16x32_bf16 v[48:51], v[132:135], v[212:215], v[48:51]
	v_mfma_f32_16x16x32_bf16 v[44:47], v[158:161], v[212:215], v[44:47]
	v_mfma_f32_16x16x32_bf16 v[32:35], v[132:135], v[220:223], v[32:35]
	v_mfma_f32_16x16x32_bf16 v[28:31], v[158:161], v[220:223], v[28:31]
	v_mfma_f32_16x16x32_bf16 v[16:19], v[132:135], v[228:231], v[16:19]
	v_mfma_f32_16x16x32_bf16 v[12:15], v[158:161], v[228:231], v[12:15]
	v_mfma_f32_16x16x32_bf16 v[64:67], v[136:139], v[208:211], v[64:67]
	v_mfma_f32_16x16x32_bf16 v[60:63], v[162:165], v[208:211], v[60:63]
	v_mfma_f32_16x16x32_bf16 v[48:51], v[136:139], v[216:219], v[48:51]
	v_mfma_f32_16x16x32_bf16 v[44:47], v[162:165], v[216:219], v[44:47]
	v_mfma_f32_16x16x32_bf16 v[32:35], v[136:139], v[224:227], v[32:35]
	v_mfma_f32_16x16x32_bf16 v[28:31], v[162:165], v[224:227], v[28:31]
	v_mfma_f32_16x16x32_bf16 v[16:19], v[136:139], v[232:235], v[16:19]
	v_mfma_f32_16x16x32_bf16 v[12:15], v[162:165], v[232:235], v[12:15]
	v_mfma_f32_16x16x32_bf16 v[56:59], v[188:191], v[204:207], v[56:59]
	v_mfma_f32_16x16x32_bf16 v[52:55], v[196:199], v[204:207], v[52:55]
	v_mfma_f32_16x16x32_bf16 v[40:43], v[188:191], v[212:215], v[40:43]
	v_mfma_f32_16x16x32_bf16 v[36:39], v[196:199], v[212:215], v[36:39]
	v_mfma_f32_16x16x32_bf16 v[24:27], v[188:191], v[220:223], v[24:27]
	v_mfma_f32_16x16x32_bf16 v[20:23], v[196:199], v[220:223], v[20:23]
	v_mfma_f32_16x16x32_bf16 v[8:11], v[188:191], v[228:231], v[8:11]
	v_mfma_f32_16x16x32_bf16 v[4:7], v[196:199], v[228:231], v[4:7]
	v_mfma_f32_16x16x32_bf16 v[56:59], v[192:195], v[208:211], v[56:59]
	v_mfma_f32_16x16x32_bf16 v[52:55], v[200:203], v[208:211], v[52:55]
	v_mfma_f32_16x16x32_bf16 v[40:43], v[192:195], v[216:219], v[40:43]
	v_mfma_f32_16x16x32_bf16 v[36:39], v[200:203], v[216:219], v[36:39]
	v_mfma_f32_16x16x32_bf16 v[24:27], v[192:195], v[224:227], v[24:27]
	v_mfma_f32_16x16x32_bf16 v[20:23], v[200:203], v[224:227], v[20:23]
	v_mfma_f32_16x16x32_bf16 v[8:11], v[192:195], v[232:235], v[8:11]
	v_mfma_f32_16x16x32_bf16 v[4:7], v[200:203], v[232:235], v[4:7]
	s_setprio 0
	s_barrier
	s_add_i32 s64, s64, 2
	s_add_u32 s22, s22, 0x100
	s_addc_u32 s23, s23, 0
	s_add_u32 s57, s57, 0x100
	s_addc_u32 s63, s63, 0
	s_cmp_gt_u32 s64, 29
.LBB0_483:
	s_add_u32 s24, s22, 0xfff80080
	s_addc_u32 s25, s23, -1
	s_add_i32 s65, 0, 0x10000
	s_cmp_eq_u32 s64, 28
	s_cselect_b32 s27, s13, s25
	s_cselect_b32 s26, s19, s24
	s_cselect_b32 s25, s11, s63
	s_cselect_b32 s24, s56, s57
	s_add_i32 s76, 0, 0x14000
	v_add_u32_e32 v162, s65, v185
	v_add_u32_e32 v166, s76, v185
	ds_read_b128 v[132:135], v162
	ds_read_b128 v[136:139], v162 offset:1024
	ds_read_b128 v[158:161], v162 offset:2048
	ds_read_b128 v[162:165], v162 offset:3072
	ds_read_b128 v[188:191], v166
	ds_read_b128 v[192:195], v166 offset:1024
	ds_read_b128 v[196:199], v166 offset:2048
	ds_read_b128 v[200:203], v166 offset:3072
	s_add_i32 m0, s21, 0xc000
	ds_read_b128 v[204:207], v187
	ds_read_b128 v[208:211], v187 offset:1024
	ds_read_b128 v[212:215], v187 offset:2048
	ds_read_b128 v[216:219], v187 offset:3072
	ds_read_b128 v[220:223], v187 offset:4096
	ds_read_b128 v[224:227], v187 offset:5120
	ds_read_b128 v[228:231], v187 offset:6144
	ds_read_b128 v[232:235], v187 offset:7168
	global_load_lds_dwordx4 v154, s[22:23]
	s_add_i32 m0, s21, 0xe000
	s_nop 0
	global_load_lds_dwordx4 v156, s[22:23]
	s_waitcnt vmcnt(8)
	s_waitcnt lgkmcnt(0)
	s_barrier
; #define PG8_STAGE(bufoff, gbase, voff) do { _Pragma("unroll") for (int _i = 0; _i < 2; ++_i) \
;         __builtin_amdgcn_global_load_lds((const unsigned*)((const char*)(gbase) + (voff)[_i]), (PG8_LAS unsigned*)(lds + (bufoff) + ldsw + _i * 8192), 16, 0, 0); } while (0)
; #define PG8_LDA(dst, b, h) do { _Pragma("unroll") for (int m = 0; m < 4; ++m) _Pragma("unroll") for (int k = 0; k < 2; ++k) dst[m][k] = *(const PG8_LAS bf16x8*)(lds + PG8_SA(b, h) + aoff + m * 2048 + k * 1024); } while (0)
; #define PG8_LDB(dst, b, h) do { _Pragma("unroll") for (int n = 0; n < 2; ++n) _Pragma("unroll") for (int k = 0; k < 2; ++k) dst[n][k] = *(const PG8_LAS bf16x8*)(lds + PG8_SB(b, h) + boff + n * 2048 + k * 1024); } while (0)
; #define PG8_MMA(ai, bj, At, Bt) do { __builtin_amdgcn_s_setprio(1); _Pragma("unroll") for (int m = 0; m < 4; ++m) _Pragma("unroll") for (int n = 0; n < 2; ++n) _Pragma("unroll") for (int k = 0; k < 2; ++k) \
;         acc[ai][bj][m][n] = __builtin_amdgcn_mfma_f32_16x16x32_bf16(Bt[n][k], At[m][k], acc[ai][bj][m][n], 0, 0, 0); __builtin_amdgcn_s_setprio(0); } while (0)
; #define PG8_WAIT_V(n) asm volatile("s_waitcnt vmcnt(" #n ")" ::: "memory")
; #define PG8_WAIT_L(n) asm volatile("s_waitcnt lgkmcnt(" #n ")" ::: "memory")
; #define PG8_BAR __builtin_amdgcn_s_barrier()
; #define PG8_SCHED __builtin_amdgcn_sched_barrier(0)
; template <class Epi, class Sched, bool ALIGN_EPI = false, bool SP2 = false>
; __device__ __forceinline__ void gemm_phase(PG8_LAS unsigned char* lds, const Gemm g, const Sched& S, const Epi& E) {
;     ...
;             PG8_LDB(B0, 0, 0); PG8_LDB(B1, 0, 1); PG8_SCHED; PG8_LDA(At, 0, 0); PG8_STAGE(PG8_SA(1, 1), a1 + hstep, voffA);
;             PG8_WAIT_V(8); PG8_WAIT_L(0); PG8_BAR; PG8_MMA(0, 0, At, B0); PG8_MMA(0, 1, At, B1); PG8_BAR; PG8_SCHED;
;             PG8_LDA(At, 0, 1); PG8_STAGE(PG8_SB(0, 0), b2, voffB); PG8_STAGE(PG8_SB(0, 1), b2 + hstep, voffB); PG8_STAGE(PG8_SA(0, 0), a2, voffA);
;             PG8_WAIT_V(8); PG8_WAIT_L(0); PG8_BAR; PG8_MMA(1, 0, At, B0); PG8_MMA(1, 1, At, B1); PG8_BAR; PG8_SCHED;
	s_setprio 1
	v_mfma_f32_16x16x32_bf16 v[128:131], v[132:135], v[204:207], v[128:131]
	v_mfma_f32_16x16x32_bf16 v[124:127], v[158:161], v[204:207], v[124:127]
	v_mfma_f32_16x16x32_bf16 v[112:115], v[132:135], v[212:215], v[112:115]
	v_mfma_f32_16x16x32_bf16 v[108:111], v[158:161], v[212:215], v[108:111]
	v_mfma_f32_16x16x32_bf16 v[96:99], v[132:135], v[220:223], v[96:99]
	v_mfma_f32_16x16x32_bf16 v[92:95], v[158:161], v[220:223], v[92:95]
	v_mfma_f32_16x16x32_bf16 v[80:83], v[132:135], v[228:231], v[80:83]
	v_mfma_f32_16x16x32_bf16 v[76:79], v[158:161], v[228:231], v[76:79]
	v_mfma_f32_16x16x32_bf16 v[128:131], v[136:139], v[208:211], v[128:131]
	v_mfma_f32_16x16x32_bf16 v[124:127], v[162:165], v[208:211], v[124:127]
	v_mfma_f32_16x16x32_bf16 v[112:115], v[136:139], v[216:219], v[112:115]
	v_mfma_f32_16x16x32_bf16 v[108:111], v[162:165], v[216:219], v[108:111]
	v_mfma_f32_16x16x32_bf16 v[96:99], v[136:139], v[224:227], v[96:99]
	v_mfma_f32_16x16x32_bf16 v[92:95], v[162:165], v[224:227], v[92:95]
	v_mfma_f32_16x16x32_bf16 v[80:83], v[136:139], v[232:235], v[80:83]
	v_mfma_f32_16x16x32_bf16 v[76:79], v[162:165], v[232:235], v[76:79]
	v_mfma_f32_16x16x32_bf16 v[120:123], v[188:191], v[204:207], v[120:123]
	v_mfma_f32_16x16x32_bf16 v[116:119], v[196:199], v[204:207], v[116:119]
	v_mfma_f32_16x16x32_bf16 v[104:107], v[188:191], v[212:215], v[104:107]
	v_mfma_f32_16x16x32_bf16 v[100:103], v[196:199], v[212:215], v[100:103]
	v_mfma_f32_16x16x32_bf16 v[88:91], v[188:191], v[220:223], v[88:91]
	v_mfma_f32_16x16x32_bf16 v[84:87], v[196:199], v[220:223], v[84:87]
	v_mfma_f32_16x16x32_bf16 v[72:75], v[188:191], v[228:231], v[72:75]
	v_mfma_f32_16x16x32_bf16 v[68:71], v[196:199], v[228:231], v[68:71]
	v_mfma_f32_16x16x32_bf16 v[120:123], v[192:195], v[208:211], v[120:123]
	v_mfma_f32_16x16x32_bf16 v[116:119], v[200:203], v[208:211], v[116:119]
	v_mfma_f32_16x16x32_bf16 v[104:107], v[192:195], v[216:219], v[104:107]
	v_mfma_f32_16x16x32_bf16 v[100:103], v[200:203], v[216:219], v[100:103]
	v_mfma_f32_16x16x32_bf16 v[88:91], v[192:195], v[224:227], v[88:91]
	v_mfma_f32_16x16x32_bf16 v[84:87], v[200:203], v[224:227], v[84:87]
	v_mfma_f32_16x16x32_bf16 v[72:75], v[192:195], v[232:235], v[72:75]
	v_mfma_f32_16x16x32_bf16 v[68:71], v[200:203], v[232:235], v[68:71]
	s_setprio 0
	s_barrier
	s_add_i32 s65, s65, s31
	s_mov_b32 m0, s65
	ds_read_b128 v[204:207], v187 offset:16384
	ds_read_b128 v[208:211], v187 offset:17408
	ds_read_b128 v[212:215], v187 offset:18432
	ds_read_b128 v[216:219], v187 offset:19456
	ds_read_b128 v[220:223], v187 offset:20480
	ds_read_b128 v[224:227], v187 offset:21504
	ds_read_b128 v[228:231], v187 offset:22528
	ds_read_b128 v[232:235], v187 offset:23552
	global_load_lds_dwordx4 v2, s[24:25]
	s_add_i32 m0, s65, 0x2000
	s_add_u32 s66, s24, 0x80000
	s_addc_u32 s67, s25, 0
	s_add_i32 s65, s76, s31
	global_load_lds_dwordx4 v152, s[24:25]
	s_mov_b32 m0, s65
	v_lshl_add_u64 v[240:241], s[26:27], 0, v[150:151]
	global_load_lds_dwordx4 v2, s[66:67]
	s_add_i32 m0, s65, 0x2000
	s_nop 0
	global_load_lds_dwordx4 v152, s[66:67]
	v_lshl_add_u64 v[238:239], s[26:27], 0, v[0:1]
	s_mov_b32 m0, s21
	s_nop 0
	global_load_lds_dwordx4 v[238:239], off
	s_mov_b32 m0, s34
	s_nop 0
	global_load_lds_dwordx4 v[240:241], off
	s_waitcnt vmcnt(8)
	s_waitcnt lgkmcnt(0)
	s_barrier
	s_setprio 1
	v_mfma_f32_16x16x32_bf16 v[64:67], v[132:135], v[204:207], v[64:67]
	v_mfma_f32_16x16x32_bf16 v[60:63], v[158:161], v[204:207], v[60:63]
	v_mfma_f32_16x16x32_bf16 v[48:51], v[132:135], v[212:215], v[48:51]
	v_mfma_f32_16x16x32_bf16 v[44:47], v[158:161], v[212:215], v[44:47]
	v_mfma_f32_16x16x32_bf16 v[32:35], v[132:135], v[220:223], v[32:35]
	v_mfma_f32_16x16x32_bf16 v[28:31], v[158:161], v[220:223], v[28:31]
	v_mfma_f32_16x16x32_bf16 v[16:19], v[132:135], v[228:231], v[16:19]
	v_mfma_f32_16x16x32_bf16 v[12:15], v[158:161], v[228:231], v[12:15]
	v_mfma_f32_16x16x32_bf16 v[64:67], v[136:139], v[208:211], v[64:67]
	v_mfma_f32_16x16x32_bf16 v[60:63], v[162:165], v[208:211], v[60:63]
	v_mfma_f32_16x16x32_bf16 v[48:51], v[136:139], v[216:219], v[48:51]
	v_mfma_f32_16x16x32_bf16 v[44:47], v[162:165], v[216:219], v[44:47]
	v_mfma_f32_16x16x32_bf16 v[32:35], v[136:139], v[224:227], v[32:35]
	v_mfma_f32_16x16x32_bf16 v[28:31], v[162:165], v[224:227], v[28:31]
	v_mfma_f32_16x16x32_bf16 v[16:19], v[136:139], v[232:235], v[16:19]
	v_mfma_f32_16x16x32_bf16 v[12:15], v[162:165], v[232:235], v[12:15]
	v_mfma_f32_16x16x32_bf16 v[56:59], v[188:191], v[204:207], v[56:59]
	v_mfma_f32_16x16x32_bf16 v[52:55], v[196:199], v[204:207], v[52:55]
	v_mfma_f32_16x16x32_bf16 v[40:43], v[188:191], v[212:215], v[40:43]
	v_mfma_f32_16x16x32_bf16 v[36:39], v[196:199], v[212:215], v[36:39]
	v_mfma_f32_16x16x32_bf16 v[24:27], v[188:191], v[220:223], v[24:27]
	v_mfma_f32_16x16x32_bf16 v[20:23], v[196:199], v[220:223], v[20:23]
	v_mfma_f32_16x16x32_bf16 v[8:11], v[188:191], v[228:231], v[8:11]
	v_mfma_f32_16x16x32_bf16 v[4:7], v[196:199], v[228:231], v[4:7]
	v_mfma_f32_16x16x32_bf16 v[56:59], v[192:195], v[208:211], v[56:59]
	v_mfma_f32_16x16x32_bf16 v[52:55], v[200:203], v[208:211], v[52:55]
	v_mfma_f32_16x16x32_bf16 v[40:43], v[192:195], v[216:219], v[40:43]
	v_mfma_f32_16x16x32_bf16 v[36:39], v[200:203], v[216:219], v[36:39]
	v_mfma_f32_16x16x32_bf16 v[24:27], v[192:195], v[224:227], v[24:27]
	v_mfma_f32_16x16x32_bf16 v[20:23], v[200:203], v[224:227], v[20:23]
	v_mfma_f32_16x16x32_bf16 v[8:11], v[192:195], v[232:235], v[8:11]
	v_mfma_f32_16x16x32_bf16 v[4:7], v[200:203], v[232:235], v[4:7]
	s_setprio 0
	s_barrier
; #define PG8_STAGE(bufoff, gbase, voff) do { _Pragma("unroll") for (int _i = 0; _i < 2; ++_i) \
;         __builtin_amdgcn_global_load_lds((const unsigned*)((const char*)(gbase) + (voff)[_i]), (PG8_LAS unsigned*)(lds + (bufoff) + ldsw + _i * 8192), 16, 0, 0); } while (0)
; #define PG8_LDA(dst, b, h) do { _Pragma("unroll") for (int m = 0; m < 4; ++m) _Pragma("unroll") for (int k = 0; k < 2; ++k) dst[m][k] = *(const PG8_LAS bf16x8*)(lds + PG8_SA(b, h) + aoff + m * 2048 + k * 1024); } while (0)
; #define PG8_LDB(dst, b, h) do { _Pragma("unroll") for (int n = 0; n < 2; ++n) _Pragma("unroll") for (int k = 0; k < 2; ++k) dst[n][k] = *(const PG8_LAS bf16x8*)(lds + PG8_SB(b, h) + boff + n * 2048 + k * 1024); } while (0)
; #define PG8_MMA(ai, bj, At, Bt) do { __builtin_amdgcn_s_setprio(1); _Pragma("unroll") for (int m = 0; m < 4; ++m) _Pragma("unroll") for (int n = 0; n < 2; ++n) _Pragma("unroll") for (int k = 0; k < 2; ++k) \
;         acc[ai][bj][m][n] = __builtin_amdgcn_mfma_f32_16x16x32_bf16(Bt[n][k], At[m][k], acc[ai][bj][m][n], 0, 0, 0); __builtin_amdgcn_s_setprio(0); } while (0)
; #define PG8_WAIT_V(n) asm volatile("s_waitcnt vmcnt(" #n ")" ::: "memory")
; #define PG8_WAIT_L(n) asm volatile("s_waitcnt lgkmcnt(" #n ")" ::: "memory")
; #define PG8_BAR __builtin_amdgcn_s_barrier()
; #define PG8_SCHED __builtin_amdgcn_sched_barrier(0)
; template <class Epi, class Sched, bool ALIGN_EPI = false, bool SP2 = false>
; __device__ __forceinline__ void gemm_phase(PG8_LAS unsigned char* lds, const Gemm g, const Sched& S, const Epi& E) {
;     ...
;             PG8_LDB(B0, 1, 0); PG8_LDB(B1, 1, 1); PG8_SCHED; PG8_LDA(At, 1, 0); PG8_STAGE(PG8_SA(0, 1), a2 + hstep, voffA);
;             PG8_WAIT_V(8); PG8_WAIT_L(0); PG8_BAR; PG8_MMA(0, 0, At, B0); PG8_MMA(0, 1, At, B1); PG8_BAR; PG8_SCHED;
;             PG8_LDA(At, 1, 1); PG8_STAGE(PG8_SB(1, 0), b3, voffB); PG8_STAGE(PG8_SB(1, 1), b3 + hstep, voffB); PG8_STAGE(PG8_SA(1, 0), a3, voffA);
;             PG8_WAIT_V(8); PG8_WAIT_L(0); PG8_BAR; PG8_MMA(1, 0, At, B0); PG8_MMA(1, 1, At, B1); PG8_BAR; PG8_SCHED;
;     ...
;         if constexpr (ALIGN_EPI) { if (wr == 0) PG8_BAR; }
	s_add_i32 s65, 0, 0x18000
	s_add_i32 s66, 0, 0x1c000
	v_add_u32_e32 v162, s65, v185
	v_add_u32_e32 v200, s66, v185
	ds_read_b128 v[132:135], v162
	ds_read_b128 v[136:139], v162 offset:1024
	ds_read_b128 v[158:161], v162 offset:2048
	ds_read_b128 v[162:165], v162 offset:3072
	ds_read_b128 v[188:191], v200
	ds_read_b128 v[192:195], v200 offset:1024
	ds_read_b128 v[196:199], v200 offset:2048
	ds_read_b128 v[200:203], v200 offset:3072
	s_add_u32 s26, s26, 0x80000
	s_addc_u32 s27, s27, 0
	s_mov_b32 m0, s35
	ds_read_b128 v[204:207], v187 offset:32768
	ds_read_b128 v[208:211], v187 offset:33792
	ds_read_b128 v[212:215], v187 offset:34816
	ds_read_b128 v[216:219], v187 offset:35840
	ds_read_b128 v[220:223], v187 offset:36864
	ds_read_b128 v[224:227], v187 offset:37888
	ds_read_b128 v[228:231], v187 offset:38912
	ds_read_b128 v[232:235], v187 offset:39936
	global_load_lds_dwordx4 v0, s[26:27]
	s_mov_b32 m0, s42
	s_nop 0
	global_load_lds_dwordx4 v150, s[26:27]
	s_waitcnt vmcnt(8)
	s_waitcnt lgkmcnt(0)
	s_barrier
	s_setprio 1
	v_mfma_f32_16x16x32_bf16 v[128:131], v[132:135], v[204:207], v[128:131]
	v_mfma_f32_16x16x32_bf16 v[124:127], v[158:161], v[204:207], v[124:127]
	v_mfma_f32_16x16x32_bf16 v[112:115], v[132:135], v[212:215], v[112:115]
	v_mfma_f32_16x16x32_bf16 v[108:111], v[158:161], v[212:215], v[108:111]
	v_mfma_f32_16x16x32_bf16 v[96:99], v[132:135], v[220:223], v[96:99]
	v_mfma_f32_16x16x32_bf16 v[92:95], v[158:161], v[220:223], v[92:95]
	v_mfma_f32_16x16x32_bf16 v[80:83], v[132:135], v[228:231], v[80:83]
	v_mfma_f32_16x16x32_bf16 v[76:79], v[158:161], v[228:231], v[76:79]
	v_mfma_f32_16x16x32_bf16 v[128:131], v[136:139], v[208:211], v[128:131]
	v_mfma_f32_16x16x32_bf16 v[124:127], v[162:165], v[208:211], v[124:127]
	v_mfma_f32_16x16x32_bf16 v[112:115], v[136:139], v[216:219], v[112:115]
	v_mfma_f32_16x16x32_bf16 v[108:111], v[162:165], v[216:219], v[108:111]
	v_mfma_f32_16x16x32_bf16 v[96:99], v[136:139], v[224:227], v[96:99]
	v_mfma_f32_16x16x32_bf16 v[92:95], v[162:165], v[224:227], v[92:95]
	v_mfma_f32_16x16x32_bf16 v[80:83], v[136:139], v[232:235], v[80:83]
	v_mfma_f32_16x16x32_bf16 v[76:79], v[162:165], v[232:235], v[76:79]
	v_mfma_f32_16x16x32_bf16 v[120:123], v[188:191], v[204:207], v[120:123]
	v_mfma_f32_16x16x32_bf16 v[116:119], v[196:199], v[204:207], v[116:119]
	v_mfma_f32_16x16x32_bf16 v[104:107], v[188:191], v[212:215], v[104:107]
	v_mfma_f32_16x16x32_bf16 v[100:103], v[196:199], v[212:215], v[100:103]
	v_mfma_f32_16x16x32_bf16 v[88:91], v[188:191], v[220:223], v[88:91]
	v_mfma_f32_16x16x32_bf16 v[84:87], v[196:199], v[220:223], v[84:87]
	v_mfma_f32_16x16x32_bf16 v[72:75], v[188:191], v[228:231], v[72:75]
	v_mfma_f32_16x16x32_bf16 v[68:71], v[196:199], v[228:231], v[68:71]
	v_mfma_f32_16x16x32_bf16 v[120:123], v[192:195], v[208:211], v[120:123]
	v_mfma_f32_16x16x32_bf16 v[116:119], v[200:203], v[208:211], v[116:119]
	v_mfma_f32_16x16x32_bf16 v[104:107], v[192:195], v[216:219], v[104:107]
	v_mfma_f32_16x16x32_bf16 v[100:103], v[200:203], v[216:219], v[100:103]
	v_mfma_f32_16x16x32_bf16 v[88:91], v[192:195], v[224:227], v[88:91]
	v_mfma_f32_16x16x32_bf16 v[84:87], v[200:203], v[224:227], v[84:87]
	v_mfma_f32_16x16x32_bf16 v[72:75], v[192:195], v[232:235], v[72:75]
	v_mfma_f32_16x16x32_bf16 v[68:71], v[200:203], v[232:235], v[68:71]
	s_setprio 0
	s_barrier
	s_add_i32 s26, s65, s31
	s_mov_b32 m0, s26
	ds_read_b128 v[204:207], v187 offset:49152
	ds_read_b128 v[208:211], v187 offset:50176
	ds_read_b128 v[212:215], v187 offset:51200
	ds_read_b128 v[216:219], v187 offset:52224
	ds_read_b128 v[220:223], v187 offset:53248
	ds_read_b128 v[224:227], v187 offset:54272
	ds_read_b128 v[228:231], v187 offset:55296
	ds_read_b128 v[232:235], v187 offset:56320
	s_add_u32 vcc_lo, s24, 0x80
	s_addc_u32 vcc_hi, s25, 0
	global_load_lds_dwordx4 v2, vcc
	s_add_i32 m0, s26, 0x2000
	s_add_u32 s24, s24, 0x80080
	s_addc_u32 s25, s25, 0
	s_add_i32 s26, s66, s31
	s_add_u32 vcc_lo, s24, 0xfff80000
	s_addc_u32 vcc_hi, s25, -1
	global_load_lds_dwordx4 v152, vcc
	s_mov_b32 m0, s26
	s_nop 0
	global_load_lds_dwordx4 v2, s[24:25]
	s_add_i32 m0, s26, 0x2000
	s_nop 0
	global_load_lds_dwordx4 v152, s[24:25]
	v_lshl_add_u64 v[166:167], v[238:239], 0, s[36:37]
	s_mov_b32 m0, s44
	s_nop 0
	global_load_lds_dwordx4 v[166:167], off
	v_lshl_add_u64 v[166:167], v[240:241], 0, s[36:37]
	s_mov_b32 m0, s45
	s_nop 0
	global_load_lds_dwordx4 v[166:167], off
	s_waitcnt vmcnt(8)
	s_waitcnt lgkmcnt(0)
	s_barrier
	s_setprio 1
	v_mfma_f32_16x16x32_bf16 v[64:67], v[132:135], v[204:207], v[64:67]
	v_mfma_f32_16x16x32_bf16 v[60:63], v[158:161], v[204:207], v[60:63]
	v_mfma_f32_16x16x32_bf16 v[48:51], v[132:135], v[212:215], v[48:51]
	v_mfma_f32_16x16x32_bf16 v[44:47], v[158:161], v[212:215], v[44:47]
	v_mfma_f32_16x16x32_bf16 v[32:35], v[132:135], v[220:223], v[32:35]
	v_mfma_f32_16x16x32_bf16 v[28:31], v[158:161], v[220:223], v[28:31]
	v_mfma_f32_16x16x32_bf16 v[16:19], v[132:135], v[228:231], v[16:19]
	v_mfma_f32_16x16x32_bf16 v[12:15], v[158:161], v[228:231], v[12:15]
	v_mfma_f32_16x16x32_bf16 v[64:67], v[136:139], v[208:211], v[64:67]
	v_mfma_f32_16x16x32_bf16 v[60:63], v[162:165], v[208:211], v[60:63]
	v_mfma_f32_16x16x32_bf16 v[48:51], v[136:139], v[216:219], v[48:51]
	v_mfma_f32_16x16x32_bf16 v[44:47], v[162:165], v[216:219], v[44:47]
	v_mfma_f32_16x16x32_bf16 v[32:35], v[136:139], v[224:227], v[32:35]
	v_mfma_f32_16x16x32_bf16 v[28:31], v[162:165], v[224:227], v[28:31]
	v_mfma_f32_16x16x32_bf16 v[16:19], v[136:139], v[232:235], v[16:19]
	v_mfma_f32_16x16x32_bf16 v[12:15], v[162:165], v[232:235], v[12:15]
	v_mfma_f32_16x16x32_bf16 v[56:59], v[188:191], v[204:207], v[56:59]
	v_mfma_f32_16x16x32_bf16 v[52:55], v[196:199], v[204:207], v[52:55]
	v_mfma_f32_16x16x32_bf16 v[40:43], v[188:191], v[212:215], v[40:43]
	v_mfma_f32_16x16x32_bf16 v[36:39], v[196:199], v[212:215], v[36:39]
	v_mfma_f32_16x16x32_bf16 v[24:27], v[188:191], v[220:223], v[24:27]
	v_mfma_f32_16x16x32_bf16 v[20:23], v[196:199], v[220:223], v[20:23]
	v_mfma_f32_16x16x32_bf16 v[8:11], v[188:191], v[228:231], v[8:11]
	v_mfma_f32_16x16x32_bf16 v[4:7], v[196:199], v[228:231], v[4:7]
	v_mfma_f32_16x16x32_bf16 v[56:59], v[192:195], v[208:211], v[56:59]
	v_mfma_f32_16x16x32_bf16 v[52:55], v[200:203], v[208:211], v[52:55]
	v_mfma_f32_16x16x32_bf16 v[40:43], v[192:195], v[216:219], v[40:43]
	v_mfma_f32_16x16x32_bf16 v[36:39], v[200:203], v[216:219], v[36:39]
	v_mfma_f32_16x16x32_bf16 v[24:27], v[192:195], v[224:227], v[24:27]
	v_mfma_f32_16x16x32_bf16 v[20:23], v[200:203], v[224:227], v[20:23]
	v_mfma_f32_16x16x32_bf16 v[8:11], v[192:195], v[232:235], v[8:11]
	v_mfma_f32_16x16x32_bf16 v[4:7], v[200:203], v[232:235], v[4:7]
	s_setprio 0
	s_barrier
	s_add_i32 s64, s64, 2
	s_add_u32 s22, s22, 0x100
	s_addc_u32 s23, s23, 0
	s_add_u32 s57, s57, 0x100
	s_addc_u32 s63, s63, 0
	s_cmp_gt_u32 s64, 29
	s_cbranch_scc0 .LBB0_483
	s_and_b64 vcc, exec, s[8:9]
	s_cbranch_vccz .LBB0_486
	s_barrier

; #define PG8_STAGE(bufoff, gbase, voff) do { _Pragma("unroll") for (int _i = 0; _i < 2; ++_i) \
;         __builtin_amdgcn_global_load_lds((const unsigned*)((const char*)(gbase) + (voff)[_i]), (PG8_LAS unsigned*)(lds + (bufoff) + ldsw + _i * 8192), 16, 0, 0); } while (0)
; #define PG8_LDA(dst, b, h) do { _Pragma("unroll") for (int m = 0; m < 4; ++m) _Pragma("unroll") for (int k = 0; k < 2; ++k) dst[m][k] = *(const PG8_LAS bf16x8*)(lds + PG8_SA(b, h) + aoff + m * 2048 + k * 1024); } while (0)
; #define PG8_LDB(dst, b, h) do { _Pragma("unroll") for (int n = 0; n < 2; ++n) _Pragma("unroll") for (int k = 0; k < 2; ++k) dst[n][k] = *(const PG8_LAS bf16x8*)(lds + PG8_SB(b, h) + boff + n * 2048 + k * 1024); } while (0)
; #define PG8_WAIT_V(n) asm volatile("s_waitcnt vmcnt(" #n ")" ::: "memory")
; #define PG8_WAIT_L(n) asm volatile("s_waitcnt lgkmcnt(" #n ")" ::: "memory")
; #define PG8_BAR __builtin_amdgcn_s_barrier()
; #define PG8_SCHED __builtin_amdgcn_sched_barrier(0)
; template <class Epi, class Sched, bool ALIGN_EPI = false, bool SP2 = false>
; __device__ __forceinline__ void gemm_phase(PG8_LAS unsigned char* lds, const Gemm g, const Sched& S, const Epi& E) {
;     ...
;         const bool has_next = S.next(ui + 1, nxt);
;         const char* nA = has_next ? (const char*)g.A + (size_t)nxt.pm * tstep : cA; const char* nB = has_next ? (const char*)g.Bt + (size_t)nxt.pn * tstep : cB;
;         for (int t = 0; t < nt; t += 2) {
;             const bool last = (t == nt - 2);
;             const char* a1 = cA + (size_t)(t + 1) * kstep;
;             const char* a2 = last ? nA : cA + (size_t)(t + 2) * kstep; const char* b2 = last ? nB : cB + (size_t)(t + 2) * kstep;
;             const char* a3 = a2 + kstep; const char* b3 = b2 + kstep;
;             if (last && has_next) S.a_ready(nxt);
;             if constexpr (SP2) {
;             PG8_LDB(B0, 0, 0); PG8_LDB(B1, 0, 1); PG8_SCHED; PG8_LDA(At, 0, 0); PG8_STAGE(PG8_SA(1, 1), a1 + hstep, voffA);
;             PG8_WAIT_V(8); PG8_WAIT_L(0); PG8_BAR; PG8_MMA(0, 0, At, B0); PG8_MMA(0, 1, At, B1); PG8_BAR; PG8_SCHED;
;             PG8_LDA(At, 0, 1); PG8_STAGE(PG8_SB(0, 0), b2, voffB); PG8_STAGE(PG8_SB(0, 1), b2 + hstep, voffB); PG8_STAGE(PG8_SA(0, 0), a2, voffA);
;             PG8_WAIT_V(8); PG8_WAIT_L(0); PG8_BAR; PG8_MMA(1, 0, At, B0); PG8_MMA(1, 1, At, B1); PG8_BAR; PG8_SCHED;
.LBB0_566:
	s_ashr_i32 s11, s10, 31
	s_lshl_b64 s[12:13], s[10:11], 20
	s_add_u32 s12, s46, s12
	s_addc_u32 s13, s47, s13
	s_and_b64 s[14:15], s[2:3], exec
	s_cselect_b32 s11, s13, s19
	s_cselect_b32 s45, s12, s18
	s_ashr_i32 s9, s8, 31
	s_lshl_b64 s[14:15], s[8:9], 20
	s_add_u32 s14, s25, s14
	s_addc_u32 s15, s26, s15
	s_and_b64 s[22:23], s[2:3], exec
	s_cselect_b32 s9, s15, s21
	s_cselect_b32 s50, s14, s20
	s_add_u32 s18, s18, 0x80080
	s_addc_u32 s19, s19, 0
	s_add_u32 s51, s20, 0x100
	s_addc_u32 s56, s21, 0
	s_mov_b32 s57, -2
	s_add_u32 s20, s18, 0xfff80080
	s_addc_u32 s21, s19, -1
	s_add_i32 s63, 0, 0x10000
	s_cmp_eq_u32 s57, 28
	s_cselect_b32 s23, s11, s21
	s_cselect_b32 s22, s45, s20
	v_add_u32_e32 v150, s63, v153
	s_cselect_b32 s21, s9, s56
	s_cselect_b32 s20, s50, s51
	s_add_i32 s66, 0, 0x14000
	ds_read_b128 v[184:187], v150
	ds_read_b128 v[188:191], v150 offset:1024
	ds_read_b128 v[192:195], v150 offset:2048
	ds_read_b128 v[196:199], v150 offset:3072
	v_add_u32_e32 v150, s66, v153
	ds_read_b128 v[200:203], v150
	ds_read_b128 v[204:207], v150 offset:1024
	ds_read_b128 v[208:211], v150 offset:2048
	ds_read_b128 v[212:215], v150 offset:3072
	s_add_i32 m0, s29, 0xc000
	ds_read_b128 v[216:219], v155
	ds_read_b128 v[220:223], v155 offset:1024
	ds_read_b128 v[224:227], v155 offset:2048
	ds_read_b128 v[228:231], v155 offset:3072
	ds_read_b128 v[232:235], v155 offset:4096
	ds_read_b128 v[236:239], v155 offset:5120
	ds_read_b128 v[240:243], v155 offset:6144
	ds_read_b128 v[244:247], v155 offset:7168
	global_load_lds_dwordx4 v136, s[18:19]
	s_add_i32 m0, s29, 0xe000
	s_nop 0
	global_load_lds_dwordx4 v138, s[18:19]
	s_waitcnt vmcnt(8)
	s_waitcnt lgkmcnt(0)
	s_barrier
	s_setprio 1
	v_mfma_f32_16x16x32_bf16 v[128:131], v[184:187], v[216:219], 0
	v_mfma_f32_16x16x32_bf16 v[120:123], v[192:195], v[216:219], 0
	v_mfma_f32_16x16x32_bf16 v[112:115], v[184:187], v[224:227], 0
	v_mfma_f32_16x16x32_bf16 v[104:107], v[192:195], v[224:227], 0
	v_mfma_f32_16x16x32_bf16 v[96:99], v[184:187], v[232:235], 0
	v_mfma_f32_16x16x32_bf16 v[88:91], v[192:195], v[232:235], 0
	v_mfma_f32_16x16x32_bf16 v[80:83], v[184:187], v[240:243], 0
	v_mfma_f32_16x16x32_bf16 v[72:75], v[192:195], v[240:243], 0
	v_mfma_f32_16x16x32_bf16 v[128:131], v[188:191], v[220:223], v[128:131]
	v_mfma_f32_16x16x32_bf16 v[120:123], v[196:199], v[220:223], v[120:123]
	v_mfma_f32_16x16x32_bf16 v[112:115], v[188:191], v[228:231], v[112:115]
	v_mfma_f32_16x16x32_bf16 v[104:107], v[196:199], v[228:231], v[104:107]
	v_mfma_f32_16x16x32_bf16 v[96:99], v[188:191], v[236:239], v[96:99]
	v_mfma_f32_16x16x32_bf16 v[88:91], v[196:199], v[236:239], v[88:91]
	v_mfma_f32_16x16x32_bf16 v[80:83], v[188:191], v[244:247], v[80:83]
	v_mfma_f32_16x16x32_bf16 v[72:75], v[196:199], v[244:247], v[72:75]
	v_mfma_f32_16x16x32_bf16 v[124:127], v[200:203], v[216:219], 0
	v_mfma_f32_16x16x32_bf16 v[116:119], v[208:211], v[216:219], 0
	v_mfma_f32_16x16x32_bf16 v[108:111], v[200:203], v[224:227], 0
	v_mfma_f32_16x16x32_bf16 v[100:103], v[208:211], v[224:227], 0
	v_mfma_f32_16x16x32_bf16 v[92:95], v[200:203], v[232:235], 0
	v_mfma_f32_16x16x32_bf16 v[84:87], v[208:211], v[232:235], 0
	v_mfma_f32_16x16x32_bf16 v[76:79], v[200:203], v[240:243], 0
	v_mfma_f32_16x16x32_bf16 v[68:71], v[208:211], v[240:243], 0
	v_mfma_f32_16x16x32_bf16 v[124:127], v[204:207], v[220:223], v[124:127]
	v_mfma_f32_16x16x32_bf16 v[116:119], v[212:215], v[220:223], v[116:119]
	v_mfma_f32_16x16x32_bf16 v[108:111], v[204:207], v[228:231], v[108:111]
	v_mfma_f32_16x16x32_bf16 v[100:103], v[212:215], v[228:231], v[100:103]
	v_mfma_f32_16x16x32_bf16 v[92:95], v[204:207], v[236:239], v[92:95]
	v_mfma_f32_16x16x32_bf16 v[84:87], v[212:215], v[236:239], v[84:87]
	v_mfma_f32_16x16x32_bf16 v[76:79], v[204:207], v[244:247], v[76:79]
	v_mfma_f32_16x16x32_bf16 v[68:71], v[212:215], v[244:247], v[68:71]
	s_setprio 0
	s_barrier
	s_add_i32 s63, s63, s27
	s_mov_b32 m0, s63
	ds_read_b128 v[216:219], v155 offset:16384
	ds_read_b128 v[220:223], v155 offset:17408
	ds_read_b128 v[224:227], v155 offset:18432
	ds_read_b128 v[228:231], v155 offset:19456
	ds_read_b128 v[232:235], v155 offset:20480
	ds_read_b128 v[236:239], v155 offset:21504
	ds_read_b128 v[240:243], v155 offset:22528
	ds_read_b128 v[244:247], v155 offset:23552
	global_load_lds_dwordx4 v2, s[20:21]
	s_add_i32 m0, s63, 0x2000
	s_add_u32 s64, s20, 0x80000
	s_addc_u32 s65, s21, 0
	s_add_i32 s63, s66, s27
	global_load_lds_dwordx4 v0, s[20:21]
	s_mov_b32 m0, s63
	v_lshl_add_u64 v[250:251], s[22:23], 0, v[132:133]
	global_load_lds_dwordx4 v2, s[64:65]
	s_add_i32 m0, s63, 0x2000
	s_nop 0
	global_load_lds_dwordx4 v0, s[64:65]
	v_lshl_add_u64 v[248:249], s[22:23], 0, v[134:135]
	s_mov_b32 m0, s29
	s_nop 0
	global_load_lds_dwordx4 v[248:249], off
	s_mov_b32 m0, s30
	s_nop 0
	global_load_lds_dwordx4 v[250:251], off
	s_waitcnt vmcnt(8)
	s_waitcnt lgkmcnt(0)
	s_barrier
; #define PG8_STAGE(bufoff, gbase, voff) do { _Pragma("unroll") for (int _i = 0; _i < 2; ++_i) \
;         __builtin_amdgcn_global_load_lds((const unsigned*)((const char*)(gbase) + (voff)[_i]), (PG8_LAS unsigned*)(lds + (bufoff) + ldsw + _i * 8192), 16, 0, 0); } while (0)
; #define PG8_LDA(dst, b, h) do { _Pragma("unroll") for (int m = 0; m < 4; ++m) _Pragma("unroll") for (int k = 0; k < 2; ++k) dst[m][k] = *(const PG8_LAS bf16x8*)(lds + PG8_SA(b, h) + aoff + m * 2048 + k * 1024); } while (0)
; #define PG8_LDB(dst, b, h) do { _Pragma("unroll") for (int n = 0; n < 2; ++n) _Pragma("unroll") for (int k = 0; k < 2; ++k) dst[n][k] = *(const PG8_LAS bf16x8*)(lds + PG8_SB(b, h) + boff + n * 2048 + k * 1024); } while (0)
; #define PG8_MMA(ai, bj, At, Bt) do { __builtin_amdgcn_s_setprio(1); _Pragma("unroll") for (int m = 0; m < 4; ++m) _Pragma("unroll") for (int n = 0; n < 2; ++n) _Pragma("unroll") for (int k = 0; k < 2; ++k) \
;         acc[ai][bj][m][n] = __builtin_amdgcn_mfma_f32_16x16x32_bf16(Bt[n][k], At[m][k], acc[ai][bj][m][n], 0, 0, 0); __builtin_amdgcn_s_setprio(0); } while (0)
; #define PG8_WAIT_V(n) asm volatile("s_waitcnt vmcnt(" #n ")" ::: "memory")
; #define PG8_WAIT_L(n) asm volatile("s_waitcnt lgkmcnt(" #n ")" ::: "memory")
; #define PG8_BAR __builtin_amdgcn_s_barrier()
; #define PG8_SCHED __builtin_amdgcn_sched_barrier(0)
; template <class Epi, class Sched, bool ALIGN_EPI = false, bool SP2 = false>
; __device__ __forceinline__ void gemm_phase(PG8_LAS unsigned char* lds, const Gemm g, const Sched& S, const Epi& E) {
;     ...
;             PG8_WAIT_V(8); PG8_WAIT_L(0); PG8_BAR; PG8_MMA(1, 0, At, B0); PG8_MMA(1, 1, At, B1); PG8_BAR; PG8_SCHED;
;             PG8_LDB(B0, 1, 0); PG8_LDB(B1, 1, 1); PG8_SCHED; PG8_LDA(At, 1, 0); PG8_STAGE(PG8_SA(0, 1), a2 + hstep, voffA);
;             PG8_WAIT_V(8); PG8_WAIT_L(0); PG8_BAR; PG8_MMA(0, 0, At, B0); PG8_MMA(0, 1, At, B1); PG8_BAR; PG8_SCHED;
	s_setprio 1
	v_mfma_f32_16x16x32_bf16 v[64:67], v[184:187], v[216:219], 0
	v_mfma_f32_16x16x32_bf16 v[56:59], v[192:195], v[216:219], 0
	v_mfma_f32_16x16x32_bf16 v[48:51], v[184:187], v[224:227], 0
	v_mfma_f32_16x16x32_bf16 v[40:43], v[192:195], v[224:227], 0
	v_mfma_f32_16x16x32_bf16 v[32:35], v[184:187], v[232:235], 0
	v_mfma_f32_16x16x32_bf16 v[24:27], v[192:195], v[232:235], 0
	v_mfma_f32_16x16x32_bf16 v[16:19], v[184:187], v[240:243], 0
	v_mfma_f32_16x16x32_bf16 v[8:11], v[192:195], v[240:243], 0
	v_mfma_f32_16x16x32_bf16 v[64:67], v[188:191], v[220:223], v[64:67]
	v_mfma_f32_16x16x32_bf16 v[56:59], v[196:199], v[220:223], v[56:59]
	v_mfma_f32_16x16x32_bf16 v[48:51], v[188:191], v[228:231], v[48:51]
	v_mfma_f32_16x16x32_bf16 v[40:43], v[196:199], v[228:231], v[40:43]
	v_mfma_f32_16x16x32_bf16 v[32:35], v[188:191], v[236:239], v[32:35]
	v_mfma_f32_16x16x32_bf16 v[24:27], v[196:199], v[236:239], v[24:27]
	v_mfma_f32_16x16x32_bf16 v[16:19], v[188:191], v[244:247], v[16:19]
	v_mfma_f32_16x16x32_bf16 v[8:11], v[196:199], v[244:247], v[8:11]
	v_mfma_f32_16x16x32_bf16 v[60:63], v[200:203], v[216:219], 0
	v_mfma_f32_16x16x32_bf16 v[52:55], v[208:211], v[216:219], 0
	v_mfma_f32_16x16x32_bf16 v[44:47], v[200:203], v[224:227], 0
	v_mfma_f32_16x16x32_bf16 v[36:39], v[208:211], v[224:227], 0
	v_mfma_f32_16x16x32_bf16 v[28:31], v[200:203], v[232:235], 0
	v_mfma_f32_16x16x32_bf16 v[20:23], v[208:211], v[232:235], 0
	v_mfma_f32_16x16x32_bf16 v[12:15], v[200:203], v[240:243], 0
	v_mfma_f32_16x16x32_bf16 v[4:7], v[208:211], v[240:243], 0
	v_mfma_f32_16x16x32_bf16 v[60:63], v[204:207], v[220:223], v[60:63]
	v_mfma_f32_16x16x32_bf16 v[52:55], v[212:215], v[220:223], v[52:55]
	v_mfma_f32_16x16x32_bf16 v[44:47], v[204:207], v[228:231], v[44:47]
	v_mfma_f32_16x16x32_bf16 v[36:39], v[212:215], v[228:231], v[36:39]
	v_mfma_f32_16x16x32_bf16 v[28:31], v[204:207], v[236:239], v[28:31]
	v_mfma_f32_16x16x32_bf16 v[20:23], v[212:215], v[236:239], v[20:23]
	v_mfma_f32_16x16x32_bf16 v[12:15], v[204:207], v[244:247], v[12:15]
	v_mfma_f32_16x16x32_bf16 v[4:7], v[212:215], v[244:247], v[4:7]
	s_setprio 0
	s_barrier
	s_add_i32 s63, 0, 0x18000
	v_add_u32_e32 v161, s63, v153
	s_add_i32 s64, 0, 0x1c000
	ds_read_b128 v[184:187], v161
	ds_read_b128 v[188:191], v161 offset:1024
	ds_read_b128 v[192:195], v161 offset:2048
	ds_read_b128 v[196:199], v161 offset:3072
	v_add_u32_e32 v161, s64, v153
	ds_read_b128 v[200:203], v161
	ds_read_b128 v[204:207], v161 offset:1024
	ds_read_b128 v[208:211], v161 offset:2048
	ds_read_b128 v[212:215], v161 offset:3072
	s_add_u32 s22, s22, 0x80000
	s_addc_u32 s23, s23, 0
	s_mov_b32 m0, s31
	ds_read_b128 v[216:219], v155 offset:32768
	ds_read_b128 v[220:223], v155 offset:33792
	ds_read_b128 v[224:227], v155 offset:34816
	ds_read_b128 v[228:231], v155 offset:35840
	ds_read_b128 v[232:235], v155 offset:36864
	ds_read_b128 v[236:239], v155 offset:37888
	ds_read_b128 v[240:243], v155 offset:38912
	ds_read_b128 v[244:247], v155 offset:39936
	global_load_lds_dwordx4 v134, s[22:23]
	s_mov_b32 m0, s34
	s_nop 0
	global_load_lds_dwordx4 v132, s[22:23]
	s_waitcnt vmcnt(8)
	s_waitcnt lgkmcnt(0)
	s_barrier
	s_setprio 1
	v_mfma_f32_16x16x32_bf16 v[128:131], v[184:187], v[216:219], v[128:131]
	v_mfma_f32_16x16x32_bf16 v[120:123], v[192:195], v[216:219], v[120:123]
	v_mfma_f32_16x16x32_bf16 v[112:115], v[184:187], v[224:227], v[112:115]
	v_mfma_f32_16x16x32_bf16 v[104:107], v[192:195], v[224:227], v[104:107]
	v_mfma_f32_16x16x32_bf16 v[96:99], v[184:187], v[232:235], v[96:99]
	v_mfma_f32_16x16x32_bf16 v[88:91], v[192:195], v[232:235], v[88:91]
	v_mfma_f32_16x16x32_bf16 v[80:83], v[184:187], v[240:243], v[80:83]
	v_mfma_f32_16x16x32_bf16 v[72:75], v[192:195], v[240:243], v[72:75]
	v_mfma_f32_16x16x32_bf16 v[128:131], v[188:191], v[220:223], v[128:131]
	v_mfma_f32_16x16x32_bf16 v[120:123], v[196:199], v[220:223], v[120:123]
	v_mfma_f32_16x16x32_bf16 v[112:115], v[188:191], v[228:231], v[112:115]
	v_mfma_f32_16x16x32_bf16 v[104:107], v[196:199], v[228:231], v[104:107]
	v_mfma_f32_16x16x32_bf16 v[96:99], v[188:191], v[236:239], v[96:99]
	v_mfma_f32_16x16x32_bf16 v[88:91], v[196:199], v[236:239], v[88:91]
	v_mfma_f32_16x16x32_bf16 v[80:83], v[188:191], v[244:247], v[80:83]
	v_mfma_f32_16x16x32_bf16 v[72:75], v[196:199], v[244:247], v[72:75]
	v_mfma_f32_16x16x32_bf16 v[124:127], v[200:203], v[216:219], v[124:127]
	v_mfma_f32_16x16x32_bf16 v[116:119], v[208:211], v[216:219], v[116:119]
	v_mfma_f32_16x16x32_bf16 v[108:111], v[200:203], v[224:227], v[108:111]
	v_mfma_f32_16x16x32_bf16 v[100:103], v[208:211], v[224:227], v[100:103]
	v_mfma_f32_16x16x32_bf16 v[92:95], v[200:203], v[232:235], v[92:95]
	v_mfma_f32_16x16x32_bf16 v[84:87], v[208:211], v[232:235], v[84:87]
	v_mfma_f32_16x16x32_bf16 v[76:79], v[200:203], v[240:243], v[76:79]
	v_mfma_f32_16x16x32_bf16 v[68:71], v[208:211], v[240:243], v[68:71]
	v_mfma_f32_16x16x32_bf16 v[124:127], v[204:207], v[220:223], v[124:127]
	v_mfma_f32_16x16x32_bf16 v[116:119], v[212:215], v[220:223], v[116:119]
	v_mfma_f32_16x16x32_bf16 v[108:111], v[204:207], v[228:231], v[108:111]
	v_mfma_f32_16x16x32_bf16 v[100:103], v[212:215], v[228:231], v[100:103]
	v_mfma_f32_16x16x32_bf16 v[92:95], v[204:207], v[236:239], v[92:95]
	v_mfma_f32_16x16x32_bf16 v[84:87], v[212:215], v[236:239], v[84:87]
	v_mfma_f32_16x16x32_bf16 v[76:79], v[204:207], v[244:247], v[76:79]
	v_mfma_f32_16x16x32_bf16 v[68:71], v[212:215], v[244:247], v[68:71]
	s_setprio 0
	s_barrier
; #define PG8_STAGE(bufoff, gbase, voff) do { _Pragma("unroll") for (int _i = 0; _i < 2; ++_i) \
;         __builtin_amdgcn_global_load_lds((const unsigned*)((const char*)(gbase) + (voff)[_i]), (PG8_LAS unsigned*)(lds + (bufoff) + ldsw + _i * 8192), 16, 0, 0); } while (0)
; #define PG8_LDA(dst, b, h) do { _Pragma("unroll") for (int m = 0; m < 4; ++m) _Pragma("unroll") for (int k = 0; k < 2; ++k) dst[m][k] = *(const PG8_LAS bf16x8*)(lds + PG8_SA(b, h) + aoff + m * 2048 + k * 1024); } while (0)
; #define PG8_LDB(dst, b, h) do { _Pragma("unroll") for (int n = 0; n < 2; ++n) _Pragma("unroll") for (int k = 0; k < 2; ++k) dst[n][k] = *(const PG8_LAS bf16x8*)(lds + PG8_SB(b, h) + boff + n * 2048 + k * 1024); } while (0)
; #define PG8_MMA(ai, bj, At, Bt) do { __builtin_amdgcn_s_setprio(1); _Pragma("unroll") for (int m = 0; m < 4; ++m) _Pragma("unroll") for (int n = 0; n < 2; ++n) _Pragma("unroll") for (int k = 0; k < 2; ++k) \
;         acc[ai][bj][m][n] = __builtin_amdgcn_mfma_f32_16x16x32_bf16(Bt[n][k], At[m][k], acc[ai][bj][m][n], 0, 0, 0); __builtin_amdgcn_s_setprio(0); } while (0)
; #define PG8_WAIT_V(n) asm volatile("s_waitcnt vmcnt(" #n ")" ::: "memory")
; template <class Epi, class Sched, bool ALIGN_EPI = false, bool SP2 = false>
; __device__ __forceinline__ void gemm_phase(PG8_LAS unsigned char* lds, const Gemm g, const Sched& S, const Epi& E) {
;     ...
;             PG8_LDB(B0, 0, 0); PG8_LDB(B1, 0, 1); PG8_SCHED; PG8_LDA(At, 0, 0); PG8_STAGE(PG8_SA(1, 1), a1 + hstep, voffA);
;             PG8_WAIT_V(8); PG8_WAIT_L(0); PG8_BAR; PG8_MMA(0, 0, At, B0); PG8_MMA(0, 1, At, B1); PG8_BAR; PG8_SCHED;
;             PG8_LDA(At, 0, 1); PG8_STAGE(PG8_SB(0, 0), b2, voffB); PG8_STAGE(PG8_SB(0, 1), b2 + hstep, voffB); PG8_STAGE(PG8_SA(0, 0), a2, voffA);
;             PG8_WAIT_V(8); PG8_WAIT_L(0); PG8_BAR; PG8_MMA(1, 0, At, B0); PG8_MMA(1, 1, At, B1); PG8_BAR; PG8_SCHED;
;             PG8_LDB(B0, 1, 0); PG8_LDB(B1, 1, 1); PG8_SCHED; PG8_LDA(At, 1, 0); PG8_STAGE(PG8_SA(0, 1), a2 + hstep, voffA);
;             PG8_WAIT_V(8); PG8_WAIT_L(0); PG8_BAR; PG8_MMA(0, 0, At, B0); PG8_MMA(0, 1, At, B1); PG8_BAR; PG8_SCHED;
;             PG8_LDA(At, 1, 1); PG8_STAGE(PG8_SB(1, 0), b3, voffB); PG8_STAGE(PG8_SB(1, 1), b3 + hstep, voffB); PG8_STAGE(PG8_SA(1, 0), a3, voffA);
;             PG8_WAIT_V(8); PG8_WAIT_L(0); PG8_BAR; PG8_MMA(1, 0, At, B0); PG8_MMA(1, 1, At, B1); PG8_BAR; PG8_SCHED;
	s_add_i32 s22, s63, s27
	s_mov_b32 m0, s22
	ds_read_b128 v[216:219], v155 offset:49152
	ds_read_b128 v[220:223], v155 offset:50176
	ds_read_b128 v[224:227], v155 offset:51200
	ds_read_b128 v[228:231], v155 offset:52224
	ds_read_b128 v[232:235], v155 offset:53248
	ds_read_b128 v[236:239], v155 offset:54272
	ds_read_b128 v[240:243], v155 offset:55296
	ds_read_b128 v[244:247], v155 offset:56320
	s_add_u32 vcc_lo, s20, 0x80
	s_addc_u32 vcc_hi, s21, 0
	global_load_lds_dwordx4 v2, vcc
	s_add_i32 m0, s22, 0x2000
	s_add_u32 s20, s20, 0x80080
	s_addc_u32 s21, s21, 0
	s_add_i32 s22, s64, s27
	s_add_u32 vcc_lo, s20, 0xfff80000
	s_addc_u32 vcc_hi, s21, -1
	global_load_lds_dwordx4 v0, vcc
	s_mov_b32 m0, s22
	s_nop 0
	global_load_lds_dwordx4 v2, s[20:21]
	s_add_i32 m0, s22, 0x2000
	s_nop 0
	global_load_lds_dwordx4 v0, s[20:21]
	v_lshl_add_u64 v[150:151], v[248:249], 0, s[36:37]
	s_mov_b32 m0, s35
	s_nop 0
	global_load_lds_dwordx4 v[150:151], off
	v_lshl_add_u64 v[150:151], v[250:251], 0, s[36:37]
	s_mov_b32 m0, s42
	s_nop 0
	global_load_lds_dwordx4 v[150:151], off
	s_waitcnt vmcnt(8)
	s_waitcnt lgkmcnt(0)
	s_barrier
	s_setprio 1
	v_mfma_f32_16x16x32_bf16 v[64:67], v[184:187], v[216:219], v[64:67]
	v_mfma_f32_16x16x32_bf16 v[56:59], v[192:195], v[216:219], v[56:59]
	v_mfma_f32_16x16x32_bf16 v[48:51], v[184:187], v[224:227], v[48:51]
	v_mfma_f32_16x16x32_bf16 v[40:43], v[192:195], v[224:227], v[40:43]
	v_mfma_f32_16x16x32_bf16 v[32:35], v[184:187], v[232:235], v[32:35]
	v_mfma_f32_16x16x32_bf16 v[24:27], v[192:195], v[232:235], v[24:27]
	v_mfma_f32_16x16x32_bf16 v[16:19], v[184:187], v[240:243], v[16:19]
	v_mfma_f32_16x16x32_bf16 v[8:11], v[192:195], v[240:243], v[8:11]
	v_mfma_f32_16x16x32_bf16 v[64:67], v[188:191], v[220:223], v[64:67]
	v_mfma_f32_16x16x32_bf16 v[56:59], v[196:199], v[220:223], v[56:59]
	v_mfma_f32_16x16x32_bf16 v[48:51], v[188:191], v[228:231], v[48:51]
	v_mfma_f32_16x16x32_bf16 v[40:43], v[196:199], v[228:231], v[40:43]
	v_mfma_f32_16x16x32_bf16 v[32:35], v[188:191], v[236:239], v[32:35]
	v_mfma_f32_16x16x32_bf16 v[24:27], v[196:199], v[236:239], v[24:27]
	v_mfma_f32_16x16x32_bf16 v[16:19], v[188:191], v[244:247], v[16:19]
	v_mfma_f32_16x16x32_bf16 v[8:11], v[196:199], v[244:247], v[8:11]
	v_mfma_f32_16x16x32_bf16 v[60:63], v[200:203], v[216:219], v[60:63]
	v_mfma_f32_16x16x32_bf16 v[52:55], v[208:211], v[216:219], v[52:55]
	v_mfma_f32_16x16x32_bf16 v[44:47], v[200:203], v[224:227], v[44:47]
	v_mfma_f32_16x16x32_bf16 v[36:39], v[208:211], v[224:227], v[36:39]
	v_mfma_f32_16x16x32_bf16 v[28:31], v[200:203], v[232:235], v[28:31]
	v_mfma_f32_16x16x32_bf16 v[20:23], v[208:211], v[232:235], v[20:23]
	v_mfma_f32_16x16x32_bf16 v[12:15], v[200:203], v[240:243], v[12:15]
	v_mfma_f32_16x16x32_bf16 v[4:7], v[208:211], v[240:243], v[4:7]
	v_mfma_f32_16x16x32_bf16 v[60:63], v[204:207], v[220:223], v[60:63]
	v_mfma_f32_16x16x32_bf16 v[52:55], v[212:215], v[220:223], v[52:55]
	v_mfma_f32_16x16x32_bf16 v[44:47], v[204:207], v[228:231], v[44:47]
	v_mfma_f32_16x16x32_bf16 v[36:39], v[212:215], v[228:231], v[36:39]
	v_mfma_f32_16x16x32_bf16 v[28:31], v[204:207], v[236:239], v[28:31]
	v_mfma_f32_16x16x32_bf16 v[20:23], v[212:215], v[236:239], v[20:23]
	v_mfma_f32_16x16x32_bf16 v[12:15], v[204:207], v[244:247], v[12:15]
	v_mfma_f32_16x16x32_bf16 v[4:7], v[212:215], v[244:247], v[4:7]
	s_setprio 0
	s_barrier
	s_add_i32 s57, s57, 2
	s_add_u32 s18, s18, 0x100
	s_addc_u32 s19, s19, 0
	s_add_u32 s51, s51, 0x100
	s_addc_u32 s56, s56, 0
	s_cmp_gt_u32 s57, 29
.LBB0_567:
	s_add_u32 s20, s18, 0xfff80080
	s_addc_u32 s21, s19, -1
	s_add_i32 s63, 0, 0x10000
	s_cmp_eq_u32 s57, 28
	s_cselect_b32 s23, s11, s21
	s_cselect_b32 s22, s45, s20
	v_add_u32_e32 v150, s63, v153
	s_cselect_b32 s21, s9, s56
	s_cselect_b32 s20, s50, s51
	s_add_i32 s66, 0, 0x14000
	ds_read_b128 v[184:187], v150
	ds_read_b128 v[188:191], v150 offset:1024
	ds_read_b128 v[192:195], v150 offset:2048
	ds_read_b128 v[196:199], v150 offset:3072
	v_add_u32_e32 v150, s66, v153
	ds_read_b128 v[200:203], v150
	ds_read_b128 v[204:207], v150 offset:1024
	ds_read_b128 v[208:211], v150 offset:2048
	ds_read_b128 v[212:215], v150 offset:3072
	s_add_i32 m0, s29, 0xc000
	ds_read_b128 v[216:219], v155
	ds_read_b128 v[220:223], v155 offset:1024
	ds_read_b128 v[224:227], v155 offset:2048
	ds_read_b128 v[228:231], v155 offset:3072
	ds_read_b128 v[232:235], v155 offset:4096
	ds_read_b128 v[236:239], v155 offset:5120
	ds_read_b128 v[240:243], v155 offset:6144
	ds_read_b128 v[244:247], v155 offset:7168
	global_load_lds_dwordx4 v136, s[18:19]
	s_add_i32 m0, s29, 0xe000
	s_nop 0
	global_load_lds_dwordx4 v138, s[18:19]
	s_waitcnt vmcnt(8)
	s_waitcnt lgkmcnt(0)
	s_barrier
; #define PG8_STAGE(bufoff, gbase, voff) do { _Pragma("unroll") for (int _i = 0; _i < 2; ++_i) \
;         __builtin_amdgcn_global_load_lds((const unsigned*)((const char*)(gbase) + (voff)[_i]), (PG8_LAS unsigned*)(lds + (bufoff) + ldsw + _i * 8192), 16, 0, 0); } while (0)
; #define PG8_LDA(dst, b, h) do { _Pragma("unroll") for (int m = 0; m < 4; ++m) _Pragma("unroll") for (int k = 0; k < 2; ++k) dst[m][k] = *(const PG8_LAS bf16x8*)(lds + PG8_SA(b, h) + aoff + m * 2048 + k * 1024); } while (0)
; #define PG8_LDB(dst, b, h) do { _Pragma("unroll") for (int n = 0; n < 2; ++n) _Pragma("unroll") for (int k = 0; k < 2; ++k) dst[n][k] = *(const PG8_LAS bf16x8*)(lds + PG8_SB(b, h) + boff + n * 2048 + k * 1024); } while (0)
; #define PG8_MMA(ai, bj, At, Bt) do { __builtin_amdgcn_s_setprio(1); _Pragma("unroll") for (int m = 0; m < 4; ++m) _Pragma("unroll") for (int n = 0; n < 2; ++n) _Pragma("unroll") for (int k = 0; k < 2; ++k) \
;         acc[ai][bj][m][n] = __builtin_amdgcn_mfma_f32_16x16x32_bf16(Bt[n][k], At[m][k], acc[ai][bj][m][n], 0, 0, 0); __builtin_amdgcn_s_setprio(0); } while (0)
; #define PG8_WAIT_V(n) asm volatile("s_waitcnt vmcnt(" #n ")" ::: "memory")
; #define PG8_WAIT_L(n) asm volatile("s_waitcnt lgkmcnt(" #n ")" ::: "memory")
; #define PG8_BAR __builtin_amdgcn_s_barrier()
; #define PG8_SCHED __builtin_amdgcn_sched_barrier(0)
; template <class Epi, class Sched, bool ALIGN_EPI = false, bool SP2 = false>
; __device__ __forceinline__ void gemm_phase(PG8_LAS unsigned char* lds, const Gemm g, const Sched& S, const Epi& E) {
;     ...
;             PG8_LDB(B0, 0, 0); PG8_LDB(B1, 0, 1); PG8_SCHED; PG8_LDA(At, 0, 0); PG8_STAGE(PG8_SA(1, 1), a1 + hstep, voffA);
;             PG8_WAIT_V(8); PG8_WAIT_L(0); PG8_BAR; PG8_MMA(0, 0, At, B0); PG8_MMA(0, 1, At, B1); PG8_BAR; PG8_SCHED;
;             PG8_LDA(At, 0, 1); PG8_STAGE(PG8_SB(0, 0), b2, voffB); PG8_STAGE(PG8_SB(0, 1), b2 + hstep, voffB); PG8_STAGE(PG8_SA(0, 0), a2, voffA);
;             PG8_WAIT_V(8); PG8_WAIT_L(0); PG8_BAR; PG8_MMA(1, 0, At, B0); PG8_MMA(1, 1, At, B1); PG8_BAR; PG8_SCHED;
	s_setprio 1
	v_mfma_f32_16x16x32_bf16 v[128:131], v[184:187], v[216:219], v[128:131]
	v_mfma_f32_16x16x32_bf16 v[120:123], v[192:195], v[216:219], v[120:123]
	v_mfma_f32_16x16x32_bf16 v[112:115], v[184:187], v[224:227], v[112:115]
	v_mfma_f32_16x16x32_bf16 v[104:107], v[192:195], v[224:227], v[104:107]
	v_mfma_f32_16x16x32_bf16 v[96:99], v[184:187], v[232:235], v[96:99]
	v_mfma_f32_16x16x32_bf16 v[88:91], v[192:195], v[232:235], v[88:91]
	v_mfma_f32_16x16x32_bf16 v[80:83], v[184:187], v[240:243], v[80:83]
	v_mfma_f32_16x16x32_bf16 v[72:75], v[192:195], v[240:243], v[72:75]
	v_mfma_f32_16x16x32_bf16 v[128:131], v[188:191], v[220:223], v[128:131]
	v_mfma_f32_16x16x32_bf16 v[120:123], v[196:199], v[220:223], v[120:123]
	v_mfma_f32_16x16x32_bf16 v[112:115], v[188:191], v[228:231], v[112:115]
	v_mfma_f32_16x16x32_bf16 v[104:107], v[196:199], v[228:231], v[104:107]
	v_mfma_f32_16x16x32_bf16 v[96:99], v[188:191], v[236:239], v[96:99]
	v_mfma_f32_16x16x32_bf16 v[88:91], v[196:199], v[236:239], v[88:91]
	v_mfma_f32_16x16x32_bf16 v[80:83], v[188:191], v[244:247], v[80:83]
	v_mfma_f32_16x16x32_bf16 v[72:75], v[196:199], v[244:247], v[72:75]
	v_mfma_f32_16x16x32_bf16 v[124:127], v[200:203], v[216:219], v[124:127]
	v_mfma_f32_16x16x32_bf16 v[116:119], v[208:211], v[216:219], v[116:119]
	v_mfma_f32_16x16x32_bf16 v[108:111], v[200:203], v[224:227], v[108:111]
	v_mfma_f32_16x16x32_bf16 v[100:103], v[208:211], v[224:227], v[100:103]
	v_mfma_f32_16x16x32_bf16 v[92:95], v[200:203], v[232:235], v[92:95]
	v_mfma_f32_16x16x32_bf16 v[84:87], v[208:211], v[232:235], v[84:87]
	v_mfma_f32_16x16x32_bf16 v[76:79], v[200:203], v[240:243], v[76:79]
	v_mfma_f32_16x16x32_bf16 v[68:71], v[208:211], v[240:243], v[68:71]
	v_mfma_f32_16x16x32_bf16 v[124:127], v[204:207], v[220:223], v[124:127]
	v_mfma_f32_16x16x32_bf16 v[116:119], v[212:215], v[220:223], v[116:119]
	v_mfma_f32_16x16x32_bf16 v[108:111], v[204:207], v[228:231], v[108:111]
	v_mfma_f32_16x16x32_bf16 v[100:103], v[212:215], v[228:231], v[100:103]
	v_mfma_f32_16x16x32_bf16 v[92:95], v[204:207], v[236:239], v[92:95]
	v_mfma_f32_16x16x32_bf16 v[84:87], v[212:215], v[236:239], v[84:87]
	v_mfma_f32_16x16x32_bf16 v[76:79], v[204:207], v[244:247], v[76:79]
	v_mfma_f32_16x16x32_bf16 v[68:71], v[212:215], v[244:247], v[68:71]
	s_setprio 0
	s_barrier
	s_add_i32 s63, s63, s27
	s_mov_b32 m0, s63
	ds_read_b128 v[216:219], v155 offset:16384
	ds_read_b128 v[220:223], v155 offset:17408
	ds_read_b128 v[224:227], v155 offset:18432
	ds_read_b128 v[228:231], v155 offset:19456
	ds_read_b128 v[232:235], v155 offset:20480
	ds_read_b128 v[236:239], v155 offset:21504
	ds_read_b128 v[240:243], v155 offset:22528
	ds_read_b128 v[244:247], v155 offset:23552
	global_load_lds_dwordx4 v2, s[20:21]
	s_add_i32 m0, s63, 0x2000
	s_add_u32 s64, s20, 0x80000
	s_addc_u32 s65, s21, 0
	s_add_i32 s63, s66, s27
	global_load_lds_dwordx4 v0, s[20:21]
	s_mov_b32 m0, s63
	v_lshl_add_u64 v[250:251], s[22:23], 0, v[132:133]
	global_load_lds_dwordx4 v2, s[64:65]
	s_add_i32 m0, s63, 0x2000
	s_nop 0
	global_load_lds_dwordx4 v0, s[64:65]
	v_lshl_add_u64 v[248:249], s[22:23], 0, v[134:135]
	s_mov_b32 m0, s29
	s_nop 0
	global_load_lds_dwordx4 v[248:249], off
	s_mov_b32 m0, s30
	s_nop 0
	global_load_lds_dwordx4 v[250:251], off
	s_waitcnt vmcnt(8)
	s_waitcnt lgkmcnt(0)
	s_barrier
	s_setprio 1
	v_mfma_f32_16x16x32_bf16 v[64:67], v[184:187], v[216:219], v[64:67]
	v_mfma_f32_16x16x32_bf16 v[56:59], v[192:195], v[216:219], v[56:59]
	v_mfma_f32_16x16x32_bf16 v[48:51], v[184:187], v[224:227], v[48:51]
	v_mfma_f32_16x16x32_bf16 v[40:43], v[192:195], v[224:227], v[40:43]
	v_mfma_f32_16x16x32_bf16 v[32:35], v[184:187], v[232:235], v[32:35]
	v_mfma_f32_16x16x32_bf16 v[24:27], v[192:195], v[232:235], v[24:27]
	v_mfma_f32_16x16x32_bf16 v[16:19], v[184:187], v[240:243], v[16:19]
	v_mfma_f32_16x16x32_bf16 v[8:11], v[192:195], v[240:243], v[8:11]
	v_mfma_f32_16x16x32_bf16 v[64:67], v[188:191], v[220:223], v[64:67]
	v_mfma_f32_16x16x32_bf16 v[56:59], v[196:199], v[220:223], v[56:59]
	v_mfma_f32_16x16x32_bf16 v[48:51], v[188:191], v[228:231], v[48:51]
	v_mfma_f32_16x16x32_bf16 v[40:43], v[196:199], v[228:231], v[40:43]
	v_mfma_f32_16x16x32_bf16 v[32:35], v[188:191], v[236:239], v[32:35]
	v_mfma_f32_16x16x32_bf16 v[24:27], v[196:199], v[236:239], v[24:27]
	v_mfma_f32_16x16x32_bf16 v[16:19], v[188:191], v[244:247], v[16:19]
	v_mfma_f32_16x16x32_bf16 v[8:11], v[196:199], v[244:247], v[8:11]
	v_mfma_f32_16x16x32_bf16 v[60:63], v[200:203], v[216:219], v[60:63]
	v_mfma_f32_16x16x32_bf16 v[52:55], v[208:211], v[216:219], v[52:55]
	v_mfma_f32_16x16x32_bf16 v[44:47], v[200:203], v[224:227], v[44:47]
	v_mfma_f32_16x16x32_bf16 v[36:39], v[208:211], v[224:227], v[36:39]
	v_mfma_f32_16x16x32_bf16 v[28:31], v[200:203], v[232:235], v[28:31]
	v_mfma_f32_16x16x32_bf16 v[20:23], v[208:211], v[232:235], v[20:23]
	v_mfma_f32_16x16x32_bf16 v[12:15], v[200:203], v[240:243], v[12:15]
	v_mfma_f32_16x16x32_bf16 v[4:7], v[208:211], v[240:243], v[4:7]
	v_mfma_f32_16x16x32_bf16 v[60:63], v[204:207], v[220:223], v[60:63]
	v_mfma_f32_16x16x32_bf16 v[52:55], v[212:215], v[220:223], v[52:55]
	v_mfma_f32_16x16x32_bf16 v[44:47], v[204:207], v[228:231], v[44:47]
	v_mfma_f32_16x16x32_bf16 v[36:39], v[212:215], v[228:231], v[36:39]
	v_mfma_f32_16x16x32_bf16 v[28:31], v[204:207], v[236:239], v[28:31]
	v_mfma_f32_16x16x32_bf16 v[20:23], v[212:215], v[236:239], v[20:23]
	v_mfma_f32_16x16x32_bf16 v[12:15], v[204:207], v[244:247], v[12:15]
	v_mfma_f32_16x16x32_bf16 v[4:7], v[212:215], v[244:247], v[4:7]
	s_setprio 0
	s_barrier
; #define PG8_STAGE(bufoff, gbase, voff) do { _Pragma("unroll") for (int _i = 0; _i < 2; ++_i) \
;         __builtin_amdgcn_global_load_lds((const unsigned*)((const char*)(gbase) + (voff)[_i]), (PG8_LAS unsigned*)(lds + (bufoff) + ldsw + _i * 8192), 16, 0, 0); } while (0)
; #define PG8_LDA(dst, b, h) do { _Pragma("unroll") for (int m = 0; m < 4; ++m) _Pragma("unroll") for (int k = 0; k < 2; ++k) dst[m][k] = *(const PG8_LAS bf16x8*)(lds + PG8_SA(b, h) + aoff + m * 2048 + k * 1024); } while (0)
; #define PG8_LDB(dst, b, h) do { _Pragma("unroll") for (int n = 0; n < 2; ++n) _Pragma("unroll") for (int k = 0; k < 2; ++k) dst[n][k] = *(const PG8_LAS bf16x8*)(lds + PG8_SB(b, h) + boff + n * 2048 + k * 1024); } while (0)
; #define PG8_MMA(ai, bj, At, Bt) do { __builtin_amdgcn_s_setprio(1); _Pragma("unroll") for (int m = 0; m < 4; ++m) _Pragma("unroll") for (int n = 0; n < 2; ++n) _Pragma("unroll") for (int k = 0; k < 2; ++k) \
;         acc[ai][bj][m][n] = __builtin_amdgcn_mfma_f32_16x16x32_bf16(Bt[n][k], At[m][k], acc[ai][bj][m][n], 0, 0, 0); __builtin_amdgcn_s_setprio(0); } while (0)
; #define PG8_WAIT_V(n) asm volatile("s_waitcnt vmcnt(" #n ")" ::: "memory")
; #define PG8_WAIT_L(n) asm volatile("s_waitcnt lgkmcnt(" #n ")" ::: "memory")
; #define PG8_BAR __builtin_amdgcn_s_barrier()
; #define PG8_SCHED __builtin_amdgcn_sched_barrier(0)
; template <class Epi, class Sched, bool ALIGN_EPI = false, bool SP2 = false>
; __device__ __forceinline__ void gemm_phase(PG8_LAS unsigned char* lds, const Gemm g, const Sched& S, const Epi& E) {
;     ...
;             PG8_LDB(B0, 1, 0); PG8_LDB(B1, 1, 1); PG8_SCHED; PG8_LDA(At, 1, 0); PG8_STAGE(PG8_SA(0, 1), a2 + hstep, voffA);
;             PG8_WAIT_V(8); PG8_WAIT_L(0); PG8_BAR; PG8_MMA(0, 0, At, B0); PG8_MMA(0, 1, At, B1); PG8_BAR; PG8_SCHED;
;             PG8_LDA(At, 1, 1); PG8_STAGE(PG8_SB(1, 0), b3, voffB); PG8_STAGE(PG8_SB(1, 1), b3 + hstep, voffB); PG8_STAGE(PG8_SA(1, 0), a3, voffA);
;             PG8_WAIT_V(8); PG8_WAIT_L(0); PG8_BAR; PG8_MMA(1, 0, At, B0); PG8_MMA(1, 1, At, B1); PG8_BAR; PG8_SCHED;
;     ...
;         if constexpr (ALIGN_EPI) { if (wr == 0) PG8_BAR; }
	s_add_i32 s63, 0, 0x18000
	v_add_u32_e32 v161, s63, v153
	s_add_i32 s64, 0, 0x1c000
	ds_read_b128 v[184:187], v161
	ds_read_b128 v[188:191], v161 offset:1024
	ds_read_b128 v[192:195], v161 offset:2048
	ds_read_b128 v[196:199], v161 offset:3072
	v_add_u32_e32 v161, s64, v153
	ds_read_b128 v[200:203], v161
	ds_read_b128 v[204:207], v161 offset:1024
	ds_read_b128 v[208:211], v161 offset:2048
	ds_read_b128 v[212:215], v161 offset:3072
	s_add_u32 s22, s22, 0x80000
	s_addc_u32 s23, s23, 0
	s_mov_b32 m0, s31
	ds_read_b128 v[216:219], v155 offset:32768
	ds_read_b128 v[220:223], v155 offset:33792
	ds_read_b128 v[224:227], v155 offset:34816
	ds_read_b128 v[228:231], v155 offset:35840
	ds_read_b128 v[232:235], v155 offset:36864
	ds_read_b128 v[236:239], v155 offset:37888
	ds_read_b128 v[240:243], v155 offset:38912
	ds_read_b128 v[244:247], v155 offset:39936
	global_load_lds_dwordx4 v134, s[22:23]
	s_mov_b32 m0, s34
	s_nop 0
	global_load_lds_dwordx4 v132, s[22:23]
	s_waitcnt vmcnt(8)
	s_waitcnt lgkmcnt(0)
	s_barrier
	s_setprio 1
	v_mfma_f32_16x16x32_bf16 v[128:131], v[184:187], v[216:219], v[128:131]
	v_mfma_f32_16x16x32_bf16 v[120:123], v[192:195], v[216:219], v[120:123]
	v_mfma_f32_16x16x32_bf16 v[112:115], v[184:187], v[224:227], v[112:115]
	v_mfma_f32_16x16x32_bf16 v[104:107], v[192:195], v[224:227], v[104:107]
	v_mfma_f32_16x16x32_bf16 v[96:99], v[184:187], v[232:235], v[96:99]
	v_mfma_f32_16x16x32_bf16 v[88:91], v[192:195], v[232:235], v[88:91]
	v_mfma_f32_16x16x32_bf16 v[80:83], v[184:187], v[240:243], v[80:83]
	v_mfma_f32_16x16x32_bf16 v[72:75], v[192:195], v[240:243], v[72:75]
	v_mfma_f32_16x16x32_bf16 v[128:131], v[188:191], v[220:223], v[128:131]
	v_mfma_f32_16x16x32_bf16 v[120:123], v[196:199], v[220:223], v[120:123]
	v_mfma_f32_16x16x32_bf16 v[112:115], v[188:191], v[228:231], v[112:115]
	v_mfma_f32_16x16x32_bf16 v[104:107], v[196:199], v[228:231], v[104:107]
	v_mfma_f32_16x16x32_bf16 v[96:99], v[188:191], v[236:239], v[96:99]
	v_mfma_f32_16x16x32_bf16 v[88:91], v[196:199], v[236:239], v[88:91]
	v_mfma_f32_16x16x32_bf16 v[80:83], v[188:191], v[244:247], v[80:83]
	v_mfma_f32_16x16x32_bf16 v[72:75], v[196:199], v[244:247], v[72:75]
	v_mfma_f32_16x16x32_bf16 v[124:127], v[200:203], v[216:219], v[124:127]
	v_mfma_f32_16x16x32_bf16 v[116:119], v[208:211], v[216:219], v[116:119]
	v_mfma_f32_16x16x32_bf16 v[108:111], v[200:203], v[224:227], v[108:111]
	v_mfma_f32_16x16x32_bf16 v[100:103], v[208:211], v[224:227], v[100:103]
	v_mfma_f32_16x16x32_bf16 v[92:95], v[200:203], v[232:235], v[92:95]
	v_mfma_f32_16x16x32_bf16 v[84:87], v[208:211], v[232:235], v[84:87]
	v_mfma_f32_16x16x32_bf16 v[76:79], v[200:203], v[240:243], v[76:79]
	v_mfma_f32_16x16x32_bf16 v[68:71], v[208:211], v[240:243], v[68:71]
	v_mfma_f32_16x16x32_bf16 v[124:127], v[204:207], v[220:223], v[124:127]
	v_mfma_f32_16x16x32_bf16 v[116:119], v[212:215], v[220:223], v[116:119]
	v_mfma_f32_16x16x32_bf16 v[108:111], v[204:207], v[228:231], v[108:111]
	v_mfma_f32_16x16x32_bf16 v[100:103], v[212:215], v[228:231], v[100:103]
	v_mfma_f32_16x16x32_bf16 v[92:95], v[204:207], v[236:239], v[92:95]
	v_mfma_f32_16x16x32_bf16 v[84:87], v[212:215], v[236:239], v[84:87]
	v_mfma_f32_16x16x32_bf16 v[76:79], v[204:207], v[244:247], v[76:79]
	v_mfma_f32_16x16x32_bf16 v[68:71], v[212:215], v[244:247], v[68:71]
	s_setprio 0
	s_barrier
	s_add_i32 s22, s63, s27
	s_mov_b32 m0, s22
	ds_read_b128 v[216:219], v155 offset:49152
	ds_read_b128 v[220:223], v155 offset:50176
	ds_read_b128 v[224:227], v155 offset:51200
	ds_read_b128 v[228:231], v155 offset:52224
	ds_read_b128 v[232:235], v155 offset:53248
	ds_read_b128 v[236:239], v155 offset:54272
	ds_read_b128 v[240:243], v155 offset:55296
	ds_read_b128 v[244:247], v155 offset:56320
	s_add_u32 vcc_lo, s20, 0x80
	s_addc_u32 vcc_hi, s21, 0
	global_load_lds_dwordx4 v2, vcc
	s_add_i32 m0, s22, 0x2000
	s_add_u32 s20, s20, 0x80080
	s_addc_u32 s21, s21, 0
	s_add_i32 s22, s64, s27
	s_add_u32 vcc_lo, s20, 0xfff80000
	s_addc_u32 vcc_hi, s21, -1
	global_load_lds_dwordx4 v0, vcc
	s_mov_b32 m0, s22
	s_nop 0
	global_load_lds_dwordx4 v2, s[20:21]
	s_add_i32 m0, s22, 0x2000
	s_nop 0
	global_load_lds_dwordx4 v0, s[20:21]
	v_lshl_add_u64 v[150:151], v[248:249], 0, s[36:37]
	s_mov_b32 m0, s35
	s_nop 0
	global_load_lds_dwordx4 v[150:151], off
	v_lshl_add_u64 v[150:151], v[250:251], 0, s[36:37]
	s_mov_b32 m0, s42
	s_nop 0
	global_load_lds_dwordx4 v[150:151], off
	s_waitcnt vmcnt(8)
	s_waitcnt lgkmcnt(0)
	s_barrier
	s_setprio 1
	v_mfma_f32_16x16x32_bf16 v[64:67], v[184:187], v[216:219], v[64:67]
	v_mfma_f32_16x16x32_bf16 v[56:59], v[192:195], v[216:219], v[56:59]
	v_mfma_f32_16x16x32_bf16 v[48:51], v[184:187], v[224:227], v[48:51]
	v_mfma_f32_16x16x32_bf16 v[40:43], v[192:195], v[224:227], v[40:43]
	v_mfma_f32_16x16x32_bf16 v[32:35], v[184:187], v[232:235], v[32:35]
	v_mfma_f32_16x16x32_bf16 v[24:27], v[192:195], v[232:235], v[24:27]
	v_mfma_f32_16x16x32_bf16 v[16:19], v[184:187], v[240:243], v[16:19]
	v_mfma_f32_16x16x32_bf16 v[8:11], v[192:195], v[240:243], v[8:11]
	v_mfma_f32_16x16x32_bf16 v[64:67], v[188:191], v[220:223], v[64:67]
	v_mfma_f32_16x16x32_bf16 v[56:59], v[196:199], v[220:223], v[56:59]
	v_mfma_f32_16x16x32_bf16 v[48:51], v[188:191], v[228:231], v[48:51]
	v_mfma_f32_16x16x32_bf16 v[40:43], v[196:199], v[228:231], v[40:43]
	v_mfma_f32_16x16x32_bf16 v[32:35], v[188:191], v[236:239], v[32:35]
	v_mfma_f32_16x16x32_bf16 v[24:27], v[196:199], v[236:239], v[24:27]
	v_mfma_f32_16x16x32_bf16 v[16:19], v[188:191], v[244:247], v[16:19]
	v_mfma_f32_16x16x32_bf16 v[8:11], v[196:199], v[244:247], v[8:11]
	v_mfma_f32_16x16x32_bf16 v[60:63], v[200:203], v[216:219], v[60:63]
	v_mfma_f32_16x16x32_bf16 v[52:55], v[208:211], v[216:219], v[52:55]
	v_mfma_f32_16x16x32_bf16 v[44:47], v[200:203], v[224:227], v[44:47]
	v_mfma_f32_16x16x32_bf16 v[36:39], v[208:211], v[224:227], v[36:39]
	v_mfma_f32_16x16x32_bf16 v[28:31], v[200:203], v[232:235], v[28:31]
	v_mfma_f32_16x16x32_bf16 v[20:23], v[208:211], v[232:235], v[20:23]
	v_mfma_f32_16x16x32_bf16 v[12:15], v[200:203], v[240:243], v[12:15]
	v_mfma_f32_16x16x32_bf16 v[4:7], v[208:211], v[240:243], v[4:7]
	v_mfma_f32_16x16x32_bf16 v[60:63], v[204:207], v[220:223], v[60:63]
	v_mfma_f32_16x16x32_bf16 v[52:55], v[212:215], v[220:223], v[52:55]
	v_mfma_f32_16x16x32_bf16 v[44:47], v[204:207], v[228:231], v[44:47]
	v_mfma_f32_16x16x32_bf16 v[36:39], v[212:215], v[228:231], v[36:39]
	v_mfma_f32_16x16x32_bf16 v[28:31], v[204:207], v[236:239], v[28:31]
	v_mfma_f32_16x16x32_bf16 v[20:23], v[212:215], v[236:239], v[20:23]
	v_mfma_f32_16x16x32_bf16 v[12:15], v[204:207], v[244:247], v[12:15]
	v_mfma_f32_16x16x32_bf16 v[4:7], v[212:215], v[244:247], v[4:7]
	s_setprio 0
	s_barrier
	s_add_i32 s57, s57, 2
	s_add_u32 s18, s18, 0x100
	s_addc_u32 s19, s19, 0
	s_add_u32 s51, s51, 0x100
	s_addc_u32 s56, s56, 0
	s_cmp_gt_u32 s57, 29
	s_cbranch_scc0 .LBB0_567
	s_and_b64 vcc, exec, s[6:7]
	s_cbranch_vccz .LBB0_570
	s_barrier
